# K-loops: LDS-DMA loads use SGPR base + 32-bit lane offset (saddr form) instead of a v_lshl_add_u64 per load: 16 fewer VALU per K iteration in the load segments (on top of v25)
# speedup vs baseline: 1.0025x; 1.0025x over previous
.LBB0_131:
	s_add_u32 s60, s57, 0xffffff80
	s_addc_u32 s61, s58, -1
	s_cmp_eq_u32 s59, 60
	s_cselect_b32 s36, s17, s57
	s_cselect_b32 s37, s7, s58
	s_cselect_b32 s39, s21, s56
	s_cselect_b32 s38, s33, s55
	s_add_u32 s30, s36, 0x80
	s_addc_u32 s31, s37, 0
	s_add_u32 s34, s38, 0x80
	s_addc_u32 s35, s39, 0
	s_add_i32 s62, 0, 0x10000
	s_add_i32 s63, 0, 0x14000
	v_add_u32_e32 v152, s62, v1
	v_add_u32_e32 v168, s63, v1
	ds_read_b128 v[140:143], v152
	ds_read_b128 v[144:147], v152 offset:1024
	ds_read_b128 v[148:151], v152 offset:2048
	ds_read_b128 v[152:155], v152 offset:3072
	ds_read_b128 v[156:159], v168
	ds_read_b128 v[160:163], v168 offset:1024
	ds_read_b128 v[164:167], v168 offset:2048
	ds_read_b128 v[168:171], v168 offset:3072
	s_add_u32 s60, s60, 0x100000
	s_addc_u32 s61, s61, 0
	s_add_i32 m0, s29, 0xc000
	ds_read_b128 v[172:175], v5
	ds_read_b128 v[176:179], v5 offset:1024
	ds_read_b128 v[180:183], v5 offset:2048
	ds_read_b128 v[184:187], v5 offset:3072
	ds_read_b128 v[188:191], v5 offset:4096
	ds_read_b128 v[192:195], v5 offset:5120
	ds_read_b128 v[196:199], v5 offset:6144
	ds_read_b128 v[200:203], v5 offset:7168
	global_load_lds_dwordx4 v2, s[60:61]
	s_add_i32 m0, s29, 0xe000
	s_nop 0
	global_load_lds_dwordx4 v136, s[60:61]
	s_waitcnt vmcnt(8)
	s_waitcnt lgkmcnt(0)
	s_barrier
	s_setprio 1
	v_mfma_f32_16x16x32_bf16 v[130:133], v[140:143], v[172:175], v[130:133]
	v_mfma_f32_16x16x32_bf16 v[126:129], v[148:151], v[172:175], v[126:129]
	v_mfma_f32_16x16x32_bf16 v[114:117], v[140:143], v[180:183], v[114:117]
	v_mfma_f32_16x16x32_bf16 v[110:113], v[148:151], v[180:183], v[110:113]
	v_mfma_f32_16x16x32_bf16 v[98:101], v[140:143], v[188:191], v[98:101]
	v_mfma_f32_16x16x32_bf16 v[94:97], v[148:151], v[188:191], v[94:97]
	v_mfma_f32_16x16x32_bf16 v[82:85], v[140:143], v[196:199], v[82:85]
	v_mfma_f32_16x16x32_bf16 v[78:81], v[148:151], v[196:199], v[78:81]
	v_mfma_f32_16x16x32_bf16 v[130:133], v[144:147], v[176:179], v[130:133]
	v_mfma_f32_16x16x32_bf16 v[126:129], v[152:155], v[176:179], v[126:129]
	v_mfma_f32_16x16x32_bf16 v[114:117], v[144:147], v[184:187], v[114:117]
	v_mfma_f32_16x16x32_bf16 v[110:113], v[152:155], v[184:187], v[110:113]
	v_mfma_f32_16x16x32_bf16 v[98:101], v[144:147], v[192:195], v[98:101]
	v_mfma_f32_16x16x32_bf16 v[94:97], v[152:155], v[192:195], v[94:97]
	v_mfma_f32_16x16x32_bf16 v[82:85], v[144:147], v[200:203], v[82:85]
	v_mfma_f32_16x16x32_bf16 v[78:81], v[152:155], v[200:203], v[78:81]
	s_setprio 0
	s_setprio 1
	v_mfma_f32_16x16x32_bf16 v[122:125], v[156:159], v[172:175], v[122:125]
	v_mfma_f32_16x16x32_bf16 v[118:121], v[164:167], v[172:175], v[118:121]
	v_mfma_f32_16x16x32_bf16 v[106:109], v[156:159], v[180:183], v[106:109]
	v_mfma_f32_16x16x32_bf16 v[102:105], v[164:167], v[180:183], v[102:105]
	v_mfma_f32_16x16x32_bf16 v[90:93], v[156:159], v[188:191], v[90:93]
	v_mfma_f32_16x16x32_bf16 v[86:89], v[164:167], v[188:191], v[86:89]
	v_mfma_f32_16x16x32_bf16 v[74:77], v[156:159], v[196:199], v[74:77]
	v_mfma_f32_16x16x32_bf16 v[70:73], v[164:167], v[196:199], v[70:73]
	v_mfma_f32_16x16x32_bf16 v[122:125], v[160:163], v[176:179], v[122:125]
	v_mfma_f32_16x16x32_bf16 v[118:121], v[168:171], v[176:179], v[118:121]
	v_mfma_f32_16x16x32_bf16 v[106:109], v[160:163], v[184:187], v[106:109]
	v_mfma_f32_16x16x32_bf16 v[102:105], v[168:171], v[184:187], v[102:105]
	v_mfma_f32_16x16x32_bf16 v[90:93], v[160:163], v[192:195], v[90:93]
	v_mfma_f32_16x16x32_bf16 v[86:89], v[168:171], v[192:195], v[86:89]
	v_mfma_f32_16x16x32_bf16 v[74:77], v[160:163], v[200:203], v[74:77]
	v_mfma_f32_16x16x32_bf16 v[70:73], v[168:171], v[200:203], v[70:73]
	s_setprio 0
	s_barrier
	s_add_i32 s60, s62, s42
	s_mov_b32 m0, s60
	ds_read_b128 v[172:175], v5 offset:16384
	ds_read_b128 v[176:179], v5 offset:17408
	ds_read_b128 v[180:183], v5 offset:18432
	ds_read_b128 v[184:187], v5 offset:19456
	ds_read_b128 v[188:191], v5 offset:20480
	ds_read_b128 v[192:195], v5 offset:21504
	ds_read_b128 v[196:199], v5 offset:22528
	ds_read_b128 v[200:203], v5 offset:23552
	global_load_lds_dwordx4 v134, s[38:39]
	s_add_i32 m0, s60, 0x2000
	s_add_i32 s60, s63, s42
	global_load_lds_dwordx4 v138, s[38:39]
	s_add_u32 s38, s38, 0x100000
	s_addc_u32 s39, s39, 0
	s_mov_b32 m0, s60
	s_nop 0
	global_load_lds_dwordx4 v134, s[38:39]
	s_add_i32 m0, s60, 0x2000
	s_nop 0
	global_load_lds_dwordx4 v138, s[38:39]
	s_mov_b32 m0, s29
	s_nop 0
	global_load_lds_dwordx4 v2, s[36:37]
	s_mov_b32 m0, s43
	s_nop 0
	global_load_lds_dwordx4 v136, s[36:37]
	s_waitcnt vmcnt(8)
	s_waitcnt lgkmcnt(0)
	s_barrier
	s_setprio 1
	v_mfma_f32_16x16x32_bf16 v[66:69], v[140:143], v[172:175], v[66:69]
	v_mfma_f32_16x16x32_bf16 v[62:65], v[148:151], v[172:175], v[62:65]
	v_mfma_f32_16x16x32_bf16 v[50:53], v[140:143], v[180:183], v[50:53]
	v_mfma_f32_16x16x32_bf16 v[46:49], v[148:151], v[180:183], v[46:49]
	v_mfma_f32_16x16x32_bf16 v[34:37], v[140:143], v[188:191], v[34:37]
	v_mfma_f32_16x16x32_bf16 v[30:33], v[148:151], v[188:191], v[30:33]
	v_mfma_f32_16x16x32_bf16 v[18:21], v[140:143], v[196:199], v[18:21]
	v_mfma_f32_16x16x32_bf16 v[14:17], v[148:151], v[196:199], v[14:17]
	v_mfma_f32_16x16x32_bf16 v[66:69], v[144:147], v[176:179], v[66:69]
	v_mfma_f32_16x16x32_bf16 v[62:65], v[152:155], v[176:179], v[62:65]
	v_mfma_f32_16x16x32_bf16 v[50:53], v[144:147], v[184:187], v[50:53]
	v_mfma_f32_16x16x32_bf16 v[46:49], v[152:155], v[184:187], v[46:49]
	v_mfma_f32_16x16x32_bf16 v[34:37], v[144:147], v[192:195], v[34:37]
	v_mfma_f32_16x16x32_bf16 v[30:33], v[152:155], v[192:195], v[30:33]
	v_mfma_f32_16x16x32_bf16 v[18:21], v[144:147], v[200:203], v[18:21]
	v_mfma_f32_16x16x32_bf16 v[14:17], v[152:155], v[200:203], v[14:17]
	s_setprio 0
	s_setprio 1
	v_mfma_f32_16x16x32_bf16 v[58:61], v[156:159], v[172:175], v[58:61]
	v_mfma_f32_16x16x32_bf16 v[54:57], v[164:167], v[172:175], v[54:57]
	v_mfma_f32_16x16x32_bf16 v[42:45], v[156:159], v[180:183], v[42:45]
	v_mfma_f32_16x16x32_bf16 v[38:41], v[164:167], v[180:183], v[38:41]
	v_mfma_f32_16x16x32_bf16 v[26:29], v[156:159], v[188:191], v[26:29]
	v_mfma_f32_16x16x32_bf16 v[22:25], v[164:167], v[188:191], v[22:25]
	v_mfma_f32_16x16x32_bf16 v[10:13], v[156:159], v[196:199], v[10:13]
	v_mfma_f32_16x16x32_bf16 v[6:9], v[164:167], v[196:199], v[6:9]
	v_mfma_f32_16x16x32_bf16 v[58:61], v[160:163], v[176:179], v[58:61]
	v_mfma_f32_16x16x32_bf16 v[54:57], v[168:171], v[176:179], v[54:57]
	v_mfma_f32_16x16x32_bf16 v[42:45], v[160:163], v[184:187], v[42:45]
	v_mfma_f32_16x16x32_bf16 v[38:41], v[168:171], v[184:187], v[38:41]
	v_mfma_f32_16x16x32_bf16 v[26:29], v[160:163], v[192:195], v[26:29]
	v_mfma_f32_16x16x32_bf16 v[22:25], v[168:171], v[192:195], v[22:25]
	v_mfma_f32_16x16x32_bf16 v[10:13], v[160:163], v[200:203], v[10:13]
	v_mfma_f32_16x16x32_bf16 v[6:9], v[168:171], v[200:203], v[6:9]
	s_setprio 0
	s_barrier
	s_add_i32 s38, 0, 0x18000
	s_add_i32 s39, 0, 0x1c000
	v_add_u32_e32 v152, s38, v1
	v_add_u32_e32 v168, s39, v1
	ds_read_b128 v[140:143], v152
	ds_read_b128 v[144:147], v152 offset:1024
	ds_read_b128 v[148:151], v152 offset:2048
	ds_read_b128 v[152:155], v152 offset:3072
	ds_read_b128 v[156:159], v168
	ds_read_b128 v[160:163], v168 offset:1024
	ds_read_b128 v[164:167], v168 offset:2048
	ds_read_b128 v[168:171], v168 offset:3072
	s_add_u32 s36, s36, 0x100000
	s_addc_u32 s37, s37, 0
	s_mov_b32 m0, s48
	ds_read_b128 v[172:175], v5 offset:32768
	ds_read_b128 v[176:179], v5 offset:33792
	ds_read_b128 v[180:183], v5 offset:34816
	ds_read_b128 v[184:187], v5 offset:35840
	ds_read_b128 v[188:191], v5 offset:36864
	ds_read_b128 v[192:195], v5 offset:37888
	ds_read_b128 v[196:199], v5 offset:38912
	ds_read_b128 v[200:203], v5 offset:39936
	global_load_lds_dwordx4 v2, s[36:37]
	s_mov_b32 m0, s49
	s_nop 0
	global_load_lds_dwordx4 v136, s[36:37]
	s_waitcnt vmcnt(8)
	s_waitcnt lgkmcnt(0)
	s_barrier
	s_setprio 1
	v_mfma_f32_16x16x32_bf16 v[130:133], v[140:143], v[172:175], v[130:133]
	v_mfma_f32_16x16x32_bf16 v[126:129], v[148:151], v[172:175], v[126:129]
	v_mfma_f32_16x16x32_bf16 v[114:117], v[140:143], v[180:183], v[114:117]
	v_mfma_f32_16x16x32_bf16 v[110:113], v[148:151], v[180:183], v[110:113]
	v_mfma_f32_16x16x32_bf16 v[98:101], v[140:143], v[188:191], v[98:101]
	v_mfma_f32_16x16x32_bf16 v[94:97], v[148:151], v[188:191], v[94:97]
	v_mfma_f32_16x16x32_bf16 v[82:85], v[140:143], v[196:199], v[82:85]
	v_mfma_f32_16x16x32_bf16 v[78:81], v[148:151], v[196:199], v[78:81]
	v_mfma_f32_16x16x32_bf16 v[130:133], v[144:147], v[176:179], v[130:133]
	v_mfma_f32_16x16x32_bf16 v[126:129], v[152:155], v[176:179], v[126:129]
	v_mfma_f32_16x16x32_bf16 v[114:117], v[144:147], v[184:187], v[114:117]
	v_mfma_f32_16x16x32_bf16 v[110:113], v[152:155], v[184:187], v[110:113]
	v_mfma_f32_16x16x32_bf16 v[98:101], v[144:147], v[192:195], v[98:101]
	v_mfma_f32_16x16x32_bf16 v[94:97], v[152:155], v[192:195], v[94:97]
	v_mfma_f32_16x16x32_bf16 v[82:85], v[144:147], v[200:203], v[82:85]
	v_mfma_f32_16x16x32_bf16 v[78:81], v[152:155], v[200:203], v[78:81]
	s_setprio 0
	s_setprio 1
	v_mfma_f32_16x16x32_bf16 v[122:125], v[156:159], v[172:175], v[122:125]
	v_mfma_f32_16x16x32_bf16 v[118:121], v[164:167], v[172:175], v[118:121]
	v_mfma_f32_16x16x32_bf16 v[106:109], v[156:159], v[180:183], v[106:109]
	v_mfma_f32_16x16x32_bf16 v[102:105], v[164:167], v[180:183], v[102:105]
	v_mfma_f32_16x16x32_bf16 v[90:93], v[156:159], v[188:191], v[90:93]
	v_mfma_f32_16x16x32_bf16 v[86:89], v[164:167], v[188:191], v[86:89]
	v_mfma_f32_16x16x32_bf16 v[74:77], v[156:159], v[196:199], v[74:77]
	v_mfma_f32_16x16x32_bf16 v[70:73], v[164:167], v[196:199], v[70:73]
	v_mfma_f32_16x16x32_bf16 v[122:125], v[160:163], v[176:179], v[122:125]
	v_mfma_f32_16x16x32_bf16 v[118:121], v[168:171], v[176:179], v[118:121]
	v_mfma_f32_16x16x32_bf16 v[106:109], v[160:163], v[184:187], v[106:109]
	v_mfma_f32_16x16x32_bf16 v[102:105], v[168:171], v[184:187], v[102:105]
	v_mfma_f32_16x16x32_bf16 v[90:93], v[160:163], v[192:195], v[90:93]
	v_mfma_f32_16x16x32_bf16 v[86:89], v[168:171], v[192:195], v[86:89]
	v_mfma_f32_16x16x32_bf16 v[74:77], v[160:163], v[200:203], v[74:77]
	v_mfma_f32_16x16x32_bf16 v[70:73], v[168:171], v[200:203], v[70:73]
	s_setprio 0
	s_barrier
	s_add_i32 s36, s38, s42
	s_mov_b32 m0, s36
	ds_read_b128 v[172:175], v5 offset:49152
	ds_read_b128 v[176:179], v5 offset:50176
	ds_read_b128 v[180:183], v5 offset:51200
	ds_read_b128 v[184:187], v5 offset:52224
	ds_read_b128 v[188:191], v5 offset:53248
	ds_read_b128 v[192:195], v5 offset:54272
	ds_read_b128 v[196:199], v5 offset:55296
	ds_read_b128 v[200:203], v5 offset:56320
	global_load_lds_dwordx4 v134, s[34:35]
	s_add_i32 m0, s36, 0x2000
	s_add_i32 s36, s39, s42
	global_load_lds_dwordx4 v138, s[34:35]
	s_add_u32 s34, s34, 0x100000
	s_addc_u32 s35, s35, 0
	s_mov_b32 m0, s36
	s_nop 0
	global_load_lds_dwordx4 v134, s[34:35]
	s_add_i32 m0, s36, 0x2000
	s_nop 0
	global_load_lds_dwordx4 v138, s[34:35]
	s_mov_b32 m0, s52
	s_nop 0
	global_load_lds_dwordx4 v2, s[30:31]
	s_mov_b32 m0, s53
	s_nop 0
	global_load_lds_dwordx4 v136, s[30:31]
	s_waitcnt vmcnt(8)
	s_waitcnt lgkmcnt(0)
	s_barrier
	s_setprio 1
	v_mfma_f32_16x16x32_bf16 v[66:69], v[140:143], v[172:175], v[66:69]
	v_mfma_f32_16x16x32_bf16 v[62:65], v[148:151], v[172:175], v[62:65]
	v_mfma_f32_16x16x32_bf16 v[50:53], v[140:143], v[180:183], v[50:53]
	v_mfma_f32_16x16x32_bf16 v[46:49], v[148:151], v[180:183], v[46:49]
	v_mfma_f32_16x16x32_bf16 v[34:37], v[140:143], v[188:191], v[34:37]
	v_mfma_f32_16x16x32_bf16 v[30:33], v[148:151], v[188:191], v[30:33]
	v_mfma_f32_16x16x32_bf16 v[18:21], v[140:143], v[196:199], v[18:21]
	v_mfma_f32_16x16x32_bf16 v[14:17], v[148:151], v[196:199], v[14:17]
	v_mfma_f32_16x16x32_bf16 v[66:69], v[144:147], v[176:179], v[66:69]
	v_mfma_f32_16x16x32_bf16 v[62:65], v[152:155], v[176:179], v[62:65]
	v_mfma_f32_16x16x32_bf16 v[50:53], v[144:147], v[184:187], v[50:53]
	v_mfma_f32_16x16x32_bf16 v[46:49], v[152:155], v[184:187], v[46:49]
	v_mfma_f32_16x16x32_bf16 v[34:37], v[144:147], v[192:195], v[34:37]
	v_mfma_f32_16x16x32_bf16 v[30:33], v[152:155], v[192:195], v[30:33]
	v_mfma_f32_16x16x32_bf16 v[18:21], v[144:147], v[200:203], v[18:21]
	v_mfma_f32_16x16x32_bf16 v[14:17], v[152:155], v[200:203], v[14:17]
	s_setprio 0
	s_setprio 1
	v_mfma_f32_16x16x32_bf16 v[58:61], v[156:159], v[172:175], v[58:61]
	v_mfma_f32_16x16x32_bf16 v[54:57], v[164:167], v[172:175], v[54:57]
	v_mfma_f32_16x16x32_bf16 v[42:45], v[156:159], v[180:183], v[42:45]
	v_mfma_f32_16x16x32_bf16 v[38:41], v[164:167], v[180:183], v[38:41]
	v_mfma_f32_16x16x32_bf16 v[26:29], v[156:159], v[188:191], v[26:29]
	v_mfma_f32_16x16x32_bf16 v[22:25], v[164:167], v[188:191], v[22:25]
	v_mfma_f32_16x16x32_bf16 v[10:13], v[156:159], v[196:199], v[10:13]
	v_mfma_f32_16x16x32_bf16 v[6:9], v[164:167], v[196:199], v[6:9]
	v_mfma_f32_16x16x32_bf16 v[58:61], v[160:163], v[176:179], v[58:61]
	v_mfma_f32_16x16x32_bf16 v[54:57], v[168:171], v[176:179], v[54:57]
	v_mfma_f32_16x16x32_bf16 v[42:45], v[160:163], v[184:187], v[42:45]
	v_mfma_f32_16x16x32_bf16 v[38:41], v[168:171], v[184:187], v[38:41]
	v_mfma_f32_16x16x32_bf16 v[26:29], v[160:163], v[192:195], v[26:29]
	v_mfma_f32_16x16x32_bf16 v[22:25], v[168:171], v[192:195], v[22:25]
	v_mfma_f32_16x16x32_bf16 v[10:13], v[160:163], v[200:203], v[10:13]
	v_mfma_f32_16x16x32_bf16 v[6:9], v[168:171], v[200:203], v[6:9]
	s_setprio 0
	s_barrier
	s_add_i32 s59, s59, 2
	s_add_u32 s55, s55, 0x100
	s_addc_u32 s56, s56, 0
	s_add_u32 s57, s57, 0x100
	s_addc_u32 s58, s58, 0
	s_cmp_gt_u32 s59, 61
	s_cbranch_scc0 .LBB0_131
	s_and_b64 vcc, exec, s[8:9]
	s_cbranch_vccz .LBB0_134
	s_barrier

.LBB0_251:
	s_add_u32 s56, s52, 0xffffff80
	s_addc_u32 s57, s53, -1
	s_cmp_eq_u32 s54, 60
	s_cselect_b32 s28, s2, s52
	s_cselect_b32 s29, s1, s53
	s_cselect_b32 s31, s11, s33
	s_cselect_b32 s30, s15, s19
	s_add_u32 s24, s28, 0x80
	s_addc_u32 s25, s29, 0
	s_add_u32 s26, s30, 0x80
	s_addc_u32 s27, s31, 0
	s_add_i32 s55, 0, 0x10000
	s_add_i32 s58, 0, 0x14000
	v_add_u32_e32 v152, s55, v1
	v_add_u32_e32 v168, s58, v1
	ds_read_b128 v[140:143], v152
	ds_read_b128 v[144:147], v152 offset:1024
	ds_read_b128 v[148:151], v152 offset:2048
	ds_read_b128 v[152:155], v152 offset:3072
	ds_read_b128 v[156:159], v168
	ds_read_b128 v[160:163], v168 offset:1024
	ds_read_b128 v[164:167], v168 offset:2048
	ds_read_b128 v[168:171], v168 offset:3072
	s_add_u32 s56, s56, 0x100000
	s_addc_u32 s57, s57, 0
	s_add_i32 m0, s23, 0xc000
	ds_read_b128 v[172:175], v5
	ds_read_b128 v[176:179], v5 offset:1024
	ds_read_b128 v[180:183], v5 offset:2048
	ds_read_b128 v[184:187], v5 offset:3072
	ds_read_b128 v[188:191], v5 offset:4096
	ds_read_b128 v[192:195], v5 offset:5120
	ds_read_b128 v[196:199], v5 offset:6144
	ds_read_b128 v[200:203], v5 offset:7168
	global_load_lds_dwordx4 v138, s[56:57]
	s_add_i32 m0, s23, 0xe000
	s_nop 0
	global_load_lds_dwordx4 v134, s[56:57]
	s_waitcnt vmcnt(8)
	s_waitcnt lgkmcnt(0)
	s_barrier
	s_setprio 1
	v_mfma_f32_16x16x32_bf16 v[6:9], v[140:143], v[172:175], v[6:9]
	v_mfma_f32_16x16x32_bf16 v[10:13], v[148:151], v[172:175], v[10:13]
	v_mfma_f32_16x16x32_bf16 v[22:25], v[140:143], v[180:183], v[22:25]
	v_mfma_f32_16x16x32_bf16 v[26:29], v[148:151], v[180:183], v[26:29]
	v_mfma_f32_16x16x32_bf16 v[38:41], v[140:143], v[188:191], v[38:41]
	v_mfma_f32_16x16x32_bf16 v[42:45], v[148:151], v[188:191], v[42:45]
	v_mfma_f32_16x16x32_bf16 v[54:57], v[140:143], v[196:199], v[54:57]
	v_mfma_f32_16x16x32_bf16 v[58:61], v[148:151], v[196:199], v[58:61]
	v_mfma_f32_16x16x32_bf16 v[6:9], v[144:147], v[176:179], v[6:9]
	v_mfma_f32_16x16x32_bf16 v[10:13], v[152:155], v[176:179], v[10:13]
	v_mfma_f32_16x16x32_bf16 v[22:25], v[144:147], v[184:187], v[22:25]
	v_mfma_f32_16x16x32_bf16 v[26:29], v[152:155], v[184:187], v[26:29]
	v_mfma_f32_16x16x32_bf16 v[38:41], v[144:147], v[192:195], v[38:41]
	v_mfma_f32_16x16x32_bf16 v[42:45], v[152:155], v[192:195], v[42:45]
	v_mfma_f32_16x16x32_bf16 v[54:57], v[144:147], v[200:203], v[54:57]
	v_mfma_f32_16x16x32_bf16 v[58:61], v[152:155], v[200:203], v[58:61]
	s_setprio 0
	s_setprio 1
	v_mfma_f32_16x16x32_bf16 v[14:17], v[156:159], v[172:175], v[14:17]
	v_mfma_f32_16x16x32_bf16 v[18:21], v[164:167], v[172:175], v[18:21]
	v_mfma_f32_16x16x32_bf16 v[30:33], v[156:159], v[180:183], v[30:33]
	v_mfma_f32_16x16x32_bf16 v[34:37], v[164:167], v[180:183], v[34:37]
	v_mfma_f32_16x16x32_bf16 v[46:49], v[156:159], v[188:191], v[46:49]
	v_mfma_f32_16x16x32_bf16 v[50:53], v[164:167], v[188:191], v[50:53]
	v_mfma_f32_16x16x32_bf16 v[62:65], v[156:159], v[196:199], v[62:65]
	v_mfma_f32_16x16x32_bf16 v[66:69], v[164:167], v[196:199], v[66:69]
	v_mfma_f32_16x16x32_bf16 v[14:17], v[160:163], v[176:179], v[14:17]
	v_mfma_f32_16x16x32_bf16 v[18:21], v[168:171], v[176:179], v[18:21]
	v_mfma_f32_16x16x32_bf16 v[30:33], v[160:163], v[184:187], v[30:33]
	v_mfma_f32_16x16x32_bf16 v[34:37], v[168:171], v[184:187], v[34:37]
	v_mfma_f32_16x16x32_bf16 v[46:49], v[160:163], v[192:195], v[46:49]
	v_mfma_f32_16x16x32_bf16 v[50:53], v[168:171], v[192:195], v[50:53]
	v_mfma_f32_16x16x32_bf16 v[62:65], v[160:163], v[200:203], v[62:65]
	v_mfma_f32_16x16x32_bf16 v[66:69], v[168:171], v[200:203], v[66:69]
	s_setprio 0
	s_barrier
	s_add_i32 s55, s55, s37
	s_mov_b32 m0, s55
	ds_read_b128 v[172:175], v5 offset:16384
	ds_read_b128 v[176:179], v5 offset:17408
	ds_read_b128 v[180:183], v5 offset:18432
	ds_read_b128 v[184:187], v5 offset:19456
	ds_read_b128 v[188:191], v5 offset:20480
	ds_read_b128 v[192:195], v5 offset:21504
	ds_read_b128 v[196:199], v5 offset:22528
	ds_read_b128 v[200:203], v5 offset:23552
	global_load_lds_dwordx4 v136, s[30:31]
	s_add_i32 m0, s55, 0x2000
	s_add_i32 s55, s58, s37
	global_load_lds_dwordx4 v2, s[30:31]
	s_add_u32 s30, s30, 0x100000
	s_addc_u32 s31, s31, 0
	s_mov_b32 m0, s55
	s_nop 0
	global_load_lds_dwordx4 v136, s[30:31]
	s_add_i32 m0, s55, 0x2000
	s_nop 0
	global_load_lds_dwordx4 v2, s[30:31]
	s_mov_b32 m0, s23
	s_nop 0
	global_load_lds_dwordx4 v138, s[28:29]
	s_mov_b32 m0, s40
	s_nop 0
	global_load_lds_dwordx4 v134, s[28:29]
	s_waitcnt vmcnt(8)
	s_waitcnt lgkmcnt(0)
	s_barrier
	s_setprio 1
	v_mfma_f32_16x16x32_bf16 v[70:73], v[140:143], v[172:175], v[70:73]
	v_mfma_f32_16x16x32_bf16 v[74:77], v[148:151], v[172:175], v[74:77]
	v_mfma_f32_16x16x32_bf16 v[86:89], v[140:143], v[180:183], v[86:89]
	v_mfma_f32_16x16x32_bf16 v[90:93], v[148:151], v[180:183], v[90:93]
	v_mfma_f32_16x16x32_bf16 v[102:105], v[140:143], v[188:191], v[102:105]
	v_mfma_f32_16x16x32_bf16 v[106:109], v[148:151], v[188:191], v[106:109]
	v_mfma_f32_16x16x32_bf16 v[130:133], v[140:143], v[196:199], v[130:133]
	v_mfma_f32_16x16x32_bf16 v[126:129], v[148:151], v[196:199], v[126:129]
	v_mfma_f32_16x16x32_bf16 v[70:73], v[144:147], v[176:179], v[70:73]
	v_mfma_f32_16x16x32_bf16 v[74:77], v[152:155], v[176:179], v[74:77]
	v_mfma_f32_16x16x32_bf16 v[86:89], v[144:147], v[184:187], v[86:89]
	v_mfma_f32_16x16x32_bf16 v[90:93], v[152:155], v[184:187], v[90:93]
	v_mfma_f32_16x16x32_bf16 v[102:105], v[144:147], v[192:195], v[102:105]
	v_mfma_f32_16x16x32_bf16 v[106:109], v[152:155], v[192:195], v[106:109]
	v_mfma_f32_16x16x32_bf16 v[130:133], v[144:147], v[200:203], v[130:133]
	v_mfma_f32_16x16x32_bf16 v[126:129], v[152:155], v[200:203], v[126:129]
	s_setprio 0
	s_setprio 1
	v_mfma_f32_16x16x32_bf16 v[78:81], v[156:159], v[172:175], v[78:81]
	v_mfma_f32_16x16x32_bf16 v[82:85], v[164:167], v[172:175], v[82:85]
	v_mfma_f32_16x16x32_bf16 v[94:97], v[156:159], v[180:183], v[94:97]
	v_mfma_f32_16x16x32_bf16 v[98:101], v[164:167], v[180:183], v[98:101]
	v_mfma_f32_16x16x32_bf16 v[110:113], v[156:159], v[188:191], v[110:113]
	v_mfma_f32_16x16x32_bf16 v[114:117], v[164:167], v[188:191], v[114:117]
	v_mfma_f32_16x16x32_bf16 v[122:125], v[156:159], v[196:199], v[122:125]
	v_mfma_f32_16x16x32_bf16 v[118:121], v[164:167], v[196:199], v[118:121]
	v_mfma_f32_16x16x32_bf16 v[78:81], v[160:163], v[176:179], v[78:81]
	v_mfma_f32_16x16x32_bf16 v[82:85], v[168:171], v[176:179], v[82:85]
	v_mfma_f32_16x16x32_bf16 v[94:97], v[160:163], v[184:187], v[94:97]
	v_mfma_f32_16x16x32_bf16 v[98:101], v[168:171], v[184:187], v[98:101]
	v_mfma_f32_16x16x32_bf16 v[110:113], v[160:163], v[192:195], v[110:113]
	v_mfma_f32_16x16x32_bf16 v[114:117], v[168:171], v[192:195], v[114:117]
	v_mfma_f32_16x16x32_bf16 v[122:125], v[160:163], v[200:203], v[122:125]
	v_mfma_f32_16x16x32_bf16 v[118:121], v[168:171], v[200:203], v[118:121]
	s_setprio 0
	s_barrier
	s_add_i32 s30, 0, 0x18000
	s_add_i32 s31, 0, 0x1c000
	v_add_u32_e32 v152, s30, v1
	v_add_u32_e32 v168, s31, v1
	ds_read_b128 v[140:143], v152
	ds_read_b128 v[144:147], v152 offset:1024
	ds_read_b128 v[148:151], v152 offset:2048
	ds_read_b128 v[152:155], v152 offset:3072
	ds_read_b128 v[156:159], v168
	ds_read_b128 v[160:163], v168 offset:1024
	ds_read_b128 v[164:167], v168 offset:2048
	ds_read_b128 v[168:171], v168 offset:3072
	s_add_u32 s28, s28, 0x100000
	s_addc_u32 s29, s29, 0
	s_mov_b32 m0, s41
	ds_read_b128 v[172:175], v5 offset:32768
	ds_read_b128 v[176:179], v5 offset:33792
	ds_read_b128 v[180:183], v5 offset:34816
	ds_read_b128 v[184:187], v5 offset:35840
	ds_read_b128 v[188:191], v5 offset:36864
	ds_read_b128 v[192:195], v5 offset:37888
	ds_read_b128 v[196:199], v5 offset:38912
	ds_read_b128 v[200:203], v5 offset:39936
	global_load_lds_dwordx4 v138, s[28:29]
	s_mov_b32 m0, s42
	s_nop 0
	global_load_lds_dwordx4 v134, s[28:29]
	s_waitcnt vmcnt(8)
	s_waitcnt lgkmcnt(0)
	s_barrier
	s_setprio 1
	v_mfma_f32_16x16x32_bf16 v[6:9], v[140:143], v[172:175], v[6:9]
	v_mfma_f32_16x16x32_bf16 v[10:13], v[148:151], v[172:175], v[10:13]
	v_mfma_f32_16x16x32_bf16 v[22:25], v[140:143], v[180:183], v[22:25]
	v_mfma_f32_16x16x32_bf16 v[26:29], v[148:151], v[180:183], v[26:29]
	v_mfma_f32_16x16x32_bf16 v[38:41], v[140:143], v[188:191], v[38:41]
	v_mfma_f32_16x16x32_bf16 v[42:45], v[148:151], v[188:191], v[42:45]
	v_mfma_f32_16x16x32_bf16 v[54:57], v[140:143], v[196:199], v[54:57]
	v_mfma_f32_16x16x32_bf16 v[58:61], v[148:151], v[196:199], v[58:61]
	v_mfma_f32_16x16x32_bf16 v[6:9], v[144:147], v[176:179], v[6:9]
	v_mfma_f32_16x16x32_bf16 v[10:13], v[152:155], v[176:179], v[10:13]
	v_mfma_f32_16x16x32_bf16 v[22:25], v[144:147], v[184:187], v[22:25]
	v_mfma_f32_16x16x32_bf16 v[26:29], v[152:155], v[184:187], v[26:29]
	v_mfma_f32_16x16x32_bf16 v[38:41], v[144:147], v[192:195], v[38:41]
	v_mfma_f32_16x16x32_bf16 v[42:45], v[152:155], v[192:195], v[42:45]
	v_mfma_f32_16x16x32_bf16 v[54:57], v[144:147], v[200:203], v[54:57]
	v_mfma_f32_16x16x32_bf16 v[58:61], v[152:155], v[200:203], v[58:61]
	s_setprio 0
	s_setprio 1
	v_mfma_f32_16x16x32_bf16 v[14:17], v[156:159], v[172:175], v[14:17]
	v_mfma_f32_16x16x32_bf16 v[18:21], v[164:167], v[172:175], v[18:21]
	v_mfma_f32_16x16x32_bf16 v[30:33], v[156:159], v[180:183], v[30:33]
	v_mfma_f32_16x16x32_bf16 v[34:37], v[164:167], v[180:183], v[34:37]
	v_mfma_f32_16x16x32_bf16 v[46:49], v[156:159], v[188:191], v[46:49]
	v_mfma_f32_16x16x32_bf16 v[50:53], v[164:167], v[188:191], v[50:53]
	v_mfma_f32_16x16x32_bf16 v[62:65], v[156:159], v[196:199], v[62:65]
	v_mfma_f32_16x16x32_bf16 v[66:69], v[164:167], v[196:199], v[66:69]
	v_mfma_f32_16x16x32_bf16 v[14:17], v[160:163], v[176:179], v[14:17]
	v_mfma_f32_16x16x32_bf16 v[18:21], v[168:171], v[176:179], v[18:21]
	v_mfma_f32_16x16x32_bf16 v[30:33], v[160:163], v[184:187], v[30:33]
	v_mfma_f32_16x16x32_bf16 v[34:37], v[168:171], v[184:187], v[34:37]
	v_mfma_f32_16x16x32_bf16 v[46:49], v[160:163], v[192:195], v[46:49]
	v_mfma_f32_16x16x32_bf16 v[50:53], v[168:171], v[192:195], v[50:53]
	v_mfma_f32_16x16x32_bf16 v[62:65], v[160:163], v[200:203], v[62:65]
	v_mfma_f32_16x16x32_bf16 v[66:69], v[168:171], v[200:203], v[66:69]
	s_setprio 0
	s_barrier
	s_add_i32 s28, s30, s37
	s_mov_b32 m0, s28
	ds_read_b128 v[172:175], v5 offset:49152
	ds_read_b128 v[176:179], v5 offset:50176
	ds_read_b128 v[180:183], v5 offset:51200
	ds_read_b128 v[184:187], v5 offset:52224
	ds_read_b128 v[188:191], v5 offset:53248
	ds_read_b128 v[192:195], v5 offset:54272
	ds_read_b128 v[196:199], v5 offset:55296
	ds_read_b128 v[200:203], v5 offset:56320
	global_load_lds_dwordx4 v136, s[26:27]
	s_add_i32 m0, s28, 0x2000
	s_add_i32 s28, s31, s37
	global_load_lds_dwordx4 v2, s[26:27]
	s_add_u32 s26, s26, 0x100000
	s_addc_u32 s27, s27, 0
	s_mov_b32 m0, s28
	s_nop 0
	global_load_lds_dwordx4 v136, s[26:27]
	s_add_i32 m0, s28, 0x2000
	s_nop 0
	global_load_lds_dwordx4 v2, s[26:27]
	s_mov_b32 m0, s49
	s_nop 0
	global_load_lds_dwordx4 v138, s[24:25]
	s_mov_b32 m0, s50
	s_nop 0
	global_load_lds_dwordx4 v134, s[24:25]
	s_waitcnt vmcnt(8)
	s_waitcnt lgkmcnt(0)
	s_barrier
	s_setprio 1
	v_mfma_f32_16x16x32_bf16 v[70:73], v[140:143], v[172:175], v[70:73]
	v_mfma_f32_16x16x32_bf16 v[74:77], v[148:151], v[172:175], v[74:77]
	v_mfma_f32_16x16x32_bf16 v[86:89], v[140:143], v[180:183], v[86:89]
	v_mfma_f32_16x16x32_bf16 v[90:93], v[148:151], v[180:183], v[90:93]
	v_mfma_f32_16x16x32_bf16 v[102:105], v[140:143], v[188:191], v[102:105]
	v_mfma_f32_16x16x32_bf16 v[106:109], v[148:151], v[188:191], v[106:109]
	v_mfma_f32_16x16x32_bf16 v[130:133], v[140:143], v[196:199], v[130:133]
	v_mfma_f32_16x16x32_bf16 v[126:129], v[148:151], v[196:199], v[126:129]
	v_mfma_f32_16x16x32_bf16 v[70:73], v[144:147], v[176:179], v[70:73]
	v_mfma_f32_16x16x32_bf16 v[74:77], v[152:155], v[176:179], v[74:77]
	v_mfma_f32_16x16x32_bf16 v[86:89], v[144:147], v[184:187], v[86:89]
	v_mfma_f32_16x16x32_bf16 v[90:93], v[152:155], v[184:187], v[90:93]
	v_mfma_f32_16x16x32_bf16 v[102:105], v[144:147], v[192:195], v[102:105]
	v_mfma_f32_16x16x32_bf16 v[106:109], v[152:155], v[192:195], v[106:109]
	v_mfma_f32_16x16x32_bf16 v[130:133], v[144:147], v[200:203], v[130:133]
	v_mfma_f32_16x16x32_bf16 v[126:129], v[152:155], v[200:203], v[126:129]
	s_setprio 0
	s_setprio 1
	v_mfma_f32_16x16x32_bf16 v[78:81], v[156:159], v[172:175], v[78:81]
	v_mfma_f32_16x16x32_bf16 v[82:85], v[164:167], v[172:175], v[82:85]
	v_mfma_f32_16x16x32_bf16 v[94:97], v[156:159], v[180:183], v[94:97]
	v_mfma_f32_16x16x32_bf16 v[98:101], v[164:167], v[180:183], v[98:101]
	v_mfma_f32_16x16x32_bf16 v[110:113], v[156:159], v[188:191], v[110:113]
	v_mfma_f32_16x16x32_bf16 v[114:117], v[164:167], v[188:191], v[114:117]
	v_mfma_f32_16x16x32_bf16 v[122:125], v[156:159], v[196:199], v[122:125]
	v_mfma_f32_16x16x32_bf16 v[118:121], v[164:167], v[196:199], v[118:121]
	v_mfma_f32_16x16x32_bf16 v[78:81], v[160:163], v[176:179], v[78:81]
	v_mfma_f32_16x16x32_bf16 v[82:85], v[168:171], v[176:179], v[82:85]
	v_mfma_f32_16x16x32_bf16 v[94:97], v[160:163], v[184:187], v[94:97]
	v_mfma_f32_16x16x32_bf16 v[98:101], v[168:171], v[184:187], v[98:101]
	v_mfma_f32_16x16x32_bf16 v[110:113], v[160:163], v[192:195], v[110:113]
	v_mfma_f32_16x16x32_bf16 v[114:117], v[168:171], v[192:195], v[114:117]
	v_mfma_f32_16x16x32_bf16 v[122:125], v[160:163], v[200:203], v[122:125]
	v_mfma_f32_16x16x32_bf16 v[118:121], v[168:171], v[200:203], v[118:121]
	s_setprio 0
	s_barrier
	s_add_i32 s54, s54, 2
	s_add_u32 s19, s19, 0x100
	s_addc_u32 s33, s33, 0
	s_add_u32 s52, s52, 0x100
	s_addc_u32 s53, s53, 0
	s_cmp_gt_u32 s54, 61
	s_cbranch_scc0 .LBB0_251
	v_mov_b32_e32 v141, v0
	s_lshl_b32 s1, s0, 8
	s_mov_b64 s[24:25], s[84:85]
	s_add_i32 s1, s1, s43
	v_and_or_b32 v140, v141, 15, s1
	v_lshrrev_b32_e32 v141, 1, v141
	s_add_u32 s26, s24, s6
	v_and_or_b32 v148, v141, 24, s48
	s_addc_u32 s27, s25, s7
	v_ashrrev_i32_e32 v141, 31, v140
	v_lshl_add_u64 v[142:143], v[140:141], 2, s[26:27]
	s_mov_b64 s[26:27], 0x10000
	v_lshl_add_u64 v[144:145], v[142:143], 0, s[26:27]
	v_add_co_u32_e32 v142, vcc, s91, v142
	global_load_dword v146, v[144:145], off offset:512
	s_nop 0
	v_addc_co_u32_e32 v143, vcc, 0, v143, vcc
	global_load_dword v142, v[142:143], off
	s_cmp_lt_i32 s22, 8
	s_mov_b64 s[26:27], -1
	global_load_dword v205, v[144:145], off offset:64
	global_load_dword v204, v[144:145], off offset:128
	global_load_dword v203, v[144:145], off offset:192
	global_load_dword v202, v[144:145], off offset:576
	global_load_dword v201, v[144:145], off offset:640
	global_load_dword v200, v[144:145], off offset:704
	s_waitcnt vmcnt(0)
	v_fmamk_f32 v146, v146, 0x39800000, v246
	v_mul_f32_e32 v147, 0x4b800000, v146
	v_fmamk_f32 v142, v142, 0x39800000, v246
	v_cmp_gt_f32_e32 vcc, s95, v142
	v_mul_f32_e32 v143, 0x4b800000, v142
	s_nop 0
	v_cndmask_b32_e32 v142, v142, v143, vcc
	v_rsq_f32_e32 v142, v142
	s_nop 0
	v_mul_f32_e32 v143, 0x45800000, v142
	v_cndmask_b32_e32 v142, v142, v143, vcc
	v_pk_mul_f32 v[8:9], v[8:9], v[142:143] op_sel_hi:[1,0]
	v_pk_mul_f32 v[6:7], v[6:7], v[142:143] op_sel_hi:[1,0]
	v_pk_mul_f32 v[12:13], v[12:13], v[142:143] op_sel_hi:[1,0]
	v_pk_mul_f32 v[10:11], v[10:11], v[142:143] op_sel_hi:[1,0]
	v_pk_mul_f32 v[16:17], v[16:17], v[142:143] op_sel_hi:[1,0]
	v_pk_mul_f32 v[14:15], v[14:15], v[142:143] op_sel_hi:[1,0]
	v_pk_mul_f32 v[20:21], v[20:21], v[142:143] op_sel_hi:[1,0]
	v_pk_mul_f32 v[18:19], v[18:19], v[142:143] op_sel_hi:[1,0]
	s_waitcnt vmcnt(0)
	v_fmamk_f32 v142, v205, 0x39800000, v246
	v_cmp_gt_f32_e32 vcc, s95, v142
	v_mul_f32_e32 v143, 0x4b800000, v142
	s_nop 0
	v_cndmask_b32_e32 v142, v142, v143, vcc
	v_rsq_f32_e32 v142, v142
	s_nop 0
	v_mul_f32_e32 v143, 0x45800000, v142
	v_cndmask_b32_e32 v142, v142, v143, vcc
	v_pk_mul_f32 v[24:25], v[24:25], v[142:143] op_sel_hi:[1,0]
	v_pk_mul_f32 v[22:23], v[22:23], v[142:143] op_sel_hi:[1,0]
	v_pk_mul_f32 v[28:29], v[28:29], v[142:143] op_sel_hi:[1,0]
	v_pk_mul_f32 v[26:27], v[26:27], v[142:143] op_sel_hi:[1,0]
	v_pk_mul_f32 v[32:33], v[32:33], v[142:143] op_sel_hi:[1,0]
	v_pk_mul_f32 v[30:31], v[30:31], v[142:143] op_sel_hi:[1,0]
	v_pk_mul_f32 v[36:37], v[36:37], v[142:143] op_sel_hi:[1,0]
	v_pk_mul_f32 v[34:35], v[34:35], v[142:143] op_sel_hi:[1,0]
	s_waitcnt vmcnt(0)
	v_fmamk_f32 v142, v204, 0x39800000, v246
	v_cmp_gt_f32_e32 vcc, s95, v142
	v_mul_f32_e32 v143, 0x4b800000, v142
	s_nop 0
	v_cndmask_b32_e32 v142, v142, v143, vcc
	v_rsq_f32_e32 v142, v142
	s_nop 0
	v_mul_f32_e32 v143, 0x45800000, v142
	v_cndmask_b32_e32 v142, v142, v143, vcc
	v_pk_mul_f32 v[40:41], v[40:41], v[142:143] op_sel_hi:[1,0]
	v_pk_mul_f32 v[38:39], v[38:39], v[142:143] op_sel_hi:[1,0]
	v_pk_mul_f32 v[44:45], v[44:45], v[142:143] op_sel_hi:[1,0]
	v_pk_mul_f32 v[42:43], v[42:43], v[142:143] op_sel_hi:[1,0]
	v_pk_mul_f32 v[48:49], v[48:49], v[142:143] op_sel_hi:[1,0]
	v_pk_mul_f32 v[46:47], v[46:47], v[142:143] op_sel_hi:[1,0]
	v_pk_mul_f32 v[52:53], v[52:53], v[142:143] op_sel_hi:[1,0]
	v_pk_mul_f32 v[50:51], v[50:51], v[142:143] op_sel_hi:[1,0]
	s_waitcnt vmcnt(0)
	v_fmamk_f32 v142, v203, 0x39800000, v246
	v_cmp_gt_f32_e32 vcc, s95, v142
	v_mul_f32_e32 v143, 0x4b800000, v142
	s_nop 0
	v_cndmask_b32_e32 v142, v142, v143, vcc
	v_rsq_f32_e32 v142, v142
	s_nop 0
	v_mul_f32_e32 v143, 0x45800000, v142
	v_cndmask_b32_e32 v142, v142, v143, vcc
	v_cmp_gt_f32_e32 vcc, s95, v146
	v_pk_mul_f32 v[56:57], v[56:57], v[142:143] op_sel_hi:[1,0]
	v_pk_mul_f32 v[54:55], v[54:55], v[142:143] op_sel_hi:[1,0]
	v_cndmask_b32_e32 v146, v146, v147, vcc
	v_rsq_f32_e32 v146, v146
	v_pk_mul_f32 v[60:61], v[60:61], v[142:143] op_sel_hi:[1,0]
	v_pk_mul_f32 v[58:59], v[58:59], v[142:143] op_sel_hi:[1,0]
	v_pk_mul_f32 v[64:65], v[64:65], v[142:143] op_sel_hi:[1,0]
	v_mul_f32_e32 v147, 0x45800000, v146
	v_cndmask_b32_e32 v146, v146, v147, vcc
	v_pk_mul_f32 v[72:73], v[72:73], v[146:147] op_sel_hi:[1,0]
	v_pk_mul_f32 v[70:71], v[70:71], v[146:147] op_sel_hi:[1,0]
	v_pk_mul_f32 v[76:77], v[76:77], v[146:147] op_sel_hi:[1,0]
	v_pk_mul_f32 v[74:75], v[74:75], v[146:147] op_sel_hi:[1,0]
	v_pk_mul_f32 v[80:81], v[80:81], v[146:147] op_sel_hi:[1,0]
	v_pk_mul_f32 v[78:79], v[78:79], v[146:147] op_sel_hi:[1,0]
	v_pk_mul_f32 v[84:85], v[84:85], v[146:147] op_sel_hi:[1,0]
	v_pk_mul_f32 v[82:83], v[82:83], v[146:147] op_sel_hi:[1,0]
	v_pk_mul_f32 v[62:63], v[62:63], v[142:143] op_sel_hi:[1,0]
	v_pk_mul_f32 v[68:69], v[68:69], v[142:143] op_sel_hi:[1,0]
	v_pk_mul_f32 v[66:67], v[66:67], v[142:143] op_sel_hi:[1,0]
	v_add_u32_e32 v142, 0x80, v140
	v_ashrrev_i32_e32 v143, 31, v142
	s_waitcnt vmcnt(0)
	v_fmamk_f32 v146, v202, 0x39800000, v246
	v_cmp_gt_f32_e32 vcc, s95, v146
	v_mul_f32_e32 v147, 0x4b800000, v146
	s_nop 0
	v_cndmask_b32_e32 v146, v146, v147, vcc
	v_rsq_f32_e32 v146, v146
	s_nop 0
	v_mul_f32_e32 v147, 0x45800000, v146
	v_cndmask_b32_e32 v146, v146, v147, vcc
	v_pk_mul_f32 v[88:89], v[88:89], v[146:147] op_sel_hi:[1,0]
	v_pk_mul_f32 v[86:87], v[86:87], v[146:147] op_sel_hi:[1,0]
	v_pk_mul_f32 v[92:93], v[92:93], v[146:147] op_sel_hi:[1,0]
	v_pk_mul_f32 v[90:91], v[90:91], v[146:147] op_sel_hi:[1,0]
	v_pk_mul_f32 v[96:97], v[96:97], v[146:147] op_sel_hi:[1,0]
	v_pk_mul_f32 v[94:95], v[94:95], v[146:147] op_sel_hi:[1,0]
	v_pk_mul_f32 v[100:101], v[100:101], v[146:147] op_sel_hi:[1,0]
	v_pk_mul_f32 v[98:99], v[98:99], v[146:147] op_sel_hi:[1,0]
	s_waitcnt vmcnt(0)
	v_fmamk_f32 v146, v201, 0x39800000, v246
	v_cmp_gt_f32_e32 vcc, s95, v146
	v_mul_f32_e32 v147, 0x4b800000, v146
	s_waitcnt vmcnt(0)
	v_fmamk_f32 v144, v200, 0x39800000, v246
	v_cndmask_b32_e32 v146, v146, v147, vcc
	v_rsq_f32_e32 v146, v146
	v_mul_f32_e32 v145, 0x4b800000, v144
	v_mul_f32_e32 v147, 0x45800000, v146
	v_cndmask_b32_e32 v146, v146, v147, vcc
	v_cmp_gt_f32_e32 vcc, s95, v144
	v_pk_mul_f32 v[104:105], v[104:105], v[146:147] op_sel_hi:[1,0]
	v_pk_mul_f32 v[102:103], v[102:103], v[146:147] op_sel_hi:[1,0]
	v_cndmask_b32_e32 v144, v144, v145, vcc
	v_rsq_f32_e32 v144, v144
	v_pk_mul_f32 v[108:109], v[108:109], v[146:147] op_sel_hi:[1,0]
	v_pk_mul_f32 v[106:107], v[106:107], v[146:147] op_sel_hi:[1,0]
	v_pk_mul_f32 v[112:113], v[112:113], v[146:147] op_sel_hi:[1,0]
	v_mul_f32_e32 v145, 0x45800000, v144
	v_cndmask_b32_e32 v144, v144, v145, vcc
	v_pk_mul_f32 v[110:111], v[110:111], v[146:147] op_sel_hi:[1,0]
	v_pk_mul_f32 v[116:117], v[116:117], v[146:147] op_sel_hi:[1,0]
	v_pk_mul_f32 v[114:115], v[114:115], v[146:147] op_sel_hi:[1,0]
	v_pk_mul_f32 v[132:133], v[132:133], v[144:145] op_sel_hi:[1,0]
	v_pk_mul_f32 v[130:131], v[130:131], v[144:145] op_sel_hi:[1,0]
	v_pk_mul_f32 v[128:129], v[128:129], v[144:145] op_sel_hi:[1,0]
	v_pk_mul_f32 v[126:127], v[126:127], v[144:145] op_sel_hi:[1,0]
	v_pk_mul_f32 v[124:125], v[124:125], v[144:145] op_sel_hi:[1,0]
	v_pk_mul_f32 v[122:123], v[122:123], v[144:145] op_sel_hi:[1,0]
	v_pk_mul_f32 v[120:121], v[120:121], v[144:145] op_sel_hi:[1,0]
	v_pk_mul_f32 v[118:119], v[118:119], v[144:145] op_sel_hi:[1,0]
	s_cbranch_scc1 .LBB0_254
	v_mul_f32_e32 v145, 0xbfb8aa3b, v7
	v_mul_f32_e32 v146, 0xbfb8aa3b, v8
	v_exp_f32_e32 v145, v145
	v_exp_f32_e32 v146, v146
	v_mul_f32_e32 v144, 0xbfb8aa3b, v6
	v_exp_f32_e32 v144, v144
	v_add_f32_e32 v145, 1.0, v145
	v_add_f32_e32 v146, 1.0, v146
	v_rcp_f32_e32 v145, v145
	v_rcp_f32_e32 v149, v146
	v_add_f32_e32 v144, 1.0, v144
	v_mul_f32_e32 v146, 0xbfb8aa3b, v9
	v_mul_f32_e32 v147, v7, v145
	v_mul_f32_e32 v195, v8, v149
	v_mul_f32_e32 v145, 0xbfb8aa3b, v10
	v_mul_f32_e32 v149, 0xbfb8aa3b, v11
	v_rcp_f32_e32 v144, v144
	v_exp_f32_e32 v150, v146
	v_exp_f32_e32 v145, v145
	v_exp_f32_e32 v149, v149
	v_mul_f32_e32 v146, v6, v144
	v_add_f32_e32 v144, 1.0, v150
	v_add_f32_e32 v145, 1.0, v145
	v_add_f32_e32 v149, 1.0, v149
	v_mul_f32_e32 v150, 0xbfb8aa3b, v12
	v_rcp_f32_e32 v144, v144
	v_rcp_f32_e32 v145, v145
	v_rcp_f32_e32 v149, v149
	v_exp_f32_e32 v150, v150
	v_mul_f32_e32 v209, v9, v144
	v_mul_f32_e32 v144, v10, v145
	v_mul_f32_e32 v145, v11, v149
	v_add_f32_e32 v149, 1.0, v150
	v_mul_f32_e32 v150, 0xbfb8aa3b, v13
	v_exp_f32_e32 v150, v150
	v_mul_f32_e32 v151, 0xbfb8aa3b, v14
	v_exp_f32_e32 v151, v151
	v_mul_f32_e32 v240, 0xbfb8aa3b, v99
	v_add_f32_e32 v150, 1.0, v150
	v_rcp_f32_e32 v150, v150
	v_add_f32_e32 v151, 1.0, v151
	v_rcp_f32_e32 v151, v151
	v_exp_f32_e32 v240, v240
	v_mul_f32_e32 v206, v13, v150
	v_mul_f32_e32 v150, 0xbfb8aa3b, v16
	v_mul_f32_e32 v194, v14, v151
	v_exp_f32_e32 v150, v150
	v_mul_f32_e32 v151, 0xbfb8aa3b, v17
	v_exp_f32_e32 v151, v151
	v_mul_f32_e32 v152, 0xbfb8aa3b, v15
	v_rcp_f32_e32 v149, v149
	v_exp_f32_e32 v152, v152
	v_add_f32_e32 v150, 1.0, v150
	v_rcp_f32_e32 v150, v150
	v_add_f32_e32 v151, 1.0, v151
	v_add_f32_e32 v242, 1.0, v240
	v_cvt_pk_bf16_f32 v240, v146, v147
	v_mul_f32_e32 v146, 0xbfb8aa3b, v100
	v_rcp_f32_e32 v151, v151
	v_exp_f32_e32 v146, v146
	v_mul_f32_e32 v147, 0xbfb8aa3b, v101
	v_exp_f32_e32 v147, v147
	v_mul_f32_e32 v205, v12, v149
	v_add_f32_e32 v149, 1.0, v152
	v_mul_f32_e32 v152, 0xbfb8aa3b, v18
	s_lshl_b32 s1, s22, 8
	v_rcp_f32_e32 v149, v149
	v_exp_f32_e32 v152, v152
	v_mul_f32_e32 v203, v16, v150
	v_mul_f32_e32 v150, 0xbfb8aa3b, v19
	v_cvt_pk_bf16_f32 v241, v195, v209
	v_rcp_f32_e32 v195, v242
	s_addk_i32 s1, 0xf800
	v_cvt_pk_bf16_f32 v242, v144, v145
	v_cvt_pk_bf16_f32 v243, v205, v206
	v_mul_f32_e32 v205, 0xbfb8aa3b, v102
	v_mul_f32_e32 v204, v17, v151
	v_exp_f32_e32 v150, v150
	v_mul_f32_e32 v151, 0xbfb8aa3b, v20
	v_add_f32_e32 v146, 1.0, v146
	v_or_b32_e32 v144, s1, v148
	v_mov_b32_e32 v145, v4
	v_exp_f32_e32 v205, v205
	v_exp_f32_e32 v151, v151
	v_rcp_f32_e32 v209, v146
	v_add_f32_e32 v146, 1.0, v147
	v_lshl_add_u64 v[144:145], v[144:145], 1, s[24:25]
	s_mov_b64 s[26:27], 0x1b480000
	v_rcp_f32_e32 v244, v146
	v_lshl_add_u64 v[146:147], v[144:145], 0, s[26:27]
	v_lshlrev_b64 v[144:145], 13, v[140:141]
	v_mul_f32_e32 v202, v15, v149
	v_add_f32_e32 v149, 1.0, v152
	v_lshl_add_u64 v[144:145], v[146:147], 0, v[144:145]
	v_rcp_f32_e32 v149, v149
	v_add_f32_e32 v150, 1.0, v150
	global_store_dwordx4 v[144:145], v[240:243], off nt
	v_add_f32_e32 v205, 1.0, v205
	v_rcp_f32_e32 v150, v150
	v_mul_f32_e32 v240, 0xbfb8aa3b, v103
	v_add_f32_e32 v151, 1.0, v151
	v_exp_f32_e32 v240, v240
	v_cvt_pk_bf16_f32 v202, v194, v202
	v_cvt_pk_bf16_f32 v203, v203, v204
	v_rcp_f32_e32 v204, v205
	v_rcp_f32_e32 v151, v151
	v_mul_f32_e32 v152, 0xbfb8aa3b, v21
	v_mul_f32_e32 v200, v18, v149
	v_exp_f32_e32 v152, v152
	v_mul_f32_e32 v201, v19, v150
	v_add_f32_e32 v205, 1.0, v240
	v_mul_f32_e32 v240, 0xbfb8aa3b, v105
	v_mul_f32_e32 v241, v102, v204
	v_cvt_pk_bf16_f32 v204, v200, v201
	v_mul_f32_e32 v200, 0xbfb8aa3b, v106
	v_mul_f32_e32 v192, v20, v151
	v_mul_f32_e32 v151, 0xbfb8aa3b, v23
	v_rcp_f32_e32 v205, v205
	v_exp_f32_e32 v240, v240
	v_exp_f32_e32 v200, v200
	v_exp_f32_e32 v151, v151
	v_mul_f32_e32 v150, 0xbfb8aa3b, v22
	v_add_f32_e32 v149, 1.0, v152
	v_exp_f32_e32 v150, v150
	v_rcp_f32_e32 v149, v149
	v_mul_f32_e32 v242, v103, v205
	v_add_f32_e32 v205, 1.0, v240
	v_mul_f32_e32 v201, 0xbfb8aa3b, v107
	v_add_f32_e32 v200, 1.0, v200
	v_add_f32_e32 v151, 1.0, v151
	v_exp_f32_e32 v201, v201
	v_rcp_f32_e32 v240, v205
	v_rcp_f32_e32 v200, v200
	v_rcp_f32_e32 v151, v151
	v_add_f32_e32 v150, 1.0, v150
	v_rcp_f32_e32 v150, v150
	v_mul_f32_e32 v197, v21, v149
	v_mul_f32_e32 v152, 0xbfb8aa3b, v24
	v_add_f32_e32 v201, 1.0, v201
	v_cvt_pk_bf16_f32 v205, v192, v197
	v_mul_f32_e32 v197, v105, v240
	v_mul_f32_e32 v240, v106, v200
	v_mul_f32_e32 v200, 0xbfb8aa3b, v109
	v_exp_f32_e32 v152, v152
	v_mul_f32_e32 v181, v23, v151
	v_mul_f32_e32 v151, 0xbfb8aa3b, v26
	v_rcp_f32_e32 v201, v201
	v_exp_f32_e32 v200, v200
	v_exp_f32_e32 v151, v151
	v_mul_f32_e32 v179, v22, v150
	v_mul_f32_e32 v150, 0xbfb8aa3b, v25
	v_exp_f32_e32 v150, v150
	v_add_f32_e32 v149, 1.0, v152
	v_mul_f32_e32 v152, 0xbfb8aa3b, v27
	v_mul_f32_e32 v243, v107, v201
	v_mul_f32_e32 v201, 0xbfb8aa3b, v110
	v_add_f32_e32 v200, 1.0, v200
	v_rcp_f32_e32 v149, v149
	v_add_f32_e32 v151, 1.0, v151
	v_exp_f32_e32 v152, v152
	v_exp_f32_e32 v201, v201
	v_rcp_f32_e32 v200, v200
	v_rcp_f32_e32 v151, v151
	v_add_f32_e32 v150, 1.0, v150
	v_rcp_f32_e32 v150, v150
	global_store_dwordx4 v[144:145], v[202:205], off offset:256 nt
	v_mul_f32_e32 v188, v24, v149
	v_add_f32_e32 v149, 1.0, v152
	v_mul_f32_e32 v202, 0xbfb8aa3b, v111
	v_add_f32_e32 v201, 1.0, v201
	v_exp_f32_e32 v202, v202
	v_mul_f32_e32 v204, v109, v200
	v_cvt_pk_bf16_f32 v200, v179, v181
	v_mul_f32_e32 v181, 0xbfb8aa3b, v113
	v_mul_f32_e32 v178, v26, v151
	v_mul_f32_e32 v151, 0xbfb8aa3b, v29
	v_rcp_f32_e32 v149, v149
	v_rcp_f32_e32 v201, v201
	v_exp_f32_e32 v181, v181
	v_exp_f32_e32 v151, v151
	v_mul_f32_e32 v179, 0xbfb8aa3b, v112
	v_mul_f32_e32 v189, v25, v150
	v_mul_f32_e32 v150, 0xbfb8aa3b, v28
	v_exp_f32_e32 v179, v179
	v_exp_f32_e32 v150, v150
	v_add_f32_e32 v202, 1.0, v202
	v_mul_f32_e32 v187, v27, v149
	v_mul_f32_e32 v205, v110, v201
	v_cvt_pk_bf16_f32 v201, v188, v189
	v_rcp_f32_e32 v188, v202
	v_add_f32_e32 v181, 1.0, v181
	v_cvt_pk_bf16_f32 v202, v178, v187
	v_mul_f32_e32 v178, 0xbfb8aa3b, v114
	v_add_f32_e32 v151, 1.0, v151
	v_rcp_f32_e32 v181, v181
	v_exp_f32_e32 v178, v178
	v_rcp_f32_e32 v151, v151
	v_add_f32_e32 v179, 1.0, v179
	v_add_f32_e32 v150, 1.0, v150
	v_rcp_f32_e32 v179, v179
	v_rcp_f32_e32 v150, v150
	v_mul_f32_e32 v245, v113, v181
	v_add_f32_e32 v181, 1.0, v178
	v_mul_f32_e32 v178, 0xbfb8aa3b, v115
	v_mul_f32_e32 v182, v29, v151
	v_mul_f32_e32 v151, 0xbfb8aa3b, v32
	v_exp_f32_e32 v248, v178
	v_or_b32_e32 v178, 16, v140
	v_exp_f32_e32 v151, v151
	v_mul_f32_e32 v206, v100, v209
	v_mul_f32_e32 v209, v101, v244
	v_mul_f32_e32 v244, v112, v179
	v_ashrrev_i32_e32 v179, 31, v178
	v_mul_f32_e32 v152, 0xbfb8aa3b, v30
	v_mul_f32_e32 v180, v28, v150
	v_mul_f32_e32 v150, 0xbfb8aa3b, v31
	v_lshlrev_b64 v[178:179], 13, v[178:179]
	v_exp_f32_e32 v152, v152
	v_exp_f32_e32 v150, v150
	v_mul_f32_e32 v187, v111, v188
	v_lshl_add_u64 v[188:189], v[146:147], 0, v[178:179]
	v_mul_f32_e32 v178, 0xbfb8aa3b, v116
	v_exp_f32_e32 v178, v178
	v_add_f32_e32 v151, 1.0, v151
	v_rcp_f32_e32 v151, v151
	v_add_f32_e32 v149, 1.0, v152
	v_add_f32_e32 v150, 1.0, v150
	v_rcp_f32_e32 v149, v149
	v_rcp_f32_e32 v150, v150
	v_add_f32_e32 v178, 1.0, v178
	v_rcp_f32_e32 v178, v178
	v_mul_f32_e32 v173, v32, v151
	v_mul_f32_e32 v151, 0xbfb8aa3b, v35
	v_exp_f32_e32 v151, v151
	v_mul_f32_e32 v152, 0xbfb8aa3b, v33
	v_mul_f32_e32 v170, v30, v149
	v_mul_f32_e32 v172, v31, v150
	v_mul_f32_e32 v150, 0xbfb8aa3b, v34
	v_exp_f32_e32 v152, v152
	v_exp_f32_e32 v150, v150
	v_cvt_pk_bf16_f32 v203, v180, v182
	global_store_dwordx4 v[188:189], v[200:203], off nt
	v_add_f32_e32 v151, 1.0, v151
	v_rcp_f32_e32 v151, v151
	v_mul_f32_e32 v201, v116, v178
	v_cvt_pk_bf16_f32 v178, v170, v172
	v_mul_f32_e32 v170, 0xbfb8aa3b, v130
	v_exp_f32_e32 v170, v170
	v_add_f32_e32 v149, 1.0, v152
	v_add_f32_e32 v150, 1.0, v150
	v_rcp_f32_e32 v149, v149
	v_rcp_f32_e32 v150, v150
	v_add_f32_e32 v170, 1.0, v170
	v_rcp_f32_e32 v179, v181
	v_rcp_f32_e32 v170, v170
	v_mul_f32_e32 v152, 0xbfb8aa3b, v36
	v_mul_f32_e32 v169, v35, v151
	v_mul_f32_e32 v151, 0xbfb8aa3b, v38
	v_exp_f32_e32 v152, v152
	v_exp_f32_e32 v151, v151
	v_add_f32_e32 v180, 1.0, v248
	v_mul_f32_e32 v181, 0xbfb8aa3b, v117
	v_mul_f32_e32 v183, v33, v149
	v_mul_f32_e32 v168, v34, v150
	v_mul_f32_e32 v150, 0xbfb8aa3b, v37
	v_rcp_f32_e32 v180, v180
	v_exp_f32_e32 v181, v181
	v_exp_f32_e32 v150, v150
	v_mul_f32_e32 v182, v114, v179
	v_cvt_pk_bf16_f32 v179, v173, v183
	v_mul_f32_e32 v183, v130, v170
	v_mul_f32_e32 v170, 0xbfb8aa3b, v126
	v_exp_f32_e32 v170, v170
	v_add_f32_e32 v149, 1.0, v152
	v_add_f32_e32 v151, 1.0, v151
	v_rcp_f32_e32 v149, v149
	v_rcp_f32_e32 v151, v151
	v_mul_f32_e32 v200, v115, v180
	v_add_f32_e32 v180, 1.0, v181
	v_add_f32_e32 v150, 1.0, v150
	v_rcp_f32_e32 v173, v180
	v_cvt_pk_bf16_f32 v180, v168, v169
	v_mul_f32_e32 v168, 0xbfb8aa3b, v132
	v_mul_f32_e32 v169, 0xbfb8aa3b, v133
	v_rcp_f32_e32 v150, v150
	v_exp_f32_e32 v168, v168
	v_exp_f32_e32 v169, v169
	v_add_f32_e32 v170, 1.0, v170
	v_rcp_f32_e32 v170, v170
	v_mul_f32_e32 v171, v36, v149
	v_mul_f32_e32 v149, v38, v151
	v_mul_f32_e32 v151, 0xbfb8aa3b, v40
	v_mul_f32_e32 v152, 0xbfb8aa3b, v39
	v_exp_f32_e32 v151, v151
	v_exp_f32_e32 v152, v152
	v_mul_f32_e32 v174, v37, v150
	v_add_f32_e32 v168, 1.0, v168
	v_cvt_pk_bf16_f32 v181, v171, v174
	v_add_f32_e32 v169, 1.0, v169
	v_mul_f32_e32 v171, 0xbfb8aa3b, v127
	v_rcp_f32_e32 v168, v168
	v_rcp_f32_e32 v169, v169
	v_exp_f32_e32 v171, v171
	v_mul_f32_e32 v203, v126, v170
	v_mul_f32_e32 v170, 0xbfb8aa3b, v129
	v_exp_f32_e32 v170, v170
	v_add_f32_e32 v151, 1.0, v151
	v_add_f32_e32 v150, 1.0, v152
	v_mul_f32_e32 v152, 0xbfb8aa3b, v41
	v_rcp_f32_e32 v151, v151
	v_exp_f32_e32 v152, v152
	v_mul_f32_e32 v174, v132, v168
	v_mul_f32_e32 v202, v133, v169
	v_add_f32_e32 v168, 1.0, v171
	v_mul_f32_e32 v169, 0xbfb8aa3b, v128
	v_exp_f32_e32 v169, v169
	v_rcp_f32_e32 v168, v168
	v_add_f32_e32 v170, 1.0, v170
	v_mul_f32_e32 v171, 0xbfb8aa3b, v122
	v_rcp_f32_e32 v170, v170
	v_exp_f32_e32 v171, v171
	v_mul_f32_e32 v153, 0xbfb8aa3b, v42
	v_mul_f32_e32 v154, v40, v151
	v_mul_f32_e32 v151, 0xbfb8aa3b, v43
	v_rcp_f32_e32 v150, v150
	v_add_f32_e32 v152, 1.0, v152
	v_exp_f32_e32 v156, v153
	v_exp_f32_e32 v151, v151
	v_rcp_f32_e32 v152, v152
	global_store_dwordx4 v[188:189], v[178:181], off offset:256 nt
	v_add_f32_e32 v169, 1.0, v169
	v_rcp_f32_e32 v169, v169
	v_mul_f32_e32 v178, v127, v168
	v_mul_f32_e32 v168, 0xbfb8aa3b, v123
	v_mul_f32_e32 v180, v129, v170
	v_add_f32_e32 v170, 1.0, v171
	v_exp_f32_e32 v171, v168
	v_mul_f32_e32 v153, v39, v150
	v_add_f32_e32 v150, 1.0, v156
	v_add_f32_e32 v151, 1.0, v151
	v_mul_f32_e32 v156, 0xbfb8aa3b, v45
	v_mul_f32_e32 v155, v41, v152
	v_mul_f32_e32 v152, 0xbfb8aa3b, v44
	v_rcp_f32_e32 v150, v150
	v_rcp_f32_e32 v151, v151
	v_exp_f32_e32 v158, v156
	v_exp_f32_e32 v152, v152
	v_mul_f32_e32 v179, v128, v169
	v_cvt_pk_bf16_f32 v168, v149, v153
	v_cvt_pk_bf16_f32 v169, v154, v155
	v_add_f32_e32 v154, 1.0, v171
	v_mul_f32_e32 v155, 0xbfb8aa3b, v125
	v_rcp_f32_e32 v153, v170
	v_rcp_f32_e32 v154, v154
	v_exp_f32_e32 v155, v155
	v_mul_f32_e32 v156, v42, v150
	v_mul_f32_e32 v157, v43, v151
	v_add_f32_e32 v150, 1.0, v158
	v_mul_f32_e32 v151, 0xbfb8aa3b, v46
	v_mul_f32_e32 v158, 0xbfb8aa3b, v47
	v_add_f32_e32 v152, 1.0, v152
	v_exp_f32_e32 v151, v151
	v_exp_f32_e32 v158, v158
	v_rcp_f32_e32 v152, v152
	v_mul_f32_e32 v185, 0xbfb8aa3b, v61
	v_mul_f32_e32 v181, v122, v153
	v_mul_f32_e32 v188, v123, v154
	v_add_f32_e32 v153, 1.0, v155
	v_mul_f32_e32 v154, 0xbfb8aa3b, v118
	v_rcp_f32_e32 v150, v150
	v_exp_f32_e32 v185, v185
	v_mul_f32_e32 v186, 0xbfb8aa3b, v62
	v_rcp_f32_e32 v153, v153
	v_exp_f32_e32 v154, v154
	v_mul_f32_e32 v184, 0xbfb8aa3b, v60
	v_exp_f32_e32 v186, v186
	v_add_f32_e32 v151, 1.0, v151
	v_add_f32_e32 v158, 1.0, v158
	v_mul_f32_e32 v159, 0xbfb8aa3b, v48
	v_exp_f32_e32 v184, v184
	v_mul_f32_e32 v210, 0xbfb8aa3b, v71
	v_mul_f32_e32 v155, 0xbfb8aa3b, v119
	v_mul_f32_e32 v152, v44, v152
	v_rcp_f32_e32 v151, v151
	v_rcp_f32_e32 v158, v158
	v_exp_f32_e32 v159, v159
	v_mul_f32_e32 v207, 0xbfb8aa3b, v69
	v_mul_f32_e32 v208, 0xbfb8aa3b, v70
	v_exp_f32_e32 v210, v210
	v_mul_f32_e32 v226, 0xbfb8aa3b, v85
	v_exp_f32_e32 v155, v155
	v_mul_f32_e32 v161, v45, v150
	v_add_f32_e32 v185, 1.0, v185
	v_exp_f32_e32 v207, v207
	v_exp_f32_e32 v208, v208
	v_exp_f32_e32 v226, v226
	v_mul_f32_e32 v227, 0xbfb8aa3b, v86
	v_cvt_pk_bf16_f32 v170, v156, v157
	v_mul_f32_e32 v156, v125, v153
	v_add_f32_e32 v153, 1.0, v154
	v_cvt_pk_bf16_f32 v171, v152, v161
	v_or_b32_e32 v152, 32, v140
	v_rcp_f32_e32 v190, v185
	v_add_f32_e32 v185, 1.0, v186
	v_mul_f32_e32 v225, 0xbfb8aa3b, v84
	v_exp_f32_e32 v227, v227
	v_mul_f32_e32 v236, 0xbfb8aa3b, v95
	v_rcp_f32_e32 v157, v153
	v_ashrrev_i32_e32 v153, 31, v152
	v_add_f32_e32 v184, 1.0, v184
	v_rcp_f32_e32 v191, v185
	v_mul_f32_e32 v185, 0xbfb8aa3b, v63
	v_exp_f32_e32 v225, v225
	v_mul_f32_e32 v234, 0xbfb8aa3b, v93
	v_mul_f32_e32 v235, 0xbfb8aa3b, v94
	v_exp_f32_e32 v236, v236
	v_lshlrev_b64 v[152:153], 13, v[152:153]
	v_mul_f32_e32 v150, v46, v151
	v_mul_f32_e32 v151, v47, v158
	v_add_f32_e32 v158, 1.0, v159
	v_mul_f32_e32 v159, 0xbfb8aa3b, v49
	v_mul_f32_e32 v160, 0xbfb8aa3b, v50
	v_mul_f32_e32 v162, 0xbfb8aa3b, v51
	v_mul_f32_e32 v163, 0xbfb8aa3b, v52
	v_mul_f32_e32 v164, 0xbfb8aa3b, v53
	v_rcp_f32_e32 v184, v184
	v_exp_f32_e32 v193, v185
	v_add_f32_e32 v210, 1.0, v210
	v_exp_f32_e32 v234, v234
	v_exp_f32_e32 v235, v235
	v_add_f32_e32 v189, 1.0, v155
	v_lshl_add_u64 v[154:155], v[146:147], 0, v[152:153]
	v_mul_f32_e32 v152, 0xbfb8aa3b, v120
	v_mul_f32_e32 v153, 0xbfb8aa3b, v121
	v_exp_f32_e32 v159, v159
	v_exp_f32_e32 v160, v160
	v_exp_f32_e32 v162, v162
	v_exp_f32_e32 v163, v163
	v_exp_f32_e32 v164, v164
	v_add_f32_e32 v207, 1.0, v207
	v_add_f32_e32 v208, 1.0, v208
	v_rcp_f32_e32 v211, v210
	v_mul_f32_e32 v210, 0xbfb8aa3b, v72
	v_add_f32_e32 v226, 1.0, v226
	v_exp_f32_e32 v152, v152
	v_exp_f32_e32 v153, v153
	v_rcp_f32_e32 v207, v207
	v_rcp_f32_e32 v208, v208
	v_exp_f32_e32 v212, v210
	v_rcp_f32_e32 v228, v226
	v_add_f32_e32 v226, 1.0, v227
	v_mul_f32_e32 v165, 0xbfb8aa3b, v54
	v_mul_f32_e32 v166, 0xbfb8aa3b, v55
	v_mul_f32_e32 v167, 0xbfb8aa3b, v56
	v_mul_f32_e32 v175, 0xbfb8aa3b, v57
	v_add_f32_e32 v225, 1.0, v225
	v_rcp_f32_e32 v229, v226
	v_mul_f32_e32 v226, 0xbfb8aa3b, v87
	v_add_f32_e32 v236, 1.0, v236
	v_exp_f32_e32 v165, v165
	v_exp_f32_e32 v166, v166
	v_exp_f32_e32 v167, v167
	v_exp_f32_e32 v175, v175
	v_mul_f32_e32 v176, 0xbfb8aa3b, v58
	v_mul_f32_e32 v177, 0xbfb8aa3b, v59
	v_mul_f32_e32 v185, v60, v184
	v_mul_f32_e32 v186, v61, v190
	v_mul_f32_e32 v184, v62, v191
	v_add_f32_e32 v190, 1.0, v193
	v_mul_f32_e32 v191, 0xbfb8aa3b, v64
	v_mul_f32_e32 v193, 0xbfb8aa3b, v65
	v_rcp_f32_e32 v225, v225
	v_exp_f32_e32 v230, v226
	v_add_f32_e32 v234, 1.0, v234
	v_add_f32_e32 v235, 1.0, v235
	v_rcp_f32_e32 v237, v236
	v_mul_f32_e32 v236, 0xbfb8aa3b, v96
	v_add_f32_e32 v159, 1.0, v159
	v_add_f32_e32 v160, 1.0, v160
	v_add_f32_e32 v162, 1.0, v162
	v_add_f32_e32 v163, 1.0, v163
	v_add_f32_e32 v164, 1.0, v164
	v_exp_f32_e32 v176, v176
	v_exp_f32_e32 v177, v177
	v_exp_f32_e32 v191, v191
	v_exp_f32_e32 v193, v193
	v_mul_f32_e32 v196, 0xbfb8aa3b, v66
	v_mul_f32_e32 v198, 0xbfb8aa3b, v67
	v_mul_f32_e32 v199, 0xbfb8aa3b, v68
	v_rcp_f32_e32 v234, v234
	v_rcp_f32_e32 v235, v235
	v_exp_f32_e32 v238, v236
	v_add_f32_e32 v152, 1.0, v152
	v_add_f32_e32 v153, 1.0, v153
	v_rcp_f32_e32 v158, v158
	v_rcp_f32_e32 v159, v159
	v_rcp_f32_e32 v160, v160
	v_rcp_f32_e32 v162, v162
	v_rcp_f32_e32 v163, v163
	v_rcp_f32_e32 v164, v164
	v_exp_f32_e32 v196, v196
	v_exp_f32_e32 v198, v198
	v_exp_f32_e32 v199, v199
	v_mul_f32_e32 v210, v69, v207
	v_mul_f32_e32 v207, v70, v208
	v_mul_f32_e32 v208, v71, v211
	v_add_f32_e32 v211, 1.0, v212
	v_mul_f32_e32 v212, 0xbfb8aa3b, v73
	v_mul_f32_e32 v213, 0xbfb8aa3b, v74
	v_mul_f32_e32 v216, 0xbfb8aa3b, v75
	v_mul_f32_e32 v217, 0xbfb8aa3b, v76
	v_mul_f32_e32 v218, 0xbfb8aa3b, v77
	v_rcp_f32_e32 v152, v152
	v_rcp_f32_e32 v153, v153
	v_exp_f32_e32 v212, v212
	v_exp_f32_e32 v213, v213
	v_exp_f32_e32 v216, v216
	v_exp_f32_e32 v217, v217
	v_exp_f32_e32 v218, v218
	v_mul_f32_e32 v219, 0xbfb8aa3b, v78
	v_mul_f32_e32 v220, 0xbfb8aa3b, v79
	v_mul_f32_e32 v221, 0xbfb8aa3b, v80
	v_mul_f32_e32 v222, 0xbfb8aa3b, v81
	v_mul_f32_e32 v223, 0xbfb8aa3b, v82
	v_mul_f32_e32 v224, 0xbfb8aa3b, v83
	v_add_f32_e32 v165, 1.0, v165
	v_add_f32_e32 v166, 1.0, v166
	v_add_f32_e32 v167, 1.0, v167
	v_add_f32_e32 v175, 1.0, v175
	v_exp_f32_e32 v219, v219
	v_exp_f32_e32 v220, v220
	v_exp_f32_e32 v221, v221
	v_exp_f32_e32 v222, v222
	v_exp_f32_e32 v223, v223
	v_exp_f32_e32 v224, v224
	v_mul_f32_e32 v226, v84, v225
	v_mul_f32_e32 v227, v85, v228
	v_mul_f32_e32 v225, v86, v229
	v_add_f32_e32 v228, 1.0, v230
	v_mul_f32_e32 v229, 0xbfb8aa3b, v88
	v_mul_f32_e32 v230, 0xbfb8aa3b, v89
	v_mul_f32_e32 v231, 0xbfb8aa3b, v90
	v_mul_f32_e32 v232, 0xbfb8aa3b, v91
	v_mul_f32_e32 v233, 0xbfb8aa3b, v92
	v_rcp_f32_e32 v165, v165
	v_rcp_f32_e32 v166, v166
	v_rcp_f32_e32 v167, v167
	v_rcp_f32_e32 v175, v175
	v_add_f32_e32 v176, 1.0, v176
	v_add_f32_e32 v177, 1.0, v177
	v_add_f32_e32 v191, 1.0, v191
	v_add_f32_e32 v193, 1.0, v193
	v_exp_f32_e32 v229, v229
	v_exp_f32_e32 v230, v230
	v_exp_f32_e32 v231, v231
	v_exp_f32_e32 v232, v232
	v_exp_f32_e32 v233, v233
	v_mul_f32_e32 v236, v93, v234
	v_mul_f32_e32 v234, v94, v235
	v_mul_f32_e32 v235, v95, v237
	v_add_f32_e32 v237, 1.0, v238
	v_mul_f32_e32 v238, 0xbfb8aa3b, v97
	v_mul_f32_e32 v239, 0xbfb8aa3b, v98
	global_store_dwordx4 v[154:155], v[168:171], off nt
	v_cvt_pk_bf16_f32 v150, v150, v151
	v_mul_f32_e32 v158, v48, v158
	v_mul_f32_e32 v159, v49, v159
	v_mul_f32_e32 v160, v50, v160
	v_mul_f32_e32 v162, v51, v162
	v_mul_f32_e32 v163, v52, v163
	v_mul_f32_e32 v164, v53, v164
	v_rcp_f32_e32 v176, v176
	v_rcp_f32_e32 v177, v177
	v_rcp_f32_e32 v190, v190
	v_rcp_f32_e32 v191, v191
	v_rcp_f32_e32 v193, v193
	v_add_f32_e32 v196, 1.0, v196
	v_add_f32_e32 v198, 1.0, v198
	v_add_f32_e32 v199, 1.0, v199
	v_exp_f32_e32 v238, v238
	v_exp_f32_e32 v239, v239
	v_mul_f32_e32 v194, 0xbfb8aa3b, v104
	v_mul_f32_e32 v192, 0xbfb8aa3b, v108
	v_mul_f32_e32 v168, v120, v152
	v_mul_f32_e32 v169, v121, v153
	v_cvt_pk_bf16_f32 v151, v158, v159
	v_cvt_pk_bf16_f32 v152, v160, v162
	v_cvt_pk_bf16_f32 v153, v163, v164
	global_store_dwordx4 v[154:155], v[150:153], off offset:256 nt
	v_rcp_f32_e32 v196, v196
	v_rcp_f32_e32 v198, v198
	v_or_b32_e32 v150, 48, v140
	v_rcp_f32_e32 v199, v199
	v_add_f32_e32 v212, 1.0, v212
	v_add_f32_e32 v213, 1.0, v213
	v_add_f32_e32 v216, 1.0, v216
	v_add_f32_e32 v217, 1.0, v217
	v_add_f32_e32 v218, 1.0, v218
	v_exp_f32_e32 v194, v194
	v_exp_f32_e32 v192, v192
	v_ashrrev_i32_e32 v151, 31, v150
	v_rcp_f32_e32 v211, v211
	v_rcp_f32_e32 v212, v212
	v_rcp_f32_e32 v213, v213
	v_rcp_f32_e32 v216, v216
	v_rcp_f32_e32 v217, v217
	v_rcp_f32_e32 v218, v218
	v_add_f32_e32 v219, 1.0, v219
	v_add_f32_e32 v220, 1.0, v220
	v_add_f32_e32 v221, 1.0, v221
	v_add_f32_e32 v222, 1.0, v222
	v_add_f32_e32 v223, 1.0, v223
	v_add_f32_e32 v224, 1.0, v224
	v_mul_f32_e32 v172, 0xbfb8aa3b, v131
	v_mul_f32_e32 v149, 0xbfb8aa3b, v124
	v_lshlrev_b64 v[150:151], 13, v[150:151]
	v_mul_f32_e32 v165, v54, v165
	v_mul_f32_e32 v166, v55, v166
	v_mul_f32_e32 v167, v56, v167
	v_mul_f32_e32 v175, v57, v175
	v_rcp_f32_e32 v219, v219
	v_rcp_f32_e32 v220, v220
	v_rcp_f32_e32 v221, v221
	v_rcp_f32_e32 v222, v222
	v_rcp_f32_e32 v223, v223
	v_rcp_f32_e32 v224, v224
	v_add_f32_e32 v229, 1.0, v229
	v_add_f32_e32 v230, 1.0, v230
	v_add_f32_e32 v231, 1.0, v231
	v_add_f32_e32 v232, 1.0, v232
	v_add_f32_e32 v233, 1.0, v233
	v_exp_f32_e32 v172, v172
	v_exp_f32_e32 v149, v149
	v_lshl_add_u64 v[154:155], v[146:147], 0, v[150:151]
	v_cvt_pk_bf16_f32 v150, v165, v166
	v_cvt_pk_bf16_f32 v151, v167, v175
	v_mul_f32_e32 v176, v58, v176
	v_mul_f32_e32 v177, v59, v177
	v_mul_f32_e32 v190, v63, v190
	v_mul_f32_e32 v191, v64, v191
	v_mul_f32_e32 v193, v65, v193
	v_rcp_f32_e32 v228, v228
	v_rcp_f32_e32 v229, v229
	v_rcp_f32_e32 v230, v230
	v_rcp_f32_e32 v231, v231
	v_rcp_f32_e32 v232, v232
	v_rcp_f32_e32 v233, v233
	v_add_f32_e32 v238, 1.0, v238
	v_add_f32_e32 v239, 1.0, v239
	v_cvt_pk_bf16_f32 v152, v176, v177
	v_cvt_pk_bf16_f32 v153, v185, v186
	global_store_dwordx4 v[154:155], v[150:153], off nt
	v_mul_f32_e32 v196, v66, v196
	v_mul_f32_e32 v198, v67, v198
	v_cvt_pk_bf16_f32 v150, v184, v190
	v_cvt_pk_bf16_f32 v151, v191, v193
	v_mul_f32_e32 v199, v68, v199
	v_rcp_f32_e32 v237, v237
	v_rcp_f32_e32 v238, v238
	v_rcp_f32_e32 v239, v239
	v_add_f32_e32 v194, 1.0, v194
	v_add_f32_e32 v192, 1.0, v192
	v_cvt_pk_bf16_f32 v152, v196, v198
	v_cvt_pk_bf16_f32 v153, v199, v210
	global_store_dwordx4 v[154:155], v[150:153], off offset:256 nt
	v_mul_f32_e32 v211, v72, v211
	v_mul_f32_e32 v212, v73, v212
	v_lshlrev_b64 v[150:151], 13, v[142:143]
	v_mul_f32_e32 v213, v74, v213
	v_mul_f32_e32 v216, v75, v216
	v_mul_f32_e32 v217, v76, v217
	v_mul_f32_e32 v218, v77, v218
	v_rcp_f32_e32 v194, v194
	v_rcp_f32_e32 v192, v192
	v_lshl_add_u64 v[146:147], v[146:147], 0, v[150:151]
	v_cvt_pk_bf16_f32 v150, v207, v208
	v_cvt_pk_bf16_f32 v151, v211, v212
	v_cvt_pk_bf16_f32 v152, v213, v216
	v_cvt_pk_bf16_f32 v153, v217, v218
	v_add_co_u32_e32 v154, vcc, s72, v144
	v_mul_f32_e32 v219, v78, v219
	v_mul_f32_e32 v220, v79, v220
	v_mul_f32_e32 v221, v80, v221
	v_mul_f32_e32 v222, v81, v222
	v_mul_f32_e32 v223, v82, v223
	v_mul_f32_e32 v224, v83, v224
	v_add_f32_e32 v172, 1.0, v172
	v_add_f32_e32 v149, 1.0, v149
	global_store_dwordx4 v[146:147], v[150:153], off nt
	s_mov_b64 s[26:27], 0x120000
	v_addc_co_u32_e32 v155, vcc, 0, v145, vcc
	v_cvt_pk_bf16_f32 v150, v219, v220
	v_cvt_pk_bf16_f32 v151, v221, v222
	v_cvt_pk_bf16_f32 v152, v223, v224
	v_cvt_pk_bf16_f32 v153, v226, v227
	global_store_dwordx4 v[146:147], v[150:153], off offset:256 nt
	v_mul_f32_e32 v228, v87, v228
	v_mul_f32_e32 v229, v88, v229
	v_mul_f32_e32 v230, v89, v230
	v_mul_f32_e32 v231, v90, v231
	v_mul_f32_e32 v232, v91, v232
	v_mul_f32_e32 v233, v92, v233
	v_rcp_f32_e32 v172, v172
	v_rcp_f32_e32 v149, v149
	v_rcp_f32_e32 v161, v189
	v_lshl_add_u64 v[146:147], v[144:145], 0, s[26:27]
	v_cvt_pk_bf16_f32 v150, v225, v228
	v_cvt_pk_bf16_f32 v151, v229, v230
	v_cvt_pk_bf16_f32 v152, v231, v232
	v_cvt_pk_bf16_f32 v153, v233, v236
	global_store_dwordx4 v[154:155], v[150:153], off nt
	s_mov_b64 s[26:27], 0x140000
	v_add_co_u32_e32 v154, vcc, s73, v144
	v_mul_f32_e32 v237, v96, v237
	v_mul_f32_e32 v238, v97, v238
	v_mul_f32_e32 v239, v98, v239
	v_mul_f32_e32 v195, v99, v195
	v_cvt_pk_bf16_f32 v150, v234, v235
	v_cvt_pk_bf16_f32 v151, v237, v238
	v_cvt_pk_bf16_f32 v152, v239, v195
	v_cvt_pk_bf16_f32 v153, v206, v209
	global_store_dwordx4 v[146:147], v[150:153], off offset:256 nt
	v_lshl_add_u64 v[146:147], v[144:145], 0, s[26:27]
	v_addc_co_u32_e32 v155, vcc, 0, v145, vcc
	s_mov_b64 s[26:27], 0x160000
	v_mul_f32_e32 v194, v104, v194
	v_mul_f32_e32 v192, v108, v192
	v_cvt_pk_bf16_f32 v150, v241, v242
	v_cvt_pk_bf16_f32 v151, v194, v197
	v_cvt_pk_bf16_f32 v152, v240, v243
	v_cvt_pk_bf16_f32 v153, v192, v204
	global_store_dwordx4 v[154:155], v[150:153], off nt
	v_lshl_add_u64 v[154:155], v[144:145], 0, s[26:27]
	v_add_co_u32_e32 v144, vcc, 0x160000, v144
	v_mul_f32_e32 v173, v117, v173
	v_cvt_pk_bf16_f32 v150, v205, v187
	v_cvt_pk_bf16_f32 v151, v244, v245
	v_cvt_pk_bf16_f32 v152, v182, v200
	v_cvt_pk_bf16_f32 v153, v201, v173
	global_store_dwordx4 v[146:147], v[150:153], off offset:256 nt
	v_addc_co_u32_e32 v145, vcc, 0, v145, vcc
	v_mul_f32_e32 v172, v131, v172
	v_mul_f32_e32 v149, v124, v149
	v_mul_f32_e32 v157, v118, v157
	v_mul_f32_e32 v161, v119, v161
	v_cvt_pk_bf16_f32 v150, v183, v172
	v_cvt_pk_bf16_f32 v151, v174, v202
	v_cvt_pk_bf16_f32 v152, v203, v178
	v_cvt_pk_bf16_f32 v153, v179, v180
	global_store_dwordx4 v[144:145], v[150:153], off nt
	v_cvt_pk_bf16_f32 v144, v181, v188
	v_cvt_pk_bf16_f32 v145, v149, v156
	v_cvt_pk_bf16_f32 v146, v157, v161
	v_cvt_pk_bf16_f32 v147, v168, v169
	global_store_dwordx4 v[154:155], v[144:147], off offset:256 nt
	s_mov_b64 s[26:27], 0

.LBB0_346:
	s_add_u32 s54, s33, 0xffffff80
	s_addc_u32 s55, s52, -1
	s_cmp_eq_u32 s53, 60
	s_cselect_b32 s28, s2, s33
	s_cselect_b32 s29, s1, s52
	s_cselect_b32 s31, s11, s23
	s_cselect_b32 s30, s15, s19
	s_add_u32 s24, s28, 0x80
	s_addc_u32 s25, s29, 0
	s_add_u32 s26, s30, 0x80
	s_addc_u32 s27, s31, 0
	s_add_i32 s56, 0, 0x10000
	s_add_i32 s57, 0, 0x14000
	v_add_u32_e32 v152, s56, v1
	v_add_u32_e32 v168, s57, v1
	ds_read_b128 v[140:143], v152
	ds_read_b128 v[144:147], v152 offset:1024
	ds_read_b128 v[148:151], v152 offset:2048
	ds_read_b128 v[152:155], v152 offset:3072
	ds_read_b128 v[156:159], v168
	ds_read_b128 v[160:163], v168 offset:1024
	ds_read_b128 v[164:167], v168 offset:2048
	ds_read_b128 v[168:171], v168 offset:3072
	s_add_u32 s54, s54, 0x100000
	s_addc_u32 s55, s55, 0
	s_add_i32 m0, s41, 0xc000
	ds_read_b128 v[172:175], v5
	ds_read_b128 v[176:179], v5 offset:1024
	ds_read_b128 v[180:183], v5 offset:2048
	ds_read_b128 v[184:187], v5 offset:3072
	ds_read_b128 v[188:191], v5 offset:4096
	ds_read_b128 v[192:195], v5 offset:5120
	ds_read_b128 v[196:199], v5 offset:6144
	ds_read_b128 v[200:203], v5 offset:7168
	global_load_lds_dwordx4 v2, s[54:55]
	s_add_i32 m0, s41, 0xe000
	s_nop 0
	global_load_lds_dwordx4 v136, s[54:55]
	s_waitcnt vmcnt(8)
	s_waitcnt lgkmcnt(0)
	s_barrier
	s_setprio 1
	v_mfma_f32_16x16x32_bf16 v[130:133], v[140:143], v[172:175], v[130:133]
	v_mfma_f32_16x16x32_bf16 v[126:129], v[148:151], v[172:175], v[126:129]
	v_mfma_f32_16x16x32_bf16 v[114:117], v[140:143], v[180:183], v[114:117]
	v_mfma_f32_16x16x32_bf16 v[110:113], v[148:151], v[180:183], v[110:113]
	v_mfma_f32_16x16x32_bf16 v[98:101], v[140:143], v[188:191], v[98:101]
	v_mfma_f32_16x16x32_bf16 v[94:97], v[148:151], v[188:191], v[94:97]
	v_mfma_f32_16x16x32_bf16 v[82:85], v[140:143], v[196:199], v[82:85]
	v_mfma_f32_16x16x32_bf16 v[78:81], v[148:151], v[196:199], v[78:81]
	v_mfma_f32_16x16x32_bf16 v[130:133], v[144:147], v[176:179], v[130:133]
	v_mfma_f32_16x16x32_bf16 v[126:129], v[152:155], v[176:179], v[126:129]
	v_mfma_f32_16x16x32_bf16 v[114:117], v[144:147], v[184:187], v[114:117]
	v_mfma_f32_16x16x32_bf16 v[110:113], v[152:155], v[184:187], v[110:113]
	v_mfma_f32_16x16x32_bf16 v[98:101], v[144:147], v[192:195], v[98:101]
	v_mfma_f32_16x16x32_bf16 v[94:97], v[152:155], v[192:195], v[94:97]
	v_mfma_f32_16x16x32_bf16 v[82:85], v[144:147], v[200:203], v[82:85]
	v_mfma_f32_16x16x32_bf16 v[78:81], v[152:155], v[200:203], v[78:81]
	s_setprio 0
	s_setprio 1
	v_mfma_f32_16x16x32_bf16 v[122:125], v[156:159], v[172:175], v[122:125]
	v_mfma_f32_16x16x32_bf16 v[118:121], v[164:167], v[172:175], v[118:121]
	v_mfma_f32_16x16x32_bf16 v[106:109], v[156:159], v[180:183], v[106:109]
	v_mfma_f32_16x16x32_bf16 v[102:105], v[164:167], v[180:183], v[102:105]
	v_mfma_f32_16x16x32_bf16 v[90:93], v[156:159], v[188:191], v[90:93]
	v_mfma_f32_16x16x32_bf16 v[86:89], v[164:167], v[188:191], v[86:89]
	v_mfma_f32_16x16x32_bf16 v[74:77], v[156:159], v[196:199], v[74:77]
	v_mfma_f32_16x16x32_bf16 v[70:73], v[164:167], v[196:199], v[70:73]
	v_mfma_f32_16x16x32_bf16 v[122:125], v[160:163], v[176:179], v[122:125]
	v_mfma_f32_16x16x32_bf16 v[118:121], v[168:171], v[176:179], v[118:121]
	v_mfma_f32_16x16x32_bf16 v[106:109], v[160:163], v[184:187], v[106:109]
	v_mfma_f32_16x16x32_bf16 v[102:105], v[168:171], v[184:187], v[102:105]
	v_mfma_f32_16x16x32_bf16 v[90:93], v[160:163], v[192:195], v[90:93]
	v_mfma_f32_16x16x32_bf16 v[86:89], v[168:171], v[192:195], v[86:89]
	v_mfma_f32_16x16x32_bf16 v[74:77], v[160:163], v[200:203], v[74:77]
	v_mfma_f32_16x16x32_bf16 v[70:73], v[168:171], v[200:203], v[70:73]
	s_setprio 0
	s_barrier
	s_add_i32 s54, s56, s38
	s_mov_b32 m0, s54
	ds_read_b128 v[172:175], v5 offset:16384
	ds_read_b128 v[176:179], v5 offset:17408
	ds_read_b128 v[180:183], v5 offset:18432
	ds_read_b128 v[184:187], v5 offset:19456
	ds_read_b128 v[188:191], v5 offset:20480
	ds_read_b128 v[192:195], v5 offset:21504
	ds_read_b128 v[196:199], v5 offset:22528
	ds_read_b128 v[200:203], v5 offset:23552
	global_load_lds_dwordx4 v134, s[30:31]
	s_add_i32 m0, s54, 0x2000
	s_add_i32 s54, s57, s38
	global_load_lds_dwordx4 v138, s[30:31]
	s_add_u32 s30, s30, 0x100000
	s_addc_u32 s31, s31, 0
	s_mov_b32 m0, s54
	s_nop 0
	global_load_lds_dwordx4 v134, s[30:31]
	s_add_i32 m0, s54, 0x2000
	s_nop 0
	global_load_lds_dwordx4 v138, s[30:31]
	s_mov_b32 m0, s41
	s_nop 0
	global_load_lds_dwordx4 v2, s[28:29]
	s_mov_b32 m0, s3
	s_nop 0
	global_load_lds_dwordx4 v136, s[28:29]
	s_waitcnt vmcnt(8)
	s_waitcnt lgkmcnt(0)
	s_barrier
	s_setprio 1
	v_mfma_f32_16x16x32_bf16 v[66:69], v[140:143], v[172:175], v[66:69]
	v_mfma_f32_16x16x32_bf16 v[62:65], v[148:151], v[172:175], v[62:65]
	v_mfma_f32_16x16x32_bf16 v[50:53], v[140:143], v[180:183], v[50:53]
	v_mfma_f32_16x16x32_bf16 v[46:49], v[148:151], v[180:183], v[46:49]
	v_mfma_f32_16x16x32_bf16 v[34:37], v[140:143], v[188:191], v[34:37]
	v_mfma_f32_16x16x32_bf16 v[30:33], v[148:151], v[188:191], v[30:33]
	v_mfma_f32_16x16x32_bf16 v[18:21], v[140:143], v[196:199], v[18:21]
	v_mfma_f32_16x16x32_bf16 v[14:17], v[148:151], v[196:199], v[14:17]
	v_mfma_f32_16x16x32_bf16 v[66:69], v[144:147], v[176:179], v[66:69]
	v_mfma_f32_16x16x32_bf16 v[62:65], v[152:155], v[176:179], v[62:65]
	v_mfma_f32_16x16x32_bf16 v[50:53], v[144:147], v[184:187], v[50:53]
	v_mfma_f32_16x16x32_bf16 v[46:49], v[152:155], v[184:187], v[46:49]
	v_mfma_f32_16x16x32_bf16 v[34:37], v[144:147], v[192:195], v[34:37]
	v_mfma_f32_16x16x32_bf16 v[30:33], v[152:155], v[192:195], v[30:33]
	v_mfma_f32_16x16x32_bf16 v[18:21], v[144:147], v[200:203], v[18:21]
	v_mfma_f32_16x16x32_bf16 v[14:17], v[152:155], v[200:203], v[14:17]
	s_setprio 0
	s_setprio 1
	v_mfma_f32_16x16x32_bf16 v[58:61], v[156:159], v[172:175], v[58:61]
	v_mfma_f32_16x16x32_bf16 v[54:57], v[164:167], v[172:175], v[54:57]
	v_mfma_f32_16x16x32_bf16 v[42:45], v[156:159], v[180:183], v[42:45]
	v_mfma_f32_16x16x32_bf16 v[38:41], v[164:167], v[180:183], v[38:41]
	v_mfma_f32_16x16x32_bf16 v[26:29], v[156:159], v[188:191], v[26:29]
	v_mfma_f32_16x16x32_bf16 v[22:25], v[164:167], v[188:191], v[22:25]
	v_mfma_f32_16x16x32_bf16 v[10:13], v[156:159], v[196:199], v[10:13]
	v_mfma_f32_16x16x32_bf16 v[6:9], v[164:167], v[196:199], v[6:9]
	v_mfma_f32_16x16x32_bf16 v[58:61], v[160:163], v[176:179], v[58:61]
	v_mfma_f32_16x16x32_bf16 v[54:57], v[168:171], v[176:179], v[54:57]
	v_mfma_f32_16x16x32_bf16 v[42:45], v[160:163], v[184:187], v[42:45]
	v_mfma_f32_16x16x32_bf16 v[38:41], v[168:171], v[184:187], v[38:41]
	v_mfma_f32_16x16x32_bf16 v[26:29], v[160:163], v[192:195], v[26:29]
	v_mfma_f32_16x16x32_bf16 v[22:25], v[168:171], v[192:195], v[22:25]
	v_mfma_f32_16x16x32_bf16 v[10:13], v[160:163], v[200:203], v[10:13]
	v_mfma_f32_16x16x32_bf16 v[6:9], v[168:171], v[200:203], v[6:9]
	s_setprio 0
	s_barrier
	s_add_i32 s30, 0, 0x18000
	s_add_i32 s31, 0, 0x1c000
	v_add_u32_e32 v152, s30, v1
	v_add_u32_e32 v168, s31, v1
	ds_read_b128 v[140:143], v152
	ds_read_b128 v[144:147], v152 offset:1024
	ds_read_b128 v[148:151], v152 offset:2048
	ds_read_b128 v[152:155], v152 offset:3072
	ds_read_b128 v[156:159], v168
	ds_read_b128 v[160:163], v168 offset:1024
	ds_read_b128 v[164:167], v168 offset:2048
	ds_read_b128 v[168:171], v168 offset:3072
	s_add_u32 s28, s28, 0x100000
	s_addc_u32 s29, s29, 0
	s_mov_b32 m0, s43
	ds_read_b128 v[172:175], v5 offset:32768
	ds_read_b128 v[176:179], v5 offset:33792
	ds_read_b128 v[180:183], v5 offset:34816
	ds_read_b128 v[184:187], v5 offset:35840
	ds_read_b128 v[188:191], v5 offset:36864
	ds_read_b128 v[192:195], v5 offset:37888
	ds_read_b128 v[196:199], v5 offset:38912
	ds_read_b128 v[200:203], v5 offset:39936
	global_load_lds_dwordx4 v2, s[28:29]
	s_mov_b32 m0, s46
	s_nop 0
	global_load_lds_dwordx4 v136, s[28:29]
	s_waitcnt vmcnt(8)
	s_waitcnt lgkmcnt(0)
	s_barrier
	s_setprio 1
	v_mfma_f32_16x16x32_bf16 v[130:133], v[140:143], v[172:175], v[130:133]
	v_mfma_f32_16x16x32_bf16 v[126:129], v[148:151], v[172:175], v[126:129]
	v_mfma_f32_16x16x32_bf16 v[114:117], v[140:143], v[180:183], v[114:117]
	v_mfma_f32_16x16x32_bf16 v[110:113], v[148:151], v[180:183], v[110:113]
	v_mfma_f32_16x16x32_bf16 v[98:101], v[140:143], v[188:191], v[98:101]
	v_mfma_f32_16x16x32_bf16 v[94:97], v[148:151], v[188:191], v[94:97]
	v_mfma_f32_16x16x32_bf16 v[82:85], v[140:143], v[196:199], v[82:85]
	v_mfma_f32_16x16x32_bf16 v[78:81], v[148:151], v[196:199], v[78:81]
	v_mfma_f32_16x16x32_bf16 v[130:133], v[144:147], v[176:179], v[130:133]
	v_mfma_f32_16x16x32_bf16 v[126:129], v[152:155], v[176:179], v[126:129]
	v_mfma_f32_16x16x32_bf16 v[114:117], v[144:147], v[184:187], v[114:117]
	v_mfma_f32_16x16x32_bf16 v[110:113], v[152:155], v[184:187], v[110:113]
	v_mfma_f32_16x16x32_bf16 v[98:101], v[144:147], v[192:195], v[98:101]
	v_mfma_f32_16x16x32_bf16 v[94:97], v[152:155], v[192:195], v[94:97]
	v_mfma_f32_16x16x32_bf16 v[82:85], v[144:147], v[200:203], v[82:85]
	v_mfma_f32_16x16x32_bf16 v[78:81], v[152:155], v[200:203], v[78:81]
	s_setprio 0
	s_setprio 1
	v_mfma_f32_16x16x32_bf16 v[122:125], v[156:159], v[172:175], v[122:125]
	v_mfma_f32_16x16x32_bf16 v[118:121], v[164:167], v[172:175], v[118:121]
	v_mfma_f32_16x16x32_bf16 v[106:109], v[156:159], v[180:183], v[106:109]
	v_mfma_f32_16x16x32_bf16 v[102:105], v[164:167], v[180:183], v[102:105]
	v_mfma_f32_16x16x32_bf16 v[90:93], v[156:159], v[188:191], v[90:93]
	v_mfma_f32_16x16x32_bf16 v[86:89], v[164:167], v[188:191], v[86:89]
	v_mfma_f32_16x16x32_bf16 v[74:77], v[156:159], v[196:199], v[74:77]
	v_mfma_f32_16x16x32_bf16 v[70:73], v[164:167], v[196:199], v[70:73]
	v_mfma_f32_16x16x32_bf16 v[122:125], v[160:163], v[176:179], v[122:125]
	v_mfma_f32_16x16x32_bf16 v[118:121], v[168:171], v[176:179], v[118:121]
	v_mfma_f32_16x16x32_bf16 v[106:109], v[160:163], v[184:187], v[106:109]
	v_mfma_f32_16x16x32_bf16 v[102:105], v[168:171], v[184:187], v[102:105]
	v_mfma_f32_16x16x32_bf16 v[90:93], v[160:163], v[192:195], v[90:93]
	v_mfma_f32_16x16x32_bf16 v[86:89], v[168:171], v[192:195], v[86:89]
	v_mfma_f32_16x16x32_bf16 v[74:77], v[160:163], v[200:203], v[74:77]
	v_mfma_f32_16x16x32_bf16 v[70:73], v[168:171], v[200:203], v[70:73]
	s_setprio 0
	s_barrier
	s_add_i32 s28, s30, s38
	s_mov_b32 m0, s28
	ds_read_b128 v[172:175], v5 offset:49152
	ds_read_b128 v[176:179], v5 offset:50176
	ds_read_b128 v[180:183], v5 offset:51200
	ds_read_b128 v[184:187], v5 offset:52224
	ds_read_b128 v[188:191], v5 offset:53248
	ds_read_b128 v[192:195], v5 offset:54272
	ds_read_b128 v[196:199], v5 offset:55296
	ds_read_b128 v[200:203], v5 offset:56320
	global_load_lds_dwordx4 v134, s[26:27]
	s_add_i32 m0, s28, 0x2000
	s_add_i32 s28, s31, s38
	global_load_lds_dwordx4 v138, s[26:27]
	s_add_u32 s26, s26, 0x100000
	s_addc_u32 s27, s27, 0
	s_mov_b32 m0, s28
	s_nop 0
	global_load_lds_dwordx4 v134, s[26:27]
	s_add_i32 m0, s28, 0x2000
	s_nop 0
	global_load_lds_dwordx4 v138, s[26:27]
	s_mov_b32 m0, s49
	s_nop 0
	global_load_lds_dwordx4 v2, s[24:25]
	s_mov_b32 m0, s50
	s_nop 0
	global_load_lds_dwordx4 v136, s[24:25]
	s_waitcnt vmcnt(8)
	s_waitcnt lgkmcnt(0)
	s_barrier
	s_setprio 1
	v_mfma_f32_16x16x32_bf16 v[66:69], v[140:143], v[172:175], v[66:69]
	v_mfma_f32_16x16x32_bf16 v[62:65], v[148:151], v[172:175], v[62:65]
	v_mfma_f32_16x16x32_bf16 v[50:53], v[140:143], v[180:183], v[50:53]
	v_mfma_f32_16x16x32_bf16 v[46:49], v[148:151], v[180:183], v[46:49]
	v_mfma_f32_16x16x32_bf16 v[34:37], v[140:143], v[188:191], v[34:37]
	v_mfma_f32_16x16x32_bf16 v[30:33], v[148:151], v[188:191], v[30:33]
	v_mfma_f32_16x16x32_bf16 v[18:21], v[140:143], v[196:199], v[18:21]
	v_mfma_f32_16x16x32_bf16 v[14:17], v[148:151], v[196:199], v[14:17]
	v_mfma_f32_16x16x32_bf16 v[66:69], v[144:147], v[176:179], v[66:69]
	v_mfma_f32_16x16x32_bf16 v[62:65], v[152:155], v[176:179], v[62:65]
	v_mfma_f32_16x16x32_bf16 v[50:53], v[144:147], v[184:187], v[50:53]
	v_mfma_f32_16x16x32_bf16 v[46:49], v[152:155], v[184:187], v[46:49]
	v_mfma_f32_16x16x32_bf16 v[34:37], v[144:147], v[192:195], v[34:37]
	v_mfma_f32_16x16x32_bf16 v[30:33], v[152:155], v[192:195], v[30:33]
	v_mfma_f32_16x16x32_bf16 v[18:21], v[144:147], v[200:203], v[18:21]
	v_mfma_f32_16x16x32_bf16 v[14:17], v[152:155], v[200:203], v[14:17]
	s_setprio 0
	s_setprio 1
	v_mfma_f32_16x16x32_bf16 v[58:61], v[156:159], v[172:175], v[58:61]
	v_mfma_f32_16x16x32_bf16 v[54:57], v[164:167], v[172:175], v[54:57]
	v_mfma_f32_16x16x32_bf16 v[42:45], v[156:159], v[180:183], v[42:45]
	v_mfma_f32_16x16x32_bf16 v[38:41], v[164:167], v[180:183], v[38:41]
	v_mfma_f32_16x16x32_bf16 v[26:29], v[156:159], v[188:191], v[26:29]
	v_mfma_f32_16x16x32_bf16 v[22:25], v[164:167], v[188:191], v[22:25]
	v_mfma_f32_16x16x32_bf16 v[10:13], v[156:159], v[196:199], v[10:13]
	v_mfma_f32_16x16x32_bf16 v[6:9], v[164:167], v[196:199], v[6:9]
	v_mfma_f32_16x16x32_bf16 v[58:61], v[160:163], v[176:179], v[58:61]
	v_mfma_f32_16x16x32_bf16 v[54:57], v[168:171], v[176:179], v[54:57]
	v_mfma_f32_16x16x32_bf16 v[42:45], v[160:163], v[184:187], v[42:45]
	v_mfma_f32_16x16x32_bf16 v[38:41], v[168:171], v[184:187], v[38:41]
	v_mfma_f32_16x16x32_bf16 v[26:29], v[160:163], v[192:195], v[26:29]
	v_mfma_f32_16x16x32_bf16 v[22:25], v[168:171], v[192:195], v[22:25]
	v_mfma_f32_16x16x32_bf16 v[10:13], v[160:163], v[200:203], v[10:13]
	v_mfma_f32_16x16x32_bf16 v[6:9], v[168:171], v[200:203], v[6:9]
	s_setprio 0
	s_barrier
	s_add_i32 s53, s53, 2
	s_add_u32 s19, s19, 0x100
	s_addc_u32 s23, s23, 0
	s_add_u32 s33, s33, 0x100
	s_addc_u32 s52, s52, 0
	s_cmp_gt_u32 s53, 61
	s_cbranch_scc0 .LBB0_346
	v_mov_b32_e32 v140, v0
	s_lshl_b32 s1, s0, 8
	s_mov_b64 s[24:25], s[84:85]
	s_add_i32 s1, s1, s47
	v_bfe_u32 v210, v140, 4, 2
	v_and_or_b32 v140, v140, 15, s1
	s_add_u32 s26, s24, s6
	s_addc_u32 s27, s25, s7
	v_ashrrev_i32_e32 v141, 31, v140
	v_lshl_add_u64 v[142:143], v[140:141], 2, s[26:27]
	s_mov_b64 s[26:27], 0x10000
	v_lshl_add_u64 v[154:155], v[142:143], 0, s[26:27]
	v_add_co_u32_e32 v142, vcc, s91, v142
	s_cmp_gt_i32 s22, 3
	s_nop 0
	v_addc_co_u32_e32 v143, vcc, 0, v143, vcc
	global_load_dword v142, v[142:143], off
	s_cselect_b64 s[28:29], -1, 0
	s_cmp_lt_i32 s22, 4
	s_cselect_b64 s[26:27], -1, 0
	global_load_dword v205, v[154:155], off offset:64
	global_load_dword v204, v[154:155], off offset:128
	global_load_dword v203, v[154:155], off offset:192
	global_load_dword v202, v[154:155], off offset:512
	global_load_dword v201, v[154:155], off offset:576
	global_load_dword v200, v[154:155], off offset:640
	global_load_dword v199, v[154:155], off offset:704
	s_waitcnt vmcnt(0)
	v_fmamk_f32 v142, v142, 0x39800000, v246
	v_cmp_gt_f32_e32 vcc, s95, v142
	v_mul_f32_e32 v143, 0x4b800000, v142
	s_nop 0
	v_cndmask_b32_e32 v142, v142, v143, vcc
	v_rsq_f32_e32 v142, v142
	s_nop 0
	v_mul_f32_e32 v143, 0x45800000, v142
	v_cndmask_b32_e32 v142, v142, v143, vcc
	v_pk_mul_f32 v[132:133], v[132:133], v[142:143] op_sel_hi:[1,0]
	v_pk_mul_f32 v[130:131], v[130:131], v[142:143] op_sel_hi:[1,0]
	v_pk_mul_f32 v[128:129], v[128:129], v[142:143] op_sel_hi:[1,0]
	v_pk_mul_f32 v[126:127], v[126:127], v[142:143] op_sel_hi:[1,0]
	v_pk_mul_f32 v[124:125], v[124:125], v[142:143] op_sel_hi:[1,0]
	v_pk_mul_f32 v[122:123], v[122:123], v[142:143] op_sel_hi:[1,0]
	v_pk_mul_f32 v[120:121], v[120:121], v[142:143] op_sel_hi:[1,0]
	v_pk_mul_f32 v[118:119], v[118:119], v[142:143] op_sel_hi:[1,0]
	s_waitcnt vmcnt(0)
	v_fmamk_f32 v142, v205, 0x39800000, v246
	v_cmp_gt_f32_e32 vcc, s95, v142
	v_mul_f32_e32 v143, 0x4b800000, v142
	s_nop 0
	v_cndmask_b32_e32 v142, v142, v143, vcc
	v_rsq_f32_e32 v142, v142
	s_nop 0
	v_mul_f32_e32 v143, 0x45800000, v142
	v_cndmask_b32_e32 v142, v142, v143, vcc
	v_pk_mul_f32 v[116:117], v[116:117], v[142:143] op_sel_hi:[1,0]
	v_pk_mul_f32 v[114:115], v[114:115], v[142:143] op_sel_hi:[1,0]
	v_pk_mul_f32 v[112:113], v[112:113], v[142:143] op_sel_hi:[1,0]
	v_pk_mul_f32 v[110:111], v[110:111], v[142:143] op_sel_hi:[1,0]
	v_pk_mul_f32 v[108:109], v[108:109], v[142:143] op_sel_hi:[1,0]
	v_pk_mul_f32 v[106:107], v[106:107], v[142:143] op_sel_hi:[1,0]
	v_pk_mul_f32 v[104:105], v[104:105], v[142:143] op_sel_hi:[1,0]
	v_pk_mul_f32 v[102:103], v[102:103], v[142:143] op_sel_hi:[1,0]
	s_waitcnt vmcnt(0)
	v_fmamk_f32 v142, v204, 0x39800000, v246
	v_cmp_gt_f32_e32 vcc, s95, v142
	v_mul_f32_e32 v143, 0x4b800000, v142
	s_nop 0
	v_cndmask_b32_e32 v142, v142, v143, vcc
	v_rsq_f32_e32 v142, v142
	s_nop 0
	v_mul_f32_e32 v143, 0x45800000, v142
	v_cndmask_b32_e32 v142, v142, v143, vcc
	v_pk_mul_f32 v[150:151], v[94:95], v[142:143] op_sel_hi:[1,0]
	v_pk_mul_f32 v[152:153], v[98:99], v[142:143] op_sel_hi:[1,0]
	v_pk_mul_f32 v[100:101], v[100:101], v[142:143] op_sel_hi:[1,0]
	v_pk_mul_f32 v[92:93], v[92:93], v[142:143] op_sel_hi:[1,0]
	v_pk_mul_f32 v[90:91], v[90:91], v[142:143] op_sel_hi:[1,0]
	v_pk_mul_f32 v[86:87], v[86:87], v[142:143] op_sel_hi:[1,0]
	v_pk_mul_f32 v[96:97], v[96:97], v[142:143] op_sel_hi:[1,0]
	v_pk_mul_f32 v[88:89], v[88:89], v[142:143] op_sel_hi:[1,0]
	s_waitcnt vmcnt(0)
	v_fmamk_f32 v94, v203, 0x39800000, v246
	v_cmp_gt_f32_e32 vcc, s95, v94
	v_mul_f32_e32 v95, 0x4b800000, v94
	s_nop 0
	v_cndmask_b32_e32 v94, v94, v95, vcc
	v_rsq_f32_e32 v94, v94
	s_nop 0
	v_mul_f32_e32 v95, 0x45800000, v94
	v_cndmask_b32_e32 v94, v94, v95, vcc
	v_pk_mul_f32 v[164:165], v[80:81], v[94:95] op_sel_hi:[1,0]
	v_pk_mul_f32 v[80:81], v[74:75], v[94:95] op_sel_hi:[1,0]
	v_pk_mul_f32 v[166:167], v[84:85], v[94:95] op_sel_hi:[1,0]
	v_pk_mul_f32 v[170:171], v[82:83], v[94:95] op_sel_hi:[1,0]
	v_pk_mul_f32 v[168:169], v[78:79], v[94:95] op_sel_hi:[1,0]
	v_pk_mul_f32 v[78:79], v[76:77], v[94:95] op_sel_hi:[1,0]
	v_pk_mul_f32 v[72:73], v[72:73], v[94:95] op_sel_hi:[1,0]
	v_pk_mul_f32 v[70:71], v[70:71], v[94:95] op_sel_hi:[1,0]
	s_waitcnt vmcnt(0)
	v_fmamk_f32 v74, v202, 0x39800000, v246
	v_cmp_gt_f32_e32 vcc, s95, v74
	v_mul_f32_e32 v75, 0x4b800000, v74
	s_nop 0
	v_cndmask_b32_e32 v74, v74, v75, vcc
	v_rsq_f32_e32 v74, v74
	s_nop 0
	v_mul_f32_e32 v75, 0x45800000, v74
	v_cndmask_b32_e32 v98, v74, v75, vcc
	v_pk_mul_f32 v[76:77], v[68:69], v[98:99] op_sel_hi:[1,0]
	v_pk_mul_f32 v[176:177], v[66:67], v[98:99] op_sel_hi:[1,0]
	v_pk_mul_f32 v[74:75], v[64:65], v[98:99] op_sel_hi:[1,0]
	v_pk_mul_f32 v[174:175], v[62:63], v[98:99] op_sel_hi:[1,0]
	v_pk_mul_f32 v[84:85], v[60:61], v[98:99] op_sel_hi:[1,0]
	v_pk_mul_f32 v[94:95], v[58:59], v[98:99] op_sel_hi:[1,0]
	v_pk_mul_f32 v[82:83], v[56:57], v[98:99] op_sel_hi:[1,0]
	v_pk_mul_f32 v[98:99], v[54:55], v[98:99] op_sel_hi:[1,0]
	s_waitcnt vmcnt(0)
	v_fmamk_f32 v54, v201, 0x39800000, v246
	v_cmp_gt_f32_e32 vcc, s95, v54
	v_mul_f32_e32 v55, 0x4b800000, v54
	s_nop 0
	v_cndmask_b32_e32 v54, v54, v55, vcc
	v_rsq_f32_e32 v54, v54
	s_nop 0
	v_mul_f32_e32 v55, 0x45800000, v54
	v_cndmask_b32_e32 v54, v54, v55, vcc
	v_pk_mul_f32 v[146:147], v[38:39], v[54:55] op_sel_hi:[1,0]
	v_pk_mul_f32 v[180:181], v[52:53], v[54:55] op_sel_hi:[1,0]
	v_pk_mul_f32 v[184:185], v[50:51], v[54:55] op_sel_hi:[1,0]
	v_pk_mul_f32 v[144:145], v[44:45], v[54:55] op_sel_hi:[1,0]
	v_pk_mul_f32 v[148:149], v[42:43], v[54:55] op_sel_hi:[1,0]
	v_pk_mul_f32 v[182:183], v[46:47], v[54:55] op_sel_hi:[1,0]
	v_pk_mul_f32 v[178:179], v[48:49], v[54:55] op_sel_hi:[1,0]
	v_pk_mul_f32 v[142:143], v[40:41], v[54:55] op_sel_hi:[1,0]
	s_waitcnt vmcnt(0)
	v_fmamk_f32 v38, v200, 0x39800000, v246
	v_cmp_gt_f32_e32 vcc, s95, v38
	v_mul_f32_e32 v39, 0x4b800000, v38
	s_nop 0
	v_cndmask_b32_e32 v38, v38, v39, vcc
	v_rsq_f32_e32 v38, v38
	s_nop 0
	v_mul_f32_e32 v39, 0x45800000, v38
	v_cndmask_b32_e32 v38, v38, v39, vcc
	v_pk_mul_f32 v[160:161], v[22:23], v[38:39] op_sel_hi:[1,0]
	v_pk_mul_f32 v[188:189], v[36:37], v[38:39] op_sel_hi:[1,0]
	v_pk_mul_f32 v[192:193], v[34:35], v[38:39] op_sel_hi:[1,0]
	v_pk_mul_f32 v[158:159], v[28:29], v[38:39] op_sel_hi:[1,0]
	v_pk_mul_f32 v[162:163], v[26:27], v[38:39] op_sel_hi:[1,0]
	v_pk_mul_f32 v[186:187], v[32:33], v[38:39] op_sel_hi:[1,0]
	v_pk_mul_f32 v[190:191], v[30:31], v[38:39] op_sel_hi:[1,0]
	v_pk_mul_f32 v[156:157], v[24:25], v[38:39] op_sel_hi:[1,0]
	v_mul_f32_e32 v24, v95, v95
	v_mul_f32_e32 v25, v85, v85
	v_mul_f32_e32 v26, v185, v185
	v_mul_f32_e32 v27, v181, v181
	v_mul_f32_e32 v28, v149, v149
	v_mul_f32_e32 v29, v145, v145
	v_mul_f32_e32 v30, v193, v193
	v_mul_f32_e32 v31, v189, v189
	v_mul_f32_e32 v32, v163, v163
	v_mul_f32_e32 v33, v159, v159
	v_fmac_f32_e32 v24, v94, v94
	v_fmac_f32_e32 v25, v84, v84
	v_fmac_f32_e32 v26, v184, v184
	v_fmac_f32_e32 v27, v180, v180
	v_fmac_f32_e32 v28, v148, v148
	v_fmac_f32_e32 v29, v144, v144
	v_fmac_f32_e32 v30, v192, v192
	v_fmac_f32_e32 v31, v188, v188
	v_fmac_f32_e32 v32, v162, v162
	v_fmac_f32_e32 v33, v158, v158
	v_add_f32_e32 v24, v24, v25
	v_mul_f32_e32 v25, v99, v99
	v_add_f32_e32 v26, v26, v27
	v_mul_f32_e32 v27, v183, v183
	v_add_f32_e32 v28, v28, v29
	v_mul_f32_e32 v29, v147, v147
	v_add_f32_e32 v30, v30, v31
	v_mul_f32_e32 v31, v191, v191
	v_add_f32_e32 v32, v32, v33
	v_mul_f32_e32 v33, v161, v161
	v_fmac_f32_e32 v25, v98, v98
	v_fmac_f32_e32 v27, v182, v182
	v_fmac_f32_e32 v29, v146, v146
	v_fmac_f32_e32 v31, v190, v190
	v_fmac_f32_e32 v33, v160, v160
	v_add_f32_e32 v24, v25, v24
	v_mul_f32_e32 v25, v83, v83
	v_add_f32_e32 v26, v27, v26
	v_mul_f32_e32 v27, v179, v179
	v_add_f32_e32 v28, v29, v28
	v_mul_f32_e32 v29, v143, v143
	v_add_f32_e32 v30, v31, v30
	v_mul_f32_e32 v31, v187, v187
	v_add_f32_e32 v32, v33, v32
	v_mul_f32_e32 v33, v157, v157
	v_fmac_f32_e32 v25, v82, v82
	v_fmac_f32_e32 v27, v178, v178
	v_fmac_f32_e32 v29, v142, v142
	v_fmac_f32_e32 v31, v186, v186
	v_fmac_f32_e32 v33, v156, v156
	v_add_f32_e32 v24, v25, v24
	v_add_f32_e32 v26, v27, v26
	v_add_f32_e32 v28, v29, v28
	v_add_f32_e32 v30, v31, v30
	v_add_f32_e32 v32, v33, v32
	ds_swizzle_b32 v25, v24 offset:swizzle(SWAP,16)
	ds_swizzle_b32 v27, v26 offset:swizzle(SWAP,16)
	ds_swizzle_b32 v29, v28 offset:swizzle(SWAP,16)
	ds_swizzle_b32 v31, v30 offset:swizzle(SWAP,16)
	ds_swizzle_b32 v33, v32 offset:swizzle(SWAP,16)
	s_waitcnt lgkmcnt(4)
	v_add_f32_e32 v24, v24, v25
	s_waitcnt lgkmcnt(3)
	v_add_f32_e32 v26, v26, v27
	s_waitcnt lgkmcnt(2)
	v_add_f32_e32 v28, v28, v29
	s_waitcnt lgkmcnt(1)
	v_add_f32_e32 v30, v30, v31
	s_waitcnt lgkmcnt(0)
	v_add_f32_e32 v32, v32, v33
	v_mov_b32_e32 v25, v24
	v_mov_b32_e32 v27, v26
	v_mov_b32_e32 v29, v28
	v_mov_b32_e32 v31, v30
	v_mov_b32_e32 v33, v32
	v_permlane32_swap_b32_e32 v24, v25
	s_waitcnt vmcnt(0)
	v_fmamk_f32 v22, v199, 0x39800000, v246
	v_cmp_gt_f32_e32 vcc, s95, v22
	v_mul_f32_e32 v23, 0x4b800000, v22
	v_permlane32_swap_b32_e32 v26, v27
	v_cndmask_b32_e32 v22, v22, v23, vcc
	v_rsq_f32_e32 v22, v22
	v_permlane32_swap_b32_e32 v28, v29
	v_permlane32_swap_b32_e32 v30, v31
	v_mul_f32_e32 v23, 0x45800000, v22
	v_cndmask_b32_e32 v22, v22, v23, vcc
	v_pk_mul_f32 v[202:203], v[20:21], v[22:23] op_sel_hi:[1,0]
	v_pk_mul_f32 v[204:205], v[18:19], v[22:23] op_sel_hi:[1,0]
	v_pk_mul_f32 v[194:195], v[12:13], v[22:23] op_sel_hi:[1,0]
	v_pk_mul_f32 v[196:197], v[10:11], v[22:23] op_sel_hi:[1,0]
	v_pk_mul_f32 v[206:207], v[16:17], v[22:23] op_sel_hi:[1,0]
	v_pk_mul_f32 v[208:209], v[14:15], v[22:23] op_sel_hi:[1,0]
	v_pk_mul_f32 v[198:199], v[8:9], v[22:23] op_sel_hi:[1,0]
	v_pk_mul_f32 v[200:201], v[6:7], v[22:23] op_sel_hi:[1,0]
	v_mul_f32_e32 v6, v131, v131
	v_mul_f32_e32 v7, v133, v133
	v_mul_f32_e32 v8, v123, v123
	v_mul_f32_e32 v9, v125, v125
	v_mul_f32_e32 v10, v115, v115
	v_mul_f32_e32 v11, v117, v117
	v_mul_f32_e32 v12, v107, v107
	v_mul_f32_e32 v13, v109, v109
	v_mul_f32_e32 v14, v153, v153
	v_mul_f32_e32 v15, v101, v101
	v_mul_f32_e32 v16, v91, v91
	v_mul_f32_e32 v17, v93, v93
	v_mul_f32_e32 v18, v171, v171
	v_mul_f32_e32 v19, v167, v167
	v_mul_f32_e32 v20, v81, v81
	v_mul_f32_e32 v21, v79, v79
	v_mul_f32_e32 v22, v177, v177
	v_mul_f32_e32 v23, v77, v77
	v_mul_f32_e32 v34, v205, v205
	v_mul_f32_e32 v35, v203, v203
	v_mul_f32_e32 v36, v197, v197
	v_mul_f32_e32 v37, v195, v195
	v_fmac_f32_e32 v6, v130, v130
	v_fmac_f32_e32 v7, v132, v132
	v_fmac_f32_e32 v8, v122, v122
	v_fmac_f32_e32 v9, v124, v124
	v_fmac_f32_e32 v10, v114, v114
	v_fmac_f32_e32 v11, v116, v116
	v_fmac_f32_e32 v12, v106, v106
	v_fmac_f32_e32 v13, v108, v108
	v_fmac_f32_e32 v14, v152, v152
	v_fmac_f32_e32 v15, v100, v100
	v_fmac_f32_e32 v16, v90, v90
	v_fmac_f32_e32 v17, v92, v92
	v_fmac_f32_e32 v18, v170, v170
	v_fmac_f32_e32 v19, v166, v166
	v_fmac_f32_e32 v20, v80, v80
	v_fmac_f32_e32 v21, v78, v78
	v_fmac_f32_e32 v22, v176, v176
	v_fmac_f32_e32 v23, v76, v76
	v_fmac_f32_e32 v34, v204, v204
	v_fmac_f32_e32 v35, v202, v202
	v_fmac_f32_e32 v36, v196, v196
	v_fmac_f32_e32 v37, v194, v194
	v_add_f32_e32 v6, v6, v7
	v_mul_f32_e32 v7, v127, v127
	v_add_f32_e32 v8, v8, v9
	v_mul_f32_e32 v9, v119, v119
	v_add_f32_e32 v10, v10, v11
	v_mul_f32_e32 v11, v111, v111
	v_add_f32_e32 v12, v12, v13
	v_mul_f32_e32 v13, v103, v103
	v_add_f32_e32 v14, v14, v15
	v_mul_f32_e32 v15, v151, v151
	v_add_f32_e32 v16, v16, v17
	v_mul_f32_e32 v17, v87, v87
	v_add_f32_e32 v18, v18, v19
	v_mul_f32_e32 v19, v169, v169
	v_add_f32_e32 v20, v20, v21
	v_mul_f32_e32 v21, v71, v71
	v_add_f32_e32 v22, v22, v23
	v_mul_f32_e32 v23, v175, v175
	v_add_f32_e32 v34, v34, v35
	v_mul_f32_e32 v35, v209, v209
	v_add_f32_e32 v36, v36, v37
	v_mul_f32_e32 v37, v201, v201
	v_fmac_f32_e32 v7, v126, v126
	v_fmac_f32_e32 v9, v118, v118
	v_fmac_f32_e32 v11, v110, v110
	v_fmac_f32_e32 v13, v102, v102
	v_fmac_f32_e32 v15, v150, v150
	v_fmac_f32_e32 v17, v86, v86
	v_fmac_f32_e32 v19, v168, v168
	v_fmac_f32_e32 v21, v70, v70
	v_fmac_f32_e32 v23, v174, v174
	v_fmac_f32_e32 v35, v208, v208
	v_fmac_f32_e32 v37, v200, v200
	v_add_f32_e32 v6, v7, v6
	v_mul_f32_e32 v7, v129, v129
	v_add_f32_e32 v8, v9, v8
	v_mul_f32_e32 v9, v121, v121
	v_add_f32_e32 v10, v11, v10
	v_mul_f32_e32 v11, v113, v113
	v_add_f32_e32 v12, v13, v12
	v_mul_f32_e32 v13, v105, v105
	v_add_f32_e32 v14, v15, v14
	v_mul_f32_e32 v15, v97, v97
	v_add_f32_e32 v16, v17, v16
	v_mul_f32_e32 v17, v89, v89
	v_add_f32_e32 v18, v19, v18
	v_mul_f32_e32 v19, v165, v165
	v_add_f32_e32 v20, v21, v20
	v_mul_f32_e32 v21, v73, v73
	v_add_f32_e32 v22, v23, v22
	v_mul_f32_e32 v23, v75, v75
	v_add_f32_e32 v34, v35, v34
	v_mul_f32_e32 v35, v207, v207
	v_add_f32_e32 v36, v37, v36
	v_mul_f32_e32 v37, v199, v199
	v_fmac_f32_e32 v7, v128, v128
	v_fmac_f32_e32 v9, v120, v120
	v_fmac_f32_e32 v11, v112, v112
	v_fmac_f32_e32 v13, v104, v104
	v_fmac_f32_e32 v15, v96, v96
	v_fmac_f32_e32 v17, v88, v88
	v_fmac_f32_e32 v19, v164, v164
	v_fmac_f32_e32 v21, v72, v72
	v_fmac_f32_e32 v23, v74, v74
	v_fmac_f32_e32 v35, v206, v206
	v_fmac_f32_e32 v37, v198, v198
	v_add_f32_e32 v6, v7, v6
	v_add_f32_e32 v8, v9, v8
	v_add_f32_e32 v10, v11, v10
	v_add_f32_e32 v12, v13, v12
	v_add_f32_e32 v14, v15, v14
	v_add_f32_e32 v16, v17, v16
	v_add_f32_e32 v18, v19, v18
	v_add_f32_e32 v20, v21, v20
	v_add_f32_e32 v22, v23, v22
	v_add_f32_e32 v34, v35, v34
	v_add_f32_e32 v36, v37, v36
	ds_swizzle_b32 v7, v6 offset:swizzle(SWAP,16)
	ds_swizzle_b32 v9, v8 offset:swizzle(SWAP,16)
	ds_swizzle_b32 v11, v10 offset:swizzle(SWAP,16)
	ds_swizzle_b32 v13, v12 offset:swizzle(SWAP,16)
	ds_swizzle_b32 v15, v14 offset:swizzle(SWAP,16)
	ds_swizzle_b32 v17, v16 offset:swizzle(SWAP,16)
	ds_swizzle_b32 v19, v18 offset:swizzle(SWAP,16)
	ds_swizzle_b32 v21, v20 offset:swizzle(SWAP,16)
	ds_swizzle_b32 v23, v22 offset:swizzle(SWAP,16)
	ds_swizzle_b32 v35, v34 offset:swizzle(SWAP,16)
	ds_swizzle_b32 v37, v36 offset:swizzle(SWAP,16)
	s_waitcnt lgkmcnt(10)
	v_add_f32_e32 v6, v6, v7
	s_waitcnt lgkmcnt(9)
	v_add_f32_e32 v8, v8, v9
	s_waitcnt lgkmcnt(8)
	v_add_f32_e32 v10, v10, v11
	s_waitcnt lgkmcnt(7)
	v_add_f32_e32 v12, v12, v13
	s_waitcnt lgkmcnt(6)
	v_add_f32_e32 v14, v14, v15
	s_waitcnt lgkmcnt(5)
	v_add_f32_e32 v16, v16, v17
	s_waitcnt lgkmcnt(4)
	v_add_f32_e32 v18, v18, v19
	s_waitcnt lgkmcnt(3)
	v_add_f32_e32 v20, v20, v21
	s_waitcnt lgkmcnt(2)
	v_add_f32_e32 v22, v22, v23
	s_waitcnt lgkmcnt(1)
	v_add_f32_e32 v34, v34, v35
	s_waitcnt lgkmcnt(0)
	v_add_f32_e32 v36, v36, v37
	v_mov_b32_e32 v7, v6
	v_mov_b32_e32 v9, v8
	v_mov_b32_e32 v11, v10
	v_mov_b32_e32 v13, v12
	v_mov_b32_e32 v15, v14
	v_mov_b32_e32 v17, v16
	v_mov_b32_e32 v19, v18
	v_mov_b32_e32 v21, v20
	v_mov_b32_e32 v23, v22
	v_mov_b32_e32 v35, v34
	v_mov_b32_e32 v37, v36
	v_permlane32_swap_b32_e32 v6, v7
	v_permlane32_swap_b32_e32 v8, v9
	v_permlane32_swap_b32_e32 v10, v11
	v_permlane32_swap_b32_e32 v12, v13
	v_permlane32_swap_b32_e32 v14, v15
	v_permlane32_swap_b32_e32 v16, v17
	v_permlane32_swap_b32_e32 v18, v19
	v_permlane32_swap_b32_e32 v20, v21
	v_permlane32_swap_b32_e32 v22, v23
	v_permlane32_swap_b32_e32 v32, v33
	v_permlane32_swap_b32_e32 v34, v35
	v_permlane32_swap_b32_e32 v36, v37
	v_cmp_eq_u32_e32 vcc, 0, v210
	s_and_saveexec_b64 s[30:31], vcc
	s_cbranch_execz .LBB0_349
	s_and_b64 s[52:53], s[28:29], exec
	s_mov_b32 s1, 0x31000
	s_cselect_b32 s1, s1, 0x20800
	s_add_u32 s1, s24, s1
	s_addc_u32 s2, s25, 0
	s_add_u32 s52, s1, s6
	v_add_f32_e32 v8, v8, v9
	v_add_f32_e32 v9, v6, v7
	s_addc_u32 s53, s2, s7
	v_add_f32_e32 v12, v12, v13
	v_add_f32_e32 v10, v10, v11
	v_lshl_add_u64 v[6:7], v[140:141], 2, s[52:53]
	v_add_f32_e32 v8, v9, v8
	v_add_f32_e32 v16, v16, v17
	v_add_f32_e32 v14, v14, v15
	global_atomic_add_f32 v[6:7], v8, off
	v_add_f32_e32 v8, v10, v12
	v_add_f32_e32 v20, v20, v21
	v_add_f32_e32 v18, v18, v19
	global_atomic_add_f32 v[6:7], v8, off offset:64
	v_add_f32_e32 v8, v14, v16
	v_add_f32_e32 v24, v24, v25
	v_add_f32_e32 v22, v22, v23
	global_atomic_add_f32 v[6:7], v8, off offset:128
	v_add_f32_e32 v8, v18, v20
	v_add_f32_e32 v28, v28, v29
	v_add_f32_e32 v26, v26, v27
	global_atomic_add_f32 v[6:7], v8, off offset:192
	v_add_f32_e32 v8, v22, v24
	v_add_f32_e32 v32, v32, v33
	v_add_f32_e32 v30, v30, v31
	global_atomic_add_f32 v[6:7], v8, off offset:512
	v_add_f32_e32 v8, v26, v28
	v_add_f32_e32 v36, v36, v37
	v_add_f32_e32 v34, v34, v35
	global_atomic_add_f32 v[6:7], v8, off offset:576
	v_add_f32_e32 v8, v30, v32
	global_atomic_add_f32 v[6:7], v8, off offset:640
	v_add_f32_e32 v8, v34, v36
	global_atomic_add_f32 v[6:7], v8, off offset:704

.LBB0_454:
	s_add_u32 s66, s62, 0xffffff80
	s_addc_u32 s67, s63, -1
	s_cmp_eq_u32 s64, 12
	s_cselect_b32 s38, s21, s62
	s_cselect_b32 s39, s3, s63
	s_cselect_b32 s41, s23, s61
	s_cselect_b32 s40, s31, s33
	s_add_u32 s34, s38, 0x80
	s_addc_u32 s35, s39, 0
	s_add_u32 s36, s40, 0x80
	s_addc_u32 s37, s41, 0
	s_add_i32 s65, 0, 0x10000
	s_add_i32 s68, 0, 0x14000
	v_add_u32_e32 v152, s65, v1
	v_add_u32_e32 v168, s68, v1
	ds_read_b128 v[140:143], v152
	ds_read_b128 v[144:147], v152 offset:1024
	ds_read_b128 v[148:151], v152 offset:2048
	ds_read_b128 v[152:155], v152 offset:3072
	ds_read_b128 v[156:159], v168
	ds_read_b128 v[160:163], v168 offset:1024
	ds_read_b128 v[164:167], v168 offset:2048
	ds_read_b128 v[168:171], v168 offset:3072
	s_add_u32 s66, s66, 0x40000
	s_addc_u32 s67, s67, 0
	s_add_i32 m0, s29, 0xc000
	ds_read_b128 v[172:175], v5
	ds_read_b128 v[176:179], v5 offset:1024
	ds_read_b128 v[180:183], v5 offset:2048
	ds_read_b128 v[184:187], v5 offset:3072
	ds_read_b128 v[188:191], v5 offset:4096
	ds_read_b128 v[192:195], v5 offset:5120
	ds_read_b128 v[196:199], v5 offset:6144
	ds_read_b128 v[200:203], v5 offset:7168
	global_load_lds_dwordx4 v2, s[66:67]
	s_add_i32 m0, s29, 0xe000
	s_nop 0
	global_load_lds_dwordx4 v136, s[66:67]
	s_waitcnt vmcnt(8)
	s_waitcnt lgkmcnt(0)
	s_barrier
	s_setprio 1
	v_mfma_f32_16x16x32_bf16 v[130:133], v[140:143], v[172:175], v[130:133]
	v_mfma_f32_16x16x32_bf16 v[126:129], v[148:151], v[172:175], v[126:129]
	v_mfma_f32_16x16x32_bf16 v[114:117], v[140:143], v[180:183], v[114:117]
	v_mfma_f32_16x16x32_bf16 v[110:113], v[148:151], v[180:183], v[110:113]
	v_mfma_f32_16x16x32_bf16 v[98:101], v[140:143], v[188:191], v[98:101]
	v_mfma_f32_16x16x32_bf16 v[94:97], v[148:151], v[188:191], v[94:97]
	v_mfma_f32_16x16x32_bf16 v[82:85], v[140:143], v[196:199], v[82:85]
	v_mfma_f32_16x16x32_bf16 v[78:81], v[148:151], v[196:199], v[78:81]
	v_mfma_f32_16x16x32_bf16 v[130:133], v[144:147], v[176:179], v[130:133]
	v_mfma_f32_16x16x32_bf16 v[126:129], v[152:155], v[176:179], v[126:129]
	v_mfma_f32_16x16x32_bf16 v[114:117], v[144:147], v[184:187], v[114:117]
	v_mfma_f32_16x16x32_bf16 v[110:113], v[152:155], v[184:187], v[110:113]
	v_mfma_f32_16x16x32_bf16 v[98:101], v[144:147], v[192:195], v[98:101]
	v_mfma_f32_16x16x32_bf16 v[94:97], v[152:155], v[192:195], v[94:97]
	v_mfma_f32_16x16x32_bf16 v[82:85], v[144:147], v[200:203], v[82:85]
	v_mfma_f32_16x16x32_bf16 v[78:81], v[152:155], v[200:203], v[78:81]
	s_setprio 0
	s_setprio 1
	v_mfma_f32_16x16x32_bf16 v[122:125], v[156:159], v[172:175], v[122:125]
	v_mfma_f32_16x16x32_bf16 v[118:121], v[164:167], v[172:175], v[118:121]
	v_mfma_f32_16x16x32_bf16 v[106:109], v[156:159], v[180:183], v[106:109]
	v_mfma_f32_16x16x32_bf16 v[102:105], v[164:167], v[180:183], v[102:105]
	v_mfma_f32_16x16x32_bf16 v[90:93], v[156:159], v[188:191], v[90:93]
	v_mfma_f32_16x16x32_bf16 v[86:89], v[164:167], v[188:191], v[86:89]
	v_mfma_f32_16x16x32_bf16 v[74:77], v[156:159], v[196:199], v[74:77]
	v_mfma_f32_16x16x32_bf16 v[70:73], v[164:167], v[196:199], v[70:73]
	v_mfma_f32_16x16x32_bf16 v[122:125], v[160:163], v[176:179], v[122:125]
	v_mfma_f32_16x16x32_bf16 v[118:121], v[168:171], v[176:179], v[118:121]
	v_mfma_f32_16x16x32_bf16 v[106:109], v[160:163], v[184:187], v[106:109]
	v_mfma_f32_16x16x32_bf16 v[102:105], v[168:171], v[184:187], v[102:105]
	v_mfma_f32_16x16x32_bf16 v[90:93], v[160:163], v[192:195], v[90:93]
	v_mfma_f32_16x16x32_bf16 v[86:89], v[168:171], v[192:195], v[86:89]
	v_mfma_f32_16x16x32_bf16 v[74:77], v[160:163], v[200:203], v[74:77]
	v_mfma_f32_16x16x32_bf16 v[70:73], v[168:171], v[200:203], v[70:73]
	s_setprio 0
	s_barrier
	s_add_i32 s65, s65, s46
	s_mov_b32 m0, s65
	ds_read_b128 v[172:175], v5 offset:16384
	ds_read_b128 v[176:179], v5 offset:17408
	ds_read_b128 v[180:183], v5 offset:18432
	ds_read_b128 v[184:187], v5 offset:19456
	ds_read_b128 v[188:191], v5 offset:20480
	ds_read_b128 v[192:195], v5 offset:21504
	ds_read_b128 v[196:199], v5 offset:22528
	ds_read_b128 v[200:203], v5 offset:23552
	global_load_lds_dwordx4 v134, s[40:41]
	s_add_i32 m0, s65, 0x2000
	s_add_i32 s65, s68, s46
	global_load_lds_dwordx4 v138, s[40:41]
	s_add_u32 s40, s40, 0x40000
	s_addc_u32 s41, s41, 0
	s_mov_b32 m0, s65
	s_nop 0
	global_load_lds_dwordx4 v134, s[40:41]
	s_add_i32 m0, s65, 0x2000
	s_nop 0
	global_load_lds_dwordx4 v138, s[40:41]
	s_mov_b32 m0, s29
	s_nop 0
	global_load_lds_dwordx4 v2, s[38:39]
	s_mov_b32 m0, s51
	s_nop 0
	global_load_lds_dwordx4 v136, s[38:39]
	s_waitcnt vmcnt(8)
	s_waitcnt lgkmcnt(0)
	s_barrier
	s_setprio 1
	v_mfma_f32_16x16x32_bf16 v[66:69], v[140:143], v[172:175], v[66:69]
	v_mfma_f32_16x16x32_bf16 v[62:65], v[148:151], v[172:175], v[62:65]
	v_mfma_f32_16x16x32_bf16 v[50:53], v[140:143], v[180:183], v[50:53]
	v_mfma_f32_16x16x32_bf16 v[46:49], v[148:151], v[180:183], v[46:49]
	v_mfma_f32_16x16x32_bf16 v[34:37], v[140:143], v[188:191], v[34:37]
	v_mfma_f32_16x16x32_bf16 v[30:33], v[148:151], v[188:191], v[30:33]
	v_mfma_f32_16x16x32_bf16 v[18:21], v[140:143], v[196:199], v[18:21]
	v_mfma_f32_16x16x32_bf16 v[14:17], v[148:151], v[196:199], v[14:17]
	v_mfma_f32_16x16x32_bf16 v[66:69], v[144:147], v[176:179], v[66:69]
	v_mfma_f32_16x16x32_bf16 v[62:65], v[152:155], v[176:179], v[62:65]
	v_mfma_f32_16x16x32_bf16 v[50:53], v[144:147], v[184:187], v[50:53]
	v_mfma_f32_16x16x32_bf16 v[46:49], v[152:155], v[184:187], v[46:49]
	v_mfma_f32_16x16x32_bf16 v[34:37], v[144:147], v[192:195], v[34:37]
	v_mfma_f32_16x16x32_bf16 v[30:33], v[152:155], v[192:195], v[30:33]
	v_mfma_f32_16x16x32_bf16 v[18:21], v[144:147], v[200:203], v[18:21]
	v_mfma_f32_16x16x32_bf16 v[14:17], v[152:155], v[200:203], v[14:17]
	s_setprio 0
	s_setprio 1
	v_mfma_f32_16x16x32_bf16 v[58:61], v[156:159], v[172:175], v[58:61]
	v_mfma_f32_16x16x32_bf16 v[54:57], v[164:167], v[172:175], v[54:57]
	v_mfma_f32_16x16x32_bf16 v[42:45], v[156:159], v[180:183], v[42:45]
	v_mfma_f32_16x16x32_bf16 v[38:41], v[164:167], v[180:183], v[38:41]
	v_mfma_f32_16x16x32_bf16 v[26:29], v[156:159], v[188:191], v[26:29]
	v_mfma_f32_16x16x32_bf16 v[22:25], v[164:167], v[188:191], v[22:25]
	v_mfma_f32_16x16x32_bf16 v[10:13], v[156:159], v[196:199], v[10:13]
	v_mfma_f32_16x16x32_bf16 v[6:9], v[164:167], v[196:199], v[6:9]
	v_mfma_f32_16x16x32_bf16 v[58:61], v[160:163], v[176:179], v[58:61]
	v_mfma_f32_16x16x32_bf16 v[54:57], v[168:171], v[176:179], v[54:57]
	v_mfma_f32_16x16x32_bf16 v[42:45], v[160:163], v[184:187], v[42:45]
	v_mfma_f32_16x16x32_bf16 v[38:41], v[168:171], v[184:187], v[38:41]
	v_mfma_f32_16x16x32_bf16 v[26:29], v[160:163], v[192:195], v[26:29]
	v_mfma_f32_16x16x32_bf16 v[22:25], v[168:171], v[192:195], v[22:25]
	v_mfma_f32_16x16x32_bf16 v[10:13], v[160:163], v[200:203], v[10:13]
	v_mfma_f32_16x16x32_bf16 v[6:9], v[168:171], v[200:203], v[6:9]
	s_setprio 0
	s_barrier
	s_add_i32 s40, 0, 0x18000
	s_add_i32 s41, 0, 0x1c000
	v_add_u32_e32 v152, s40, v1
	v_add_u32_e32 v168, s41, v1
	ds_read_b128 v[140:143], v152
	ds_read_b128 v[144:147], v152 offset:1024
	ds_read_b128 v[148:151], v152 offset:2048
	ds_read_b128 v[152:155], v152 offset:3072
	ds_read_b128 v[156:159], v168
	ds_read_b128 v[160:163], v168 offset:1024
	ds_read_b128 v[164:167], v168 offset:2048
	ds_read_b128 v[168:171], v168 offset:3072
	s_add_u32 s38, s38, 0x40000
	s_addc_u32 s39, s39, 0
	s_mov_b32 m0, s52
	ds_read_b128 v[172:175], v5 offset:32768
	ds_read_b128 v[176:179], v5 offset:33792
	ds_read_b128 v[180:183], v5 offset:34816
	ds_read_b128 v[184:187], v5 offset:35840
	ds_read_b128 v[188:191], v5 offset:36864
	ds_read_b128 v[192:195], v5 offset:37888
	ds_read_b128 v[196:199], v5 offset:38912
	ds_read_b128 v[200:203], v5 offset:39936
	global_load_lds_dwordx4 v2, s[38:39]
	s_mov_b32 m0, s53
	s_nop 0
	global_load_lds_dwordx4 v136, s[38:39]
	s_waitcnt vmcnt(8)
	s_waitcnt lgkmcnt(0)
	s_barrier
	s_setprio 1
	v_mfma_f32_16x16x32_bf16 v[130:133], v[140:143], v[172:175], v[130:133]
	v_mfma_f32_16x16x32_bf16 v[126:129], v[148:151], v[172:175], v[126:129]
	v_mfma_f32_16x16x32_bf16 v[114:117], v[140:143], v[180:183], v[114:117]
	v_mfma_f32_16x16x32_bf16 v[110:113], v[148:151], v[180:183], v[110:113]
	v_mfma_f32_16x16x32_bf16 v[98:101], v[140:143], v[188:191], v[98:101]
	v_mfma_f32_16x16x32_bf16 v[94:97], v[148:151], v[188:191], v[94:97]
	v_mfma_f32_16x16x32_bf16 v[82:85], v[140:143], v[196:199], v[82:85]
	v_mfma_f32_16x16x32_bf16 v[78:81], v[148:151], v[196:199], v[78:81]
	v_mfma_f32_16x16x32_bf16 v[130:133], v[144:147], v[176:179], v[130:133]
	v_mfma_f32_16x16x32_bf16 v[126:129], v[152:155], v[176:179], v[126:129]
	v_mfma_f32_16x16x32_bf16 v[114:117], v[144:147], v[184:187], v[114:117]
	v_mfma_f32_16x16x32_bf16 v[110:113], v[152:155], v[184:187], v[110:113]
	v_mfma_f32_16x16x32_bf16 v[98:101], v[144:147], v[192:195], v[98:101]
	v_mfma_f32_16x16x32_bf16 v[94:97], v[152:155], v[192:195], v[94:97]
	v_mfma_f32_16x16x32_bf16 v[82:85], v[144:147], v[200:203], v[82:85]
	v_mfma_f32_16x16x32_bf16 v[78:81], v[152:155], v[200:203], v[78:81]
	s_setprio 0
	s_setprio 1
	v_mfma_f32_16x16x32_bf16 v[122:125], v[156:159], v[172:175], v[122:125]
	v_mfma_f32_16x16x32_bf16 v[118:121], v[164:167], v[172:175], v[118:121]
	v_mfma_f32_16x16x32_bf16 v[106:109], v[156:159], v[180:183], v[106:109]
	v_mfma_f32_16x16x32_bf16 v[102:105], v[164:167], v[180:183], v[102:105]
	v_mfma_f32_16x16x32_bf16 v[90:93], v[156:159], v[188:191], v[90:93]
	v_mfma_f32_16x16x32_bf16 v[86:89], v[164:167], v[188:191], v[86:89]
	v_mfma_f32_16x16x32_bf16 v[74:77], v[156:159], v[196:199], v[74:77]
	v_mfma_f32_16x16x32_bf16 v[70:73], v[164:167], v[196:199], v[70:73]
	v_mfma_f32_16x16x32_bf16 v[122:125], v[160:163], v[176:179], v[122:125]
	v_mfma_f32_16x16x32_bf16 v[118:121], v[168:171], v[176:179], v[118:121]
	v_mfma_f32_16x16x32_bf16 v[106:109], v[160:163], v[184:187], v[106:109]
	v_mfma_f32_16x16x32_bf16 v[102:105], v[168:171], v[184:187], v[102:105]
	v_mfma_f32_16x16x32_bf16 v[90:93], v[160:163], v[192:195], v[90:93]
	v_mfma_f32_16x16x32_bf16 v[86:89], v[168:171], v[192:195], v[86:89]
	v_mfma_f32_16x16x32_bf16 v[74:77], v[160:163], v[200:203], v[74:77]
	v_mfma_f32_16x16x32_bf16 v[70:73], v[168:171], v[200:203], v[70:73]
	s_setprio 0
	s_barrier
	s_add_i32 s38, s40, s46
	s_mov_b32 m0, s38
	ds_read_b128 v[172:175], v5 offset:49152
	ds_read_b128 v[176:179], v5 offset:50176
	ds_read_b128 v[180:183], v5 offset:51200
	ds_read_b128 v[184:187], v5 offset:52224
	ds_read_b128 v[188:191], v5 offset:53248
	ds_read_b128 v[192:195], v5 offset:54272
	ds_read_b128 v[196:199], v5 offset:55296
	ds_read_b128 v[200:203], v5 offset:56320
	global_load_lds_dwordx4 v134, s[36:37]
	s_add_i32 m0, s38, 0x2000
	s_add_i32 s38, s41, s46
	global_load_lds_dwordx4 v138, s[36:37]
	s_add_u32 s36, s36, 0x40000
	s_addc_u32 s37, s37, 0
	s_mov_b32 m0, s38
	s_nop 0
	global_load_lds_dwordx4 v134, s[36:37]
	s_add_i32 m0, s38, 0x2000
	s_nop 0
	global_load_lds_dwordx4 v138, s[36:37]
	s_mov_b32 m0, s56
	s_nop 0
	global_load_lds_dwordx4 v2, s[34:35]
	s_mov_b32 m0, s57
	s_nop 0
	global_load_lds_dwordx4 v136, s[34:35]
	s_waitcnt vmcnt(8)
	s_waitcnt lgkmcnt(0)
	s_barrier
	s_setprio 1
	v_mfma_f32_16x16x32_bf16 v[66:69], v[140:143], v[172:175], v[66:69]
	v_mfma_f32_16x16x32_bf16 v[62:65], v[148:151], v[172:175], v[62:65]
	v_mfma_f32_16x16x32_bf16 v[50:53], v[140:143], v[180:183], v[50:53]
	v_mfma_f32_16x16x32_bf16 v[46:49], v[148:151], v[180:183], v[46:49]
	v_mfma_f32_16x16x32_bf16 v[34:37], v[140:143], v[188:191], v[34:37]
	v_mfma_f32_16x16x32_bf16 v[30:33], v[148:151], v[188:191], v[30:33]
	v_mfma_f32_16x16x32_bf16 v[18:21], v[140:143], v[196:199], v[18:21]
	v_mfma_f32_16x16x32_bf16 v[14:17], v[148:151], v[196:199], v[14:17]
	v_mfma_f32_16x16x32_bf16 v[66:69], v[144:147], v[176:179], v[66:69]
	v_mfma_f32_16x16x32_bf16 v[62:65], v[152:155], v[176:179], v[62:65]
	v_mfma_f32_16x16x32_bf16 v[50:53], v[144:147], v[184:187], v[50:53]
	v_mfma_f32_16x16x32_bf16 v[46:49], v[152:155], v[184:187], v[46:49]
	v_mfma_f32_16x16x32_bf16 v[34:37], v[144:147], v[192:195], v[34:37]
	v_mfma_f32_16x16x32_bf16 v[30:33], v[152:155], v[192:195], v[30:33]
	v_mfma_f32_16x16x32_bf16 v[18:21], v[144:147], v[200:203], v[18:21]
	v_mfma_f32_16x16x32_bf16 v[14:17], v[152:155], v[200:203], v[14:17]
	s_setprio 0
	s_setprio 1
	v_mfma_f32_16x16x32_bf16 v[58:61], v[156:159], v[172:175], v[58:61]
	v_mfma_f32_16x16x32_bf16 v[54:57], v[164:167], v[172:175], v[54:57]
	v_mfma_f32_16x16x32_bf16 v[42:45], v[156:159], v[180:183], v[42:45]
	v_mfma_f32_16x16x32_bf16 v[38:41], v[164:167], v[180:183], v[38:41]
	v_mfma_f32_16x16x32_bf16 v[26:29], v[156:159], v[188:191], v[26:29]
	v_mfma_f32_16x16x32_bf16 v[22:25], v[164:167], v[188:191], v[22:25]
	v_mfma_f32_16x16x32_bf16 v[10:13], v[156:159], v[196:199], v[10:13]
	v_mfma_f32_16x16x32_bf16 v[6:9], v[164:167], v[196:199], v[6:9]
	v_mfma_f32_16x16x32_bf16 v[58:61], v[160:163], v[176:179], v[58:61]
	v_mfma_f32_16x16x32_bf16 v[54:57], v[168:171], v[176:179], v[54:57]
	v_mfma_f32_16x16x32_bf16 v[42:45], v[160:163], v[184:187], v[42:45]
	v_mfma_f32_16x16x32_bf16 v[38:41], v[168:171], v[184:187], v[38:41]
	v_mfma_f32_16x16x32_bf16 v[26:29], v[160:163], v[192:195], v[26:29]
	v_mfma_f32_16x16x32_bf16 v[22:25], v[168:171], v[192:195], v[22:25]
	v_mfma_f32_16x16x32_bf16 v[10:13], v[160:163], v[200:203], v[10:13]
	v_mfma_f32_16x16x32_bf16 v[6:9], v[168:171], v[200:203], v[6:9]
	s_setprio 0
	s_barrier
	s_add_i32 s64, s64, 2
	s_add_u32 s33, s33, 0x100
	s_addc_u32 s61, s61, 0
	s_add_u32 s62, s62, 0x100
	s_addc_u32 s63, s63, 0
	s_cmp_gt_u32 s64, 13
	s_cbranch_scc0 .LBB0_454
	s_and_b64 vcc, exec, s[8:9]
	s_cbranch_vccz .LBB0_457
	s_barrier

.LBB0_480:
	s_add_u32 s58, s54, 0xffffff80
	s_addc_u32 s59, s55, -1
	s_cmp_eq_u32 s56, 4
	s_cselect_b32 s30, s25, s54
	s_cselect_b32 s31, s15, s55
	s_cselect_b32 s35, s17, s53
	s_cselect_b32 s34, s33, s52
	s_add_u32 s26, s30, 0x80
	s_addc_u32 s27, s31, 0
	s_add_u32 s28, s34, 0x80
	s_addc_u32 s29, s35, 0
	s_add_i32 s57, 0, 0x10000
	s_add_i32 s60, 0, 0x14000
	v_add_u32_e32 v152, s57, v1
	v_add_u32_e32 v168, s60, v1
	ds_read_b128 v[140:143], v152
	ds_read_b128 v[144:147], v152 offset:1024
	ds_read_b128 v[148:151], v152 offset:2048
	ds_read_b128 v[152:155], v152 offset:3072
	ds_read_b128 v[156:159], v168
	ds_read_b128 v[160:163], v168 offset:1024
	ds_read_b128 v[164:167], v168 offset:2048
	ds_read_b128 v[168:171], v168 offset:3072
	s_add_u32 s58, s58, 0x20000
	s_addc_u32 s59, s59, 0
	s_add_i32 m0, s43, 0xc000
	ds_read_b128 v[172:175], v5
	ds_read_b128 v[176:179], v5 offset:1024
	ds_read_b128 v[180:183], v5 offset:2048
	ds_read_b128 v[184:187], v5 offset:3072
	ds_read_b128 v[188:191], v5 offset:4096
	ds_read_b128 v[192:195], v5 offset:5120
	ds_read_b128 v[196:199], v5 offset:6144
	ds_read_b128 v[200:203], v5 offset:7168
	global_load_lds_dwordx4 v2, s[58:59]
	s_add_i32 m0, s43, 0xe000
	s_nop 0
	global_load_lds_dwordx4 v136, s[58:59]
	s_waitcnt vmcnt(8)
	s_waitcnt lgkmcnt(0)
	s_barrier
	s_setprio 1
	v_mfma_f32_16x16x32_bf16 v[130:133], v[140:143], v[172:175], v[130:133]
	v_mfma_f32_16x16x32_bf16 v[126:129], v[148:151], v[172:175], v[126:129]
	v_mfma_f32_16x16x32_bf16 v[114:117], v[140:143], v[180:183], v[114:117]
	v_mfma_f32_16x16x32_bf16 v[110:113], v[148:151], v[180:183], v[110:113]
	v_mfma_f32_16x16x32_bf16 v[98:101], v[140:143], v[188:191], v[98:101]
	v_mfma_f32_16x16x32_bf16 v[94:97], v[148:151], v[188:191], v[94:97]
	v_mfma_f32_16x16x32_bf16 v[82:85], v[140:143], v[196:199], v[82:85]
	v_mfma_f32_16x16x32_bf16 v[78:81], v[148:151], v[196:199], v[78:81]
	v_mfma_f32_16x16x32_bf16 v[130:133], v[144:147], v[176:179], v[130:133]
	v_mfma_f32_16x16x32_bf16 v[126:129], v[152:155], v[176:179], v[126:129]
	v_mfma_f32_16x16x32_bf16 v[114:117], v[144:147], v[184:187], v[114:117]
	v_mfma_f32_16x16x32_bf16 v[110:113], v[152:155], v[184:187], v[110:113]
	v_mfma_f32_16x16x32_bf16 v[98:101], v[144:147], v[192:195], v[98:101]
	v_mfma_f32_16x16x32_bf16 v[94:97], v[152:155], v[192:195], v[94:97]
	v_mfma_f32_16x16x32_bf16 v[82:85], v[144:147], v[200:203], v[82:85]
	v_mfma_f32_16x16x32_bf16 v[78:81], v[152:155], v[200:203], v[78:81]
	s_setprio 0
	s_setprio 1
	v_mfma_f32_16x16x32_bf16 v[122:125], v[156:159], v[172:175], v[122:125]
	v_mfma_f32_16x16x32_bf16 v[118:121], v[164:167], v[172:175], v[118:121]
	v_mfma_f32_16x16x32_bf16 v[106:109], v[156:159], v[180:183], v[106:109]
	v_mfma_f32_16x16x32_bf16 v[102:105], v[164:167], v[180:183], v[102:105]
	v_mfma_f32_16x16x32_bf16 v[90:93], v[156:159], v[188:191], v[90:93]
	v_mfma_f32_16x16x32_bf16 v[86:89], v[164:167], v[188:191], v[86:89]
	v_mfma_f32_16x16x32_bf16 v[74:77], v[156:159], v[196:199], v[74:77]
	v_mfma_f32_16x16x32_bf16 v[70:73], v[164:167], v[196:199], v[70:73]
	v_mfma_f32_16x16x32_bf16 v[122:125], v[160:163], v[176:179], v[122:125]
	v_mfma_f32_16x16x32_bf16 v[118:121], v[168:171], v[176:179], v[118:121]
	v_mfma_f32_16x16x32_bf16 v[106:109], v[160:163], v[184:187], v[106:109]
	v_mfma_f32_16x16x32_bf16 v[102:105], v[168:171], v[184:187], v[102:105]
	v_mfma_f32_16x16x32_bf16 v[90:93], v[160:163], v[192:195], v[90:93]
	v_mfma_f32_16x16x32_bf16 v[86:89], v[168:171], v[192:195], v[86:89]
	v_mfma_f32_16x16x32_bf16 v[74:77], v[160:163], v[200:203], v[74:77]
	v_mfma_f32_16x16x32_bf16 v[70:73], v[168:171], v[200:203], v[70:73]
	s_setprio 0
	s_barrier
	s_add_i32 s57, s57, s42
	s_mov_b32 m0, s57
	ds_read_b128 v[172:175], v5 offset:16384
	ds_read_b128 v[176:179], v5 offset:17408
	ds_read_b128 v[180:183], v5 offset:18432
	ds_read_b128 v[184:187], v5 offset:19456
	ds_read_b128 v[188:191], v5 offset:20480
	ds_read_b128 v[192:195], v5 offset:21504
	ds_read_b128 v[196:199], v5 offset:22528
	ds_read_b128 v[200:203], v5 offset:23552
	global_load_lds_dwordx4 v134, s[34:35]
	s_add_i32 m0, s57, 0x2000
	s_add_i32 s57, s60, s42
	global_load_lds_dwordx4 v138, s[34:35]
	s_add_u32 s34, s34, 0x20000
	s_addc_u32 s35, s35, 0
	s_mov_b32 m0, s57
	s_nop 0
	global_load_lds_dwordx4 v134, s[34:35]
	s_add_i32 m0, s57, 0x2000
	s_nop 0
	global_load_lds_dwordx4 v138, s[34:35]
	s_mov_b32 m0, s43
	s_nop 0
	global_load_lds_dwordx4 v2, s[30:31]
	s_mov_b32 m0, s44
	s_nop 0
	global_load_lds_dwordx4 v136, s[30:31]
	s_waitcnt vmcnt(8)
	s_waitcnt lgkmcnt(0)
	s_barrier
	s_setprio 1
	v_mfma_f32_16x16x32_bf16 v[66:69], v[140:143], v[172:175], v[66:69]
	v_mfma_f32_16x16x32_bf16 v[62:65], v[148:151], v[172:175], v[62:65]
	v_mfma_f32_16x16x32_bf16 v[50:53], v[140:143], v[180:183], v[50:53]
	v_mfma_f32_16x16x32_bf16 v[46:49], v[148:151], v[180:183], v[46:49]
	v_mfma_f32_16x16x32_bf16 v[34:37], v[140:143], v[188:191], v[34:37]
	v_mfma_f32_16x16x32_bf16 v[30:33], v[148:151], v[188:191], v[30:33]
	v_mfma_f32_16x16x32_bf16 v[18:21], v[140:143], v[196:199], v[18:21]
	v_mfma_f32_16x16x32_bf16 v[14:17], v[148:151], v[196:199], v[14:17]
	v_mfma_f32_16x16x32_bf16 v[66:69], v[144:147], v[176:179], v[66:69]
	v_mfma_f32_16x16x32_bf16 v[62:65], v[152:155], v[176:179], v[62:65]
	v_mfma_f32_16x16x32_bf16 v[50:53], v[144:147], v[184:187], v[50:53]
	v_mfma_f32_16x16x32_bf16 v[46:49], v[152:155], v[184:187], v[46:49]
	v_mfma_f32_16x16x32_bf16 v[34:37], v[144:147], v[192:195], v[34:37]
	v_mfma_f32_16x16x32_bf16 v[30:33], v[152:155], v[192:195], v[30:33]
	v_mfma_f32_16x16x32_bf16 v[18:21], v[144:147], v[200:203], v[18:21]
	v_mfma_f32_16x16x32_bf16 v[14:17], v[152:155], v[200:203], v[14:17]
	s_setprio 0
	s_setprio 1
	v_mfma_f32_16x16x32_bf16 v[58:61], v[156:159], v[172:175], v[58:61]
	v_mfma_f32_16x16x32_bf16 v[54:57], v[164:167], v[172:175], v[54:57]
	v_mfma_f32_16x16x32_bf16 v[42:45], v[156:159], v[180:183], v[42:45]
	v_mfma_f32_16x16x32_bf16 v[38:41], v[164:167], v[180:183], v[38:41]
	v_mfma_f32_16x16x32_bf16 v[26:29], v[156:159], v[188:191], v[26:29]
	v_mfma_f32_16x16x32_bf16 v[22:25], v[164:167], v[188:191], v[22:25]
	v_mfma_f32_16x16x32_bf16 v[10:13], v[156:159], v[196:199], v[10:13]
	v_mfma_f32_16x16x32_bf16 v[6:9], v[164:167], v[196:199], v[6:9]
	v_mfma_f32_16x16x32_bf16 v[58:61], v[160:163], v[176:179], v[58:61]
	v_mfma_f32_16x16x32_bf16 v[54:57], v[168:171], v[176:179], v[54:57]
	v_mfma_f32_16x16x32_bf16 v[42:45], v[160:163], v[184:187], v[42:45]
	v_mfma_f32_16x16x32_bf16 v[38:41], v[168:171], v[184:187], v[38:41]
	v_mfma_f32_16x16x32_bf16 v[26:29], v[160:163], v[192:195], v[26:29]
	v_mfma_f32_16x16x32_bf16 v[22:25], v[168:171], v[192:195], v[22:25]
	v_mfma_f32_16x16x32_bf16 v[10:13], v[160:163], v[200:203], v[10:13]
	v_mfma_f32_16x16x32_bf16 v[6:9], v[168:171], v[200:203], v[6:9]
	s_setprio 0
	s_barrier
	s_add_i32 s34, 0, 0x18000
	s_add_i32 s35, 0, 0x1c000
	v_add_u32_e32 v152, s34, v1
	v_add_u32_e32 v168, s35, v1
	ds_read_b128 v[140:143], v152
	ds_read_b128 v[144:147], v152 offset:1024
	ds_read_b128 v[148:151], v152 offset:2048
	ds_read_b128 v[152:155], v152 offset:3072
	ds_read_b128 v[156:159], v168
	ds_read_b128 v[160:163], v168 offset:1024
	ds_read_b128 v[164:167], v168 offset:2048
	ds_read_b128 v[168:171], v168 offset:3072
	s_add_u32 s30, s30, 0x20000
	s_addc_u32 s31, s31, 0
	s_mov_b32 m0, s45
	ds_read_b128 v[172:175], v5 offset:32768
	ds_read_b128 v[176:179], v5 offset:33792
	ds_read_b128 v[180:183], v5 offset:34816
	ds_read_b128 v[184:187], v5 offset:35840
	ds_read_b128 v[188:191], v5 offset:36864
	ds_read_b128 v[192:195], v5 offset:37888
	ds_read_b128 v[196:199], v5 offset:38912
	ds_read_b128 v[200:203], v5 offset:39936
	global_load_lds_dwordx4 v2, s[30:31]
	s_mov_b32 m0, s46
	s_nop 0
	global_load_lds_dwordx4 v136, s[30:31]
	s_waitcnt vmcnt(8)
	s_waitcnt lgkmcnt(0)
	s_barrier
	s_setprio 1
	v_mfma_f32_16x16x32_bf16 v[130:133], v[140:143], v[172:175], v[130:133]
	v_mfma_f32_16x16x32_bf16 v[126:129], v[148:151], v[172:175], v[126:129]
	v_mfma_f32_16x16x32_bf16 v[114:117], v[140:143], v[180:183], v[114:117]
	v_mfma_f32_16x16x32_bf16 v[110:113], v[148:151], v[180:183], v[110:113]
	v_mfma_f32_16x16x32_bf16 v[98:101], v[140:143], v[188:191], v[98:101]
	v_mfma_f32_16x16x32_bf16 v[94:97], v[148:151], v[188:191], v[94:97]
	v_mfma_f32_16x16x32_bf16 v[82:85], v[140:143], v[196:199], v[82:85]
	v_mfma_f32_16x16x32_bf16 v[78:81], v[148:151], v[196:199], v[78:81]
	v_mfma_f32_16x16x32_bf16 v[130:133], v[144:147], v[176:179], v[130:133]
	v_mfma_f32_16x16x32_bf16 v[126:129], v[152:155], v[176:179], v[126:129]
	v_mfma_f32_16x16x32_bf16 v[114:117], v[144:147], v[184:187], v[114:117]
	v_mfma_f32_16x16x32_bf16 v[110:113], v[152:155], v[184:187], v[110:113]
	v_mfma_f32_16x16x32_bf16 v[98:101], v[144:147], v[192:195], v[98:101]
	v_mfma_f32_16x16x32_bf16 v[94:97], v[152:155], v[192:195], v[94:97]
	v_mfma_f32_16x16x32_bf16 v[82:85], v[144:147], v[200:203], v[82:85]
	v_mfma_f32_16x16x32_bf16 v[78:81], v[152:155], v[200:203], v[78:81]
	s_setprio 0
	s_setprio 1
	v_mfma_f32_16x16x32_bf16 v[122:125], v[156:159], v[172:175], v[122:125]
	v_mfma_f32_16x16x32_bf16 v[118:121], v[164:167], v[172:175], v[118:121]
	v_mfma_f32_16x16x32_bf16 v[106:109], v[156:159], v[180:183], v[106:109]
	v_mfma_f32_16x16x32_bf16 v[102:105], v[164:167], v[180:183], v[102:105]
	v_mfma_f32_16x16x32_bf16 v[90:93], v[156:159], v[188:191], v[90:93]
	v_mfma_f32_16x16x32_bf16 v[86:89], v[164:167], v[188:191], v[86:89]
	v_mfma_f32_16x16x32_bf16 v[74:77], v[156:159], v[196:199], v[74:77]
	v_mfma_f32_16x16x32_bf16 v[70:73], v[164:167], v[196:199], v[70:73]
	v_mfma_f32_16x16x32_bf16 v[122:125], v[160:163], v[176:179], v[122:125]
	v_mfma_f32_16x16x32_bf16 v[118:121], v[168:171], v[176:179], v[118:121]
	v_mfma_f32_16x16x32_bf16 v[106:109], v[160:163], v[184:187], v[106:109]
	v_mfma_f32_16x16x32_bf16 v[102:105], v[168:171], v[184:187], v[102:105]
	v_mfma_f32_16x16x32_bf16 v[90:93], v[160:163], v[192:195], v[90:93]
	v_mfma_f32_16x16x32_bf16 v[86:89], v[168:171], v[192:195], v[86:89]
	v_mfma_f32_16x16x32_bf16 v[74:77], v[160:163], v[200:203], v[74:77]
	v_mfma_f32_16x16x32_bf16 v[70:73], v[168:171], v[200:203], v[70:73]
	s_setprio 0
	s_barrier
	s_add_i32 s30, s34, s42
	s_mov_b32 m0, s30
	ds_read_b128 v[172:175], v5 offset:49152
	ds_read_b128 v[176:179], v5 offset:50176
	ds_read_b128 v[180:183], v5 offset:51200
	ds_read_b128 v[184:187], v5 offset:52224
	ds_read_b128 v[188:191], v5 offset:53248
	ds_read_b128 v[192:195], v5 offset:54272
	ds_read_b128 v[196:199], v5 offset:55296
	ds_read_b128 v[200:203], v5 offset:56320
	global_load_lds_dwordx4 v134, s[28:29]
	s_add_i32 m0, s30, 0x2000
	s_add_i32 s30, s35, s42
	global_load_lds_dwordx4 v138, s[28:29]
	s_add_u32 s28, s28, 0x20000
	s_addc_u32 s29, s29, 0
	s_mov_b32 m0, s30
	s_nop 0
	global_load_lds_dwordx4 v134, s[28:29]
	s_add_i32 m0, s30, 0x2000
	s_nop 0
	global_load_lds_dwordx4 v138, s[28:29]
	s_mov_b32 m0, s49
	s_nop 0
	global_load_lds_dwordx4 v2, s[26:27]
	s_mov_b32 m0, s50
	s_nop 0
	global_load_lds_dwordx4 v136, s[26:27]
	s_waitcnt vmcnt(8)
	s_waitcnt lgkmcnt(0)
	s_barrier
	s_setprio 1
	v_mfma_f32_16x16x32_bf16 v[66:69], v[140:143], v[172:175], v[66:69]
	v_mfma_f32_16x16x32_bf16 v[62:65], v[148:151], v[172:175], v[62:65]
	v_mfma_f32_16x16x32_bf16 v[50:53], v[140:143], v[180:183], v[50:53]
	v_mfma_f32_16x16x32_bf16 v[46:49], v[148:151], v[180:183], v[46:49]
	v_mfma_f32_16x16x32_bf16 v[34:37], v[140:143], v[188:191], v[34:37]
	v_mfma_f32_16x16x32_bf16 v[30:33], v[148:151], v[188:191], v[30:33]
	v_mfma_f32_16x16x32_bf16 v[18:21], v[140:143], v[196:199], v[18:21]
	v_mfma_f32_16x16x32_bf16 v[14:17], v[148:151], v[196:199], v[14:17]
	v_mfma_f32_16x16x32_bf16 v[66:69], v[144:147], v[176:179], v[66:69]
	v_mfma_f32_16x16x32_bf16 v[62:65], v[152:155], v[176:179], v[62:65]
	v_mfma_f32_16x16x32_bf16 v[50:53], v[144:147], v[184:187], v[50:53]
	v_mfma_f32_16x16x32_bf16 v[46:49], v[152:155], v[184:187], v[46:49]
	v_mfma_f32_16x16x32_bf16 v[34:37], v[144:147], v[192:195], v[34:37]
	v_mfma_f32_16x16x32_bf16 v[30:33], v[152:155], v[192:195], v[30:33]
	v_mfma_f32_16x16x32_bf16 v[18:21], v[144:147], v[200:203], v[18:21]
	v_mfma_f32_16x16x32_bf16 v[14:17], v[152:155], v[200:203], v[14:17]
	s_setprio 0
	s_setprio 1
	v_mfma_f32_16x16x32_bf16 v[58:61], v[156:159], v[172:175], v[58:61]
	v_mfma_f32_16x16x32_bf16 v[54:57], v[164:167], v[172:175], v[54:57]
	v_mfma_f32_16x16x32_bf16 v[42:45], v[156:159], v[180:183], v[42:45]
	v_mfma_f32_16x16x32_bf16 v[38:41], v[164:167], v[180:183], v[38:41]
	v_mfma_f32_16x16x32_bf16 v[26:29], v[156:159], v[188:191], v[26:29]
	v_mfma_f32_16x16x32_bf16 v[22:25], v[164:167], v[188:191], v[22:25]
	v_mfma_f32_16x16x32_bf16 v[10:13], v[156:159], v[196:199], v[10:13]
	v_mfma_f32_16x16x32_bf16 v[6:9], v[164:167], v[196:199], v[6:9]
	v_mfma_f32_16x16x32_bf16 v[58:61], v[160:163], v[176:179], v[58:61]
	v_mfma_f32_16x16x32_bf16 v[54:57], v[168:171], v[176:179], v[54:57]
	v_mfma_f32_16x16x32_bf16 v[42:45], v[160:163], v[184:187], v[42:45]
	v_mfma_f32_16x16x32_bf16 v[38:41], v[168:171], v[184:187], v[38:41]
	v_mfma_f32_16x16x32_bf16 v[26:29], v[160:163], v[192:195], v[26:29]
	v_mfma_f32_16x16x32_bf16 v[22:25], v[168:171], v[192:195], v[22:25]
	v_mfma_f32_16x16x32_bf16 v[10:13], v[160:163], v[200:203], v[10:13]
	v_mfma_f32_16x16x32_bf16 v[6:9], v[168:171], v[200:203], v[6:9]
	s_setprio 0
	s_barrier
	s_add_i32 s56, s56, 2
	s_add_u32 s52, s52, 0x100
	s_addc_u32 s53, s53, 0
	s_add_u32 s54, s54, 0x100
	s_addc_u32 s55, s55, 0
	s_cmp_gt_u32 s56, 5
	s_cbranch_scc0 .LBB0_480
	s_and_b64 vcc, exec, s[8:9]
	s_cbranch_vccz .LBB0_483
	s_barrier

.LBB0_536:
	s_add_u32 s48, s45, 0xffffff80
	s_addc_u32 s49, s46, -1
	s_cmp_eq_u32 s47, 4
	s_cselect_b32 s22, s41, s45
	s_cselect_b32 s23, s7, s46
	s_cselect_b32 s25, s9, s44
	s_cselect_b32 s24, s42, s43
	s_add_u32 s18, s22, 0x80
	s_addc_u32 s19, s23, 0
	s_add_u32 s20, s24, 0x80
	s_addc_u32 s21, s25, 0
	s_add_i32 s50, 0, 0x10000
	s_add_i32 s51, 0, 0x14000
	v_add_u32_e32 v152, s50, v1
	v_add_u32_e32 v168, s51, v1
	ds_read_b128 v[140:143], v152
	ds_read_b128 v[144:147], v152 offset:1024
	ds_read_b128 v[148:151], v152 offset:2048
	ds_read_b128 v[152:155], v152 offset:3072
	ds_read_b128 v[156:159], v168
	ds_read_b128 v[160:163], v168 offset:1024
	ds_read_b128 v[164:167], v168 offset:2048
	ds_read_b128 v[168:171], v168 offset:3072
	s_add_u32 s48, s48, 0x20000
	s_addc_u32 s49, s49, 0
	s_add_i32 m0, s15, 0xc000
	ds_read_b128 v[172:175], v5
	ds_read_b128 v[176:179], v5 offset:1024
	ds_read_b128 v[180:183], v5 offset:2048
	ds_read_b128 v[184:187], v5 offset:3072
	ds_read_b128 v[188:191], v5 offset:4096
	ds_read_b128 v[192:195], v5 offset:5120
	ds_read_b128 v[196:199], v5 offset:6144
	ds_read_b128 v[200:203], v5 offset:7168
	global_load_lds_dwordx4 v2, s[48:49]
	s_add_i32 m0, s15, 0xe000
	s_nop 0
	global_load_lds_dwordx4 v136, s[48:49]
	s_waitcnt vmcnt(8)
	s_waitcnt lgkmcnt(0)
	s_barrier
	s_setprio 1
	v_mfma_f32_16x16x32_bf16 v[130:133], v[140:143], v[172:175], v[130:133]
	v_mfma_f32_16x16x32_bf16 v[126:129], v[148:151], v[172:175], v[126:129]
	v_mfma_f32_16x16x32_bf16 v[122:125], v[140:143], v[180:183], v[122:125]
	v_mfma_f32_16x16x32_bf16 v[114:117], v[148:151], v[180:183], v[114:117]
	v_mfma_f32_16x16x32_bf16 v[106:109], v[140:143], v[188:191], v[106:109]
	v_mfma_f32_16x16x32_bf16 v[98:101], v[148:151], v[188:191], v[98:101]
	v_mfma_f32_16x16x32_bf16 v[90:93], v[140:143], v[196:199], v[90:93]
	v_mfma_f32_16x16x32_bf16 v[82:85], v[148:151], v[196:199], v[82:85]
	v_mfma_f32_16x16x32_bf16 v[130:133], v[144:147], v[176:179], v[130:133]
	v_mfma_f32_16x16x32_bf16 v[126:129], v[152:155], v[176:179], v[126:129]
	v_mfma_f32_16x16x32_bf16 v[122:125], v[144:147], v[184:187], v[122:125]
	v_mfma_f32_16x16x32_bf16 v[114:117], v[152:155], v[184:187], v[114:117]
	v_mfma_f32_16x16x32_bf16 v[106:109], v[144:147], v[192:195], v[106:109]
	v_mfma_f32_16x16x32_bf16 v[98:101], v[152:155], v[192:195], v[98:101]
	v_mfma_f32_16x16x32_bf16 v[90:93], v[144:147], v[200:203], v[90:93]
	v_mfma_f32_16x16x32_bf16 v[82:85], v[152:155], v[200:203], v[82:85]
	s_setprio 0
	s_setprio 1
	v_mfma_f32_16x16x32_bf16 v[118:121], v[156:159], v[172:175], v[118:121]
	v_mfma_f32_16x16x32_bf16 v[110:113], v[164:167], v[172:175], v[110:113]
	v_mfma_f32_16x16x32_bf16 v[102:105], v[156:159], v[180:183], v[102:105]
	v_mfma_f32_16x16x32_bf16 v[94:97], v[164:167], v[180:183], v[94:97]
	v_mfma_f32_16x16x32_bf16 v[86:89], v[156:159], v[188:191], v[86:89]
	v_mfma_f32_16x16x32_bf16 v[78:81], v[164:167], v[188:191], v[78:81]
	v_mfma_f32_16x16x32_bf16 v[74:77], v[156:159], v[196:199], v[74:77]
	v_mfma_f32_16x16x32_bf16 v[70:73], v[164:167], v[196:199], v[70:73]
	v_mfma_f32_16x16x32_bf16 v[118:121], v[160:163], v[176:179], v[118:121]
	v_mfma_f32_16x16x32_bf16 v[110:113], v[168:171], v[176:179], v[110:113]
	v_mfma_f32_16x16x32_bf16 v[102:105], v[160:163], v[184:187], v[102:105]
	v_mfma_f32_16x16x32_bf16 v[94:97], v[168:171], v[184:187], v[94:97]
	v_mfma_f32_16x16x32_bf16 v[86:89], v[160:163], v[192:195], v[86:89]
	v_mfma_f32_16x16x32_bf16 v[78:81], v[168:171], v[192:195], v[78:81]
	v_mfma_f32_16x16x32_bf16 v[74:77], v[160:163], v[200:203], v[74:77]
	v_mfma_f32_16x16x32_bf16 v[70:73], v[168:171], v[200:203], v[70:73]
	s_setprio 0
	s_barrier
	s_add_i32 s48, s50, s29
	s_mov_b32 m0, s48
	ds_read_b128 v[172:175], v5 offset:16384
	ds_read_b128 v[176:179], v5 offset:17408
	ds_read_b128 v[180:183], v5 offset:18432
	ds_read_b128 v[184:187], v5 offset:19456
	ds_read_b128 v[188:191], v5 offset:20480
	ds_read_b128 v[192:195], v5 offset:21504
	ds_read_b128 v[196:199], v5 offset:22528
	ds_read_b128 v[200:203], v5 offset:23552
	global_load_lds_dwordx4 v134, s[24:25]
	s_add_i32 m0, s48, 0x2000
	s_add_i32 s48, s51, s29
	global_load_lds_dwordx4 v138, s[24:25]
	s_add_u32 s24, s24, 0x20000
	s_addc_u32 s25, s25, 0
	s_mov_b32 m0, s48
	s_nop 0
	global_load_lds_dwordx4 v134, s[24:25]
	s_add_i32 m0, s48, 0x2000
	s_nop 0
	global_load_lds_dwordx4 v138, s[24:25]
	s_mov_b32 m0, s15
	s_nop 0
	global_load_lds_dwordx4 v2, s[22:23]
	s_mov_b32 m0, s17
	s_nop 0
	global_load_lds_dwordx4 v136, s[22:23]
	s_waitcnt vmcnt(8)
	s_waitcnt lgkmcnt(0)
	s_barrier
	s_setprio 1
	v_mfma_f32_16x16x32_bf16 v[66:69], v[140:143], v[172:175], v[66:69]
	v_mfma_f32_16x16x32_bf16 v[62:65], v[148:151], v[172:175], v[62:65]
	v_mfma_f32_16x16x32_bf16 v[58:61], v[140:143], v[180:183], v[58:61]
	v_mfma_f32_16x16x32_bf16 v[50:53], v[148:151], v[180:183], v[50:53]
	v_mfma_f32_16x16x32_bf16 v[42:45], v[140:143], v[188:191], v[42:45]
	v_mfma_f32_16x16x32_bf16 v[34:37], v[148:151], v[188:191], v[34:37]
	v_mfma_f32_16x16x32_bf16 v[26:29], v[140:143], v[196:199], v[26:29]
	v_mfma_f32_16x16x32_bf16 v[18:21], v[148:151], v[196:199], v[18:21]
	v_mfma_f32_16x16x32_bf16 v[66:69], v[144:147], v[176:179], v[66:69]
	v_mfma_f32_16x16x32_bf16 v[62:65], v[152:155], v[176:179], v[62:65]
	v_mfma_f32_16x16x32_bf16 v[58:61], v[144:147], v[184:187], v[58:61]
	v_mfma_f32_16x16x32_bf16 v[50:53], v[152:155], v[184:187], v[50:53]
	v_mfma_f32_16x16x32_bf16 v[42:45], v[144:147], v[192:195], v[42:45]
	v_mfma_f32_16x16x32_bf16 v[34:37], v[152:155], v[192:195], v[34:37]
	v_mfma_f32_16x16x32_bf16 v[26:29], v[144:147], v[200:203], v[26:29]
	v_mfma_f32_16x16x32_bf16 v[18:21], v[152:155], v[200:203], v[18:21]
	s_setprio 0
	s_setprio 1
	v_mfma_f32_16x16x32_bf16 v[54:57], v[156:159], v[172:175], v[54:57]
	v_mfma_f32_16x16x32_bf16 v[46:49], v[164:167], v[172:175], v[46:49]
	v_mfma_f32_16x16x32_bf16 v[38:41], v[156:159], v[180:183], v[38:41]
	v_mfma_f32_16x16x32_bf16 v[30:33], v[164:167], v[180:183], v[30:33]
	v_mfma_f32_16x16x32_bf16 v[22:25], v[156:159], v[188:191], v[22:25]
	v_mfma_f32_16x16x32_bf16 v[14:17], v[164:167], v[188:191], v[14:17]
	v_mfma_f32_16x16x32_bf16 v[10:13], v[156:159], v[196:199], v[10:13]
	v_mfma_f32_16x16x32_bf16 v[6:9], v[164:167], v[196:199], v[6:9]
	v_mfma_f32_16x16x32_bf16 v[54:57], v[160:163], v[176:179], v[54:57]
	v_mfma_f32_16x16x32_bf16 v[46:49], v[168:171], v[176:179], v[46:49]
	v_mfma_f32_16x16x32_bf16 v[38:41], v[160:163], v[184:187], v[38:41]
	v_mfma_f32_16x16x32_bf16 v[30:33], v[168:171], v[184:187], v[30:33]
	v_mfma_f32_16x16x32_bf16 v[22:25], v[160:163], v[192:195], v[22:25]
	v_mfma_f32_16x16x32_bf16 v[14:17], v[168:171], v[192:195], v[14:17]
	v_mfma_f32_16x16x32_bf16 v[10:13], v[160:163], v[200:203], v[10:13]
	v_mfma_f32_16x16x32_bf16 v[6:9], v[168:171], v[200:203], v[6:9]
	s_setprio 0
	s_barrier
	s_add_i32 s24, 0, 0x18000
	s_add_i32 s25, 0, 0x1c000
	v_add_u32_e32 v152, s24, v1
	v_add_u32_e32 v168, s25, v1
	ds_read_b128 v[140:143], v152
	ds_read_b128 v[144:147], v152 offset:1024
	ds_read_b128 v[148:151], v152 offset:2048
	ds_read_b128 v[152:155], v152 offset:3072
	ds_read_b128 v[156:159], v168
	ds_read_b128 v[160:163], v168 offset:1024
	ds_read_b128 v[164:167], v168 offset:2048
	ds_read_b128 v[168:171], v168 offset:3072
	s_add_u32 s22, s22, 0x20000
	s_addc_u32 s23, s23, 0
	s_mov_b32 m0, s31
	ds_read_b128 v[172:175], v5 offset:32768
	ds_read_b128 v[176:179], v5 offset:33792
	ds_read_b128 v[180:183], v5 offset:34816
	ds_read_b128 v[184:187], v5 offset:35840
	ds_read_b128 v[188:191], v5 offset:36864
	ds_read_b128 v[192:195], v5 offset:37888
	ds_read_b128 v[196:199], v5 offset:38912
	ds_read_b128 v[200:203], v5 offset:39936
	global_load_lds_dwordx4 v2, s[22:23]
	s_mov_b32 m0, s33
	s_nop 0
	global_load_lds_dwordx4 v136, s[22:23]
	s_waitcnt vmcnt(8)
	s_waitcnt lgkmcnt(0)
	s_barrier
	s_setprio 1
	v_mfma_f32_16x16x32_bf16 v[130:133], v[140:143], v[172:175], v[130:133]
	v_mfma_f32_16x16x32_bf16 v[126:129], v[148:151], v[172:175], v[126:129]
	v_mfma_f32_16x16x32_bf16 v[122:125], v[140:143], v[180:183], v[122:125]
	v_mfma_f32_16x16x32_bf16 v[114:117], v[148:151], v[180:183], v[114:117]
	v_mfma_f32_16x16x32_bf16 v[106:109], v[140:143], v[188:191], v[106:109]
	v_mfma_f32_16x16x32_bf16 v[98:101], v[148:151], v[188:191], v[98:101]
	v_mfma_f32_16x16x32_bf16 v[90:93], v[140:143], v[196:199], v[90:93]
	v_mfma_f32_16x16x32_bf16 v[82:85], v[148:151], v[196:199], v[82:85]
	v_mfma_f32_16x16x32_bf16 v[130:133], v[144:147], v[176:179], v[130:133]
	v_mfma_f32_16x16x32_bf16 v[126:129], v[152:155], v[176:179], v[126:129]
	v_mfma_f32_16x16x32_bf16 v[122:125], v[144:147], v[184:187], v[122:125]
	v_mfma_f32_16x16x32_bf16 v[114:117], v[152:155], v[184:187], v[114:117]
	v_mfma_f32_16x16x32_bf16 v[106:109], v[144:147], v[192:195], v[106:109]
	v_mfma_f32_16x16x32_bf16 v[98:101], v[152:155], v[192:195], v[98:101]
	v_mfma_f32_16x16x32_bf16 v[90:93], v[144:147], v[200:203], v[90:93]
	v_mfma_f32_16x16x32_bf16 v[82:85], v[152:155], v[200:203], v[82:85]
	s_setprio 0
	s_setprio 1
	v_mfma_f32_16x16x32_bf16 v[118:121], v[156:159], v[172:175], v[118:121]
	v_mfma_f32_16x16x32_bf16 v[110:113], v[164:167], v[172:175], v[110:113]
	v_mfma_f32_16x16x32_bf16 v[102:105], v[156:159], v[180:183], v[102:105]
	v_mfma_f32_16x16x32_bf16 v[94:97], v[164:167], v[180:183], v[94:97]
	v_mfma_f32_16x16x32_bf16 v[86:89], v[156:159], v[188:191], v[86:89]
	v_mfma_f32_16x16x32_bf16 v[78:81], v[164:167], v[188:191], v[78:81]
	v_mfma_f32_16x16x32_bf16 v[74:77], v[156:159], v[196:199], v[74:77]
	v_mfma_f32_16x16x32_bf16 v[70:73], v[164:167], v[196:199], v[70:73]
	v_mfma_f32_16x16x32_bf16 v[118:121], v[160:163], v[176:179], v[118:121]
	v_mfma_f32_16x16x32_bf16 v[110:113], v[168:171], v[176:179], v[110:113]
	v_mfma_f32_16x16x32_bf16 v[102:105], v[160:163], v[184:187], v[102:105]
	v_mfma_f32_16x16x32_bf16 v[94:97], v[168:171], v[184:187], v[94:97]
	v_mfma_f32_16x16x32_bf16 v[86:89], v[160:163], v[192:195], v[86:89]
	v_mfma_f32_16x16x32_bf16 v[78:81], v[168:171], v[192:195], v[78:81]
	v_mfma_f32_16x16x32_bf16 v[74:77], v[160:163], v[200:203], v[74:77]
	v_mfma_f32_16x16x32_bf16 v[70:73], v[168:171], v[200:203], v[70:73]
	s_setprio 0
	s_barrier
	s_add_i32 s22, s24, s29
	s_mov_b32 m0, s22
	ds_read_b128 v[172:175], v5 offset:49152
	ds_read_b128 v[176:179], v5 offset:50176
	ds_read_b128 v[180:183], v5 offset:51200
	ds_read_b128 v[184:187], v5 offset:52224
	ds_read_b128 v[188:191], v5 offset:53248
	ds_read_b128 v[192:195], v5 offset:54272
	ds_read_b128 v[196:199], v5 offset:55296
	ds_read_b128 v[200:203], v5 offset:56320
	global_load_lds_dwordx4 v134, s[20:21]
	s_add_i32 m0, s22, 0x2000
	s_add_i32 s22, s25, s29
	global_load_lds_dwordx4 v138, s[20:21]
	s_add_u32 s20, s20, 0x20000
	s_addc_u32 s21, s21, 0
	s_mov_b32 m0, s22
	s_nop 0
	global_load_lds_dwordx4 v134, s[20:21]
	s_add_i32 m0, s22, 0x2000
	s_nop 0
	global_load_lds_dwordx4 v138, s[20:21]
	s_mov_b32 m0, s38
	s_nop 0
	global_load_lds_dwordx4 v2, s[18:19]
	s_mov_b32 m0, s39
	s_nop 0
	global_load_lds_dwordx4 v136, s[18:19]
	s_waitcnt vmcnt(8)
	s_waitcnt lgkmcnt(0)
	s_barrier
	s_setprio 1
	v_mfma_f32_16x16x32_bf16 v[66:69], v[140:143], v[172:175], v[66:69]
	v_mfma_f32_16x16x32_bf16 v[62:65], v[148:151], v[172:175], v[62:65]
	v_mfma_f32_16x16x32_bf16 v[58:61], v[140:143], v[180:183], v[58:61]
	v_mfma_f32_16x16x32_bf16 v[50:53], v[148:151], v[180:183], v[50:53]
	v_mfma_f32_16x16x32_bf16 v[42:45], v[140:143], v[188:191], v[42:45]
	v_mfma_f32_16x16x32_bf16 v[34:37], v[148:151], v[188:191], v[34:37]
	v_mfma_f32_16x16x32_bf16 v[26:29], v[140:143], v[196:199], v[26:29]
	v_mfma_f32_16x16x32_bf16 v[18:21], v[148:151], v[196:199], v[18:21]
	v_mfma_f32_16x16x32_bf16 v[66:69], v[144:147], v[176:179], v[66:69]
	v_mfma_f32_16x16x32_bf16 v[62:65], v[152:155], v[176:179], v[62:65]
	v_mfma_f32_16x16x32_bf16 v[58:61], v[144:147], v[184:187], v[58:61]
	v_mfma_f32_16x16x32_bf16 v[50:53], v[152:155], v[184:187], v[50:53]
	v_mfma_f32_16x16x32_bf16 v[42:45], v[144:147], v[192:195], v[42:45]
	v_mfma_f32_16x16x32_bf16 v[34:37], v[152:155], v[192:195], v[34:37]
	v_mfma_f32_16x16x32_bf16 v[26:29], v[144:147], v[200:203], v[26:29]
	v_mfma_f32_16x16x32_bf16 v[18:21], v[152:155], v[200:203], v[18:21]
	s_setprio 0
	s_setprio 1
	v_mfma_f32_16x16x32_bf16 v[54:57], v[156:159], v[172:175], v[54:57]
	v_mfma_f32_16x16x32_bf16 v[46:49], v[164:167], v[172:175], v[46:49]
	v_mfma_f32_16x16x32_bf16 v[38:41], v[156:159], v[180:183], v[38:41]
	v_mfma_f32_16x16x32_bf16 v[30:33], v[164:167], v[180:183], v[30:33]
	v_mfma_f32_16x16x32_bf16 v[22:25], v[156:159], v[188:191], v[22:25]
	v_mfma_f32_16x16x32_bf16 v[14:17], v[164:167], v[188:191], v[14:17]
	v_mfma_f32_16x16x32_bf16 v[10:13], v[156:159], v[196:199], v[10:13]
	v_mfma_f32_16x16x32_bf16 v[6:9], v[164:167], v[196:199], v[6:9]
	v_mfma_f32_16x16x32_bf16 v[54:57], v[160:163], v[176:179], v[54:57]
	v_mfma_f32_16x16x32_bf16 v[46:49], v[168:171], v[176:179], v[46:49]
	v_mfma_f32_16x16x32_bf16 v[38:41], v[160:163], v[184:187], v[38:41]
	v_mfma_f32_16x16x32_bf16 v[30:33], v[168:171], v[184:187], v[30:33]
	v_mfma_f32_16x16x32_bf16 v[22:25], v[160:163], v[192:195], v[22:25]
	v_mfma_f32_16x16x32_bf16 v[14:17], v[168:171], v[192:195], v[14:17]
	v_mfma_f32_16x16x32_bf16 v[10:13], v[160:163], v[200:203], v[10:13]
	v_mfma_f32_16x16x32_bf16 v[6:9], v[168:171], v[200:203], v[6:9]
	s_setprio 0
	s_barrier
	s_add_i32 s47, s47, 2
	s_add_u32 s43, s43, 0x100
	s_addc_u32 s44, s44, 0
	s_add_u32 s45, s45, 0x100
	s_addc_u32 s46, s46, 0
	s_cmp_gt_u32 s47, 5
	s_cbranch_scc0 .LBB0_536
	s_lshl_b32 s20, s16, 8
	v_mov_b32_e32 v140, v0
	s_mov_b64 s[18:19], s[84:85]
	s_lshl_b32 s7, s14, 8
	s_ashr_i32 s21, s20, 31
	s_add_i32 s7, s7, s34
	s_lshl_b64 s[20:21], s[20:21], 1
	v_and_b32_e32 v142, 15, v140
	s_add_u32 s18, s18, s20
	v_or_b32_e32 v146, s7, v142
	v_lshrrev_b32_e32 v140, 1, v140
	s_addc_u32 s19, s19, s21
	s_ashr_i32 s9, s7, 11
	v_mov_b32_e32 v143, s7
	s_movk_i32 s7, 0x7cf
	v_and_or_b32 v140, v140, 24, s35
	s_mulk_i32 s9, 0x810
	v_bitop3_b32 v142, v142, s7, v143 bitop3:0xc8
	v_lshlrev_b32_e32 v140, 1, v140
	v_mov_b32_e32 v141, v4
	v_add_u32_e32 v142, s9, v142
	v_lshl_add_u64 v[140:141], s[18:19], 0, v[140:141]
	s_mov_b64 s[18:19], 0x2c900000
	v_ashrrev_i32_e32 v143, 31, v142
	v_lshl_add_u64 v[140:141], v[140:141], 0, s[18:19]
	v_lshlrev_b64 v[144:145], 13, v[142:143]
	v_lshl_add_u64 v[144:145], v[140:141], 0, v[144:145]
	v_cvt_pk_bf16_f32 v130, v130, v131
	v_cvt_pk_bf16_f32 v131, v132, v133
	v_cvt_pk_bf16_f32 v132, v126, v127
	v_cvt_pk_bf16_f32 v133, v128, v129
	global_store_dwordx4 v[144:145], v[130:133], off nt
	v_cvt_pk_bf16_f32 v118, v118, v119
	v_cvt_pk_bf16_f32 v119, v120, v121
	v_cvt_pk_bf16_f32 v120, v110, v111
	v_add_u32_e32 v110, 16, v142
	v_ashrrev_i32_e32 v111, 31, v110
	v_lshlrev_b64 v[110:111], 13, v[110:111]
	v_cvt_pk_bf16_f32 v121, v112, v113
	global_store_dwordx4 v[144:145], v[118:121], off offset:256 nt
	s_movk_i32 s7, 0x810
	s_and_b64 vcc, exec, s[0:1]
	v_lshl_add_u64 v[118:119], v[140:141], 0, v[110:111]
	v_cvt_pk_bf16_f32 v110, v122, v123
	v_cvt_pk_bf16_f32 v111, v124, v125
	v_cvt_pk_bf16_f32 v112, v114, v115
	v_cvt_pk_bf16_f32 v113, v116, v117
	global_store_dwordx4 v[118:119], v[110:113], off nt
	v_cvt_pk_bf16_f32 v102, v102, v103
	v_cvt_pk_bf16_f32 v103, v104, v105
	v_cvt_pk_bf16_f32 v104, v94, v95
	v_add_u32_e32 v94, 32, v142
	v_ashrrev_i32_e32 v95, 31, v94
	v_lshlrev_b64 v[94:95], 13, v[94:95]
	v_cvt_pk_bf16_f32 v105, v96, v97
	global_store_dwordx4 v[118:119], v[102:105], off offset:256 nt
	s_mov_b32 s16, s8
	s_mov_b32 s14, s6
	v_lshl_add_u64 v[102:103], v[140:141], 0, v[94:95]
	v_cvt_pk_bf16_f32 v94, v106, v107
	v_cvt_pk_bf16_f32 v95, v108, v109
	v_cvt_pk_bf16_f32 v96, v98, v99
	v_cvt_pk_bf16_f32 v97, v100, v101
	global_store_dwordx4 v[102:103], v[94:97], off nt
	v_cvt_pk_bf16_f32 v86, v86, v87
	v_cvt_pk_bf16_f32 v87, v88, v89
	v_cvt_pk_bf16_f32 v88, v78, v79
	v_add_u32_e32 v78, 48, v142
	v_ashrrev_i32_e32 v79, 31, v78
	v_lshlrev_b64 v[78:79], 13, v[78:79]
	v_cvt_pk_bf16_f32 v89, v80, v81
	global_store_dwordx4 v[102:103], v[86:89], off offset:256 nt
	s_mov_b64 s[20:21], s[10:11]
	s_mov_b64 s[18:19], s[12:13]
	v_lshl_add_u64 v[86:87], v[140:141], 0, v[78:79]
	v_cvt_pk_bf16_f32 v78, v90, v91
	v_cvt_pk_bf16_f32 v79, v92, v93
	v_cvt_pk_bf16_f32 v80, v82, v83
	v_cvt_pk_bf16_f32 v81, v84, v85
	global_store_dwordx4 v[86:87], v[78:81], off nt
	v_cvt_pk_bf16_f32 v74, v74, v75
	v_cvt_pk_bf16_f32 v75, v76, v77
	v_cvt_pk_bf16_f32 v76, v70, v71
	v_add_u32_e32 v70, 0x80, v146
	v_ashrrev_i32_e32 v71, 11, v70
	v_and_b32_e32 v70, 0x7cf, v70
	v_mad_i32_i24 v70, v71, s7, v70
	v_ashrrev_i32_e32 v71, 31, v70
	v_cvt_pk_bf16_f32 v77, v72, v73
	v_lshlrev_b64 v[72:73], 13, v[70:71]
	global_store_dwordx4 v[86:87], v[74:77], off offset:256 nt
	v_lshl_add_u64 v[72:73], v[140:141], 0, v[72:73]
	v_cvt_pk_bf16_f32 v66, v66, v67
	v_cvt_pk_bf16_f32 v67, v68, v69
	v_cvt_pk_bf16_f32 v68, v62, v63
	v_cvt_pk_bf16_f32 v69, v64, v65
	global_store_dwordx4 v[72:73], v[66:69], off nt
	v_cvt_pk_bf16_f32 v54, v54, v55
	v_cvt_pk_bf16_f32 v55, v56, v57
	v_cvt_pk_bf16_f32 v56, v46, v47
	v_add_u32_e32 v46, 16, v70
	v_ashrrev_i32_e32 v47, 31, v46
	v_lshlrev_b64 v[46:47], 13, v[46:47]
	v_cvt_pk_bf16_f32 v57, v48, v49
	global_store_dwordx4 v[72:73], v[54:57], off offset:256 nt
	s_mov_b32 s51, 0x40c000
	s_mov_b32 s47, 0x120000
	v_lshl_add_u64 v[54:55], v[140:141], 0, v[46:47]
	v_cvt_pk_bf16_f32 v46, v58, v59
	v_cvt_pk_bf16_f32 v47, v60, v61
	v_cvt_pk_bf16_f32 v48, v50, v51
	v_cvt_pk_bf16_f32 v49, v52, v53
	global_store_dwordx4 v[54:55], v[46:49], off nt
	v_cvt_pk_bf16_f32 v38, v38, v39
	v_cvt_pk_bf16_f32 v39, v40, v41
	v_cvt_pk_bf16_f32 v40, v30, v31
	v_add_u32_e32 v30, 32, v70
	v_ashrrev_i32_e32 v31, 31, v30
	v_lshlrev_b64 v[30:31], 13, v[30:31]
	v_cvt_pk_bf16_f32 v41, v32, v33
	global_store_dwordx4 v[54:55], v[38:41], off offset:256 nt
	s_mov_b64 s[48:49], 0x7ffff
	s_nop 0
	v_lshl_add_u64 v[38:39], v[140:141], 0, v[30:31]
	v_cvt_pk_bf16_f32 v30, v42, v43
	v_cvt_pk_bf16_f32 v31, v44, v45
	v_cvt_pk_bf16_f32 v32, v34, v35
	v_cvt_pk_bf16_f32 v33, v36, v37
	global_store_dwordx4 v[38:39], v[30:33], off nt
	v_cvt_pk_bf16_f32 v22, v22, v23
	v_cvt_pk_bf16_f32 v23, v24, v25
	v_cvt_pk_bf16_f32 v24, v14, v15
	v_add_u32_e32 v14, 48, v70
	v_ashrrev_i32_e32 v15, 31, v14
	v_lshlrev_b64 v[14:15], 13, v[14:15]
	v_cvt_pk_bf16_f32 v25, v16, v17
	global_store_dwordx4 v[38:39], v[22:25], off offset:256 nt
	s_nop 1
	v_lshl_add_u64 v[22:23], v[140:141], 0, v[14:15]
	v_cvt_pk_bf16_f32 v14, v26, v27
	v_cvt_pk_bf16_f32 v15, v28, v29
	v_cvt_pk_bf16_f32 v16, v18, v19
	v_cvt_pk_bf16_f32 v17, v20, v21
	global_store_dwordx4 v[22:23], v[14:17], off nt
	v_cvt_pk_bf16_f32 v10, v10, v11
	v_cvt_pk_bf16_f32 v11, v12, v13
	v_cvt_pk_bf16_f32 v12, v6, v7
	v_cvt_pk_bf16_f32 v13, v8, v9
	global_store_dwordx4 v[22:23], v[10:13], off offset:256 nt
	s_cbranch_vccz .LBB0_529
	s_waitcnt vmcnt(0)
	s_cmpk_gt_u32 s28, 0xff
	s_cbranch_scc1 .LBB0_540
	s_barrier

.LBB0_924:
	s_add_u32 s48, s45, 0xffffff80
	s_addc_u32 s49, s46, -1
	s_cmp_eq_u32 s47, 60
	s_cselect_b32 s22, s9, s45
	s_cselect_b32 s23, s7, s46
	s_cselect_b32 s25, s11, s44
	s_cselect_b32 s24, s13, s33
	s_add_u32 s18, s22, 0x80
	s_addc_u32 s19, s23, 0
	s_add_u32 s20, s24, 0x80
	s_addc_u32 s21, s25, 0
	s_add_i32 s50, 0, 0x10000
	s_add_i32 s51, 0, 0x14000
	v_add_u32_e32 v90, s50, v1
	v_add_u32_e32 v162, s51, v1
	ds_read_b128 v[78:81], v90
	ds_read_b128 v[82:85], v90 offset:1024
	ds_read_b128 v[86:89], v90 offset:2048
	ds_read_b128 v[90:93], v90 offset:3072
	ds_read_b128 v[142:145], v162
	ds_read_b128 v[146:149], v162 offset:1024
	ds_read_b128 v[158:161], v162 offset:2048
	ds_read_b128 v[162:165], v162 offset:3072
	s_add_u32 s48, s48, 0x100000
	s_addc_u32 s49, s49, 0
	s_add_i32 m0, s35, 0xc000
	ds_read_b128 v[166:169], v5
	ds_read_b128 v[170:173], v5 offset:1024
	ds_read_b128 v[174:177], v5 offset:2048
	ds_read_b128 v[178:181], v5 offset:3072
	ds_read_b128 v[182:185], v5 offset:4096
	ds_read_b128 v[186:189], v5 offset:5120
	ds_read_b128 v[190:193], v5 offset:6144
	ds_read_b128 v[194:197], v5 offset:7168
	global_load_lds_dwordx4 v2, s[48:49]
	s_add_i32 m0, s35, 0xe000
	s_nop 0
	global_load_lds_dwordx4 v218, s[48:49]
	s_waitcnt vmcnt(8)
	s_waitcnt lgkmcnt(0)
	s_barrier
	s_setprio 1
	v_mfma_f32_16x16x32_bf16 v[154:157], v[78:81], v[166:169], v[154:157]
	v_mfma_f32_16x16x32_bf16 v[150:153], v[86:89], v[166:169], v[150:153]
	v_mfma_f32_16x16x32_bf16 v[134:137], v[78:81], v[174:177], v[134:137]
	v_mfma_f32_16x16x32_bf16 v[126:129], v[86:89], v[174:177], v[126:129]
	v_mfma_f32_16x16x32_bf16 v[118:121], v[78:81], v[182:185], v[118:121]
	v_mfma_f32_16x16x32_bf16 v[110:113], v[86:89], v[182:185], v[110:113]
	v_mfma_f32_16x16x32_bf16 v[102:105], v[78:81], v[190:193], v[102:105]
	v_mfma_f32_16x16x32_bf16 v[94:97], v[86:89], v[190:193], v[94:97]
	v_mfma_f32_16x16x32_bf16 v[154:157], v[82:85], v[170:173], v[154:157]
	v_mfma_f32_16x16x32_bf16 v[150:153], v[90:93], v[170:173], v[150:153]
	v_mfma_f32_16x16x32_bf16 v[134:137], v[82:85], v[178:181], v[134:137]
	v_mfma_f32_16x16x32_bf16 v[126:129], v[90:93], v[178:181], v[126:129]
	v_mfma_f32_16x16x32_bf16 v[118:121], v[82:85], v[186:189], v[118:121]
	v_mfma_f32_16x16x32_bf16 v[110:113], v[90:93], v[186:189], v[110:113]
	v_mfma_f32_16x16x32_bf16 v[102:105], v[82:85], v[194:197], v[102:105]
	v_mfma_f32_16x16x32_bf16 v[94:97], v[90:93], v[194:197], v[94:97]
	s_setprio 0
	s_setprio 1
	v_mfma_f32_16x16x32_bf16 v[138:141], v[142:145], v[166:169], v[138:141]
	v_mfma_f32_16x16x32_bf16 v[130:133], v[158:161], v[166:169], v[130:133]
	v_mfma_f32_16x16x32_bf16 v[122:125], v[142:145], v[174:177], v[122:125]
	v_mfma_f32_16x16x32_bf16 v[114:117], v[158:161], v[174:177], v[114:117]
	v_mfma_f32_16x16x32_bf16 v[106:109], v[142:145], v[182:185], v[106:109]
	v_mfma_f32_16x16x32_bf16 v[98:101], v[158:161], v[182:185], v[98:101]
	v_mfma_f32_16x16x32_bf16 v[74:77], v[142:145], v[190:193], v[74:77]
	v_mfma_f32_16x16x32_bf16 v[70:73], v[158:161], v[190:193], v[70:73]
	v_mfma_f32_16x16x32_bf16 v[138:141], v[146:149], v[170:173], v[138:141]
	v_mfma_f32_16x16x32_bf16 v[130:133], v[162:165], v[170:173], v[130:133]
	v_mfma_f32_16x16x32_bf16 v[122:125], v[146:149], v[178:181], v[122:125]
	v_mfma_f32_16x16x32_bf16 v[114:117], v[162:165], v[178:181], v[114:117]
	v_mfma_f32_16x16x32_bf16 v[106:109], v[146:149], v[186:189], v[106:109]
	v_mfma_f32_16x16x32_bf16 v[98:101], v[162:165], v[186:189], v[98:101]
	v_mfma_f32_16x16x32_bf16 v[74:77], v[146:149], v[194:197], v[74:77]
	v_mfma_f32_16x16x32_bf16 v[70:73], v[162:165], v[194:197], v[70:73]
	s_setprio 0
	s_barrier
	s_add_i32 s48, s50, s29
	s_mov_b32 m0, s48
	ds_read_b128 v[166:169], v5 offset:16384
	ds_read_b128 v[170:173], v5 offset:17408
	ds_read_b128 v[174:177], v5 offset:18432
	ds_read_b128 v[178:181], v5 offset:19456
	ds_read_b128 v[182:185], v5 offset:20480
	ds_read_b128 v[186:189], v5 offset:21504
	ds_read_b128 v[190:193], v5 offset:22528
	ds_read_b128 v[194:197], v5 offset:23552
	global_load_lds_dwordx4 v216, s[24:25]
	s_add_i32 m0, s48, 0x2000
	s_add_i32 s48, s51, s29
	global_load_lds_dwordx4 v220, s[24:25]
	s_add_u32 s24, s24, 0x100000
	s_addc_u32 s25, s25, 0
	s_mov_b32 m0, s48
	s_nop 0
	global_load_lds_dwordx4 v216, s[24:25]
	s_add_i32 m0, s48, 0x2000
	s_nop 0
	global_load_lds_dwordx4 v220, s[24:25]
	s_mov_b32 m0, s35
	s_nop 0
	global_load_lds_dwordx4 v2, s[22:23]
	s_mov_b32 m0, s36
	s_nop 0
	global_load_lds_dwordx4 v218, s[22:23]
	s_waitcnt vmcnt(8)
	s_waitcnt lgkmcnt(0)
	s_barrier
	s_setprio 1
	v_mfma_f32_16x16x32_bf16 v[66:69], v[78:81], v[166:169], v[66:69]
	v_mfma_f32_16x16x32_bf16 v[62:65], v[86:89], v[166:169], v[62:65]
	v_mfma_f32_16x16x32_bf16 v[54:57], v[78:81], v[174:177], v[54:57]
	v_mfma_f32_16x16x32_bf16 v[46:49], v[86:89], v[174:177], v[46:49]
	v_mfma_f32_16x16x32_bf16 v[38:41], v[78:81], v[182:185], v[38:41]
	v_mfma_f32_16x16x32_bf16 v[30:33], v[86:89], v[182:185], v[30:33]
	v_mfma_f32_16x16x32_bf16 v[22:25], v[78:81], v[190:193], v[22:25]
	v_mfma_f32_16x16x32_bf16 v[14:17], v[86:89], v[190:193], v[14:17]
	v_mfma_f32_16x16x32_bf16 v[66:69], v[82:85], v[170:173], v[66:69]
	v_mfma_f32_16x16x32_bf16 v[62:65], v[90:93], v[170:173], v[62:65]
	v_mfma_f32_16x16x32_bf16 v[54:57], v[82:85], v[178:181], v[54:57]
	v_mfma_f32_16x16x32_bf16 v[46:49], v[90:93], v[178:181], v[46:49]
	v_mfma_f32_16x16x32_bf16 v[38:41], v[82:85], v[186:189], v[38:41]
	v_mfma_f32_16x16x32_bf16 v[30:33], v[90:93], v[186:189], v[30:33]
	v_mfma_f32_16x16x32_bf16 v[22:25], v[82:85], v[194:197], v[22:25]
	v_mfma_f32_16x16x32_bf16 v[14:17], v[90:93], v[194:197], v[14:17]
	s_setprio 0
	s_setprio 1
	v_mfma_f32_16x16x32_bf16 v[58:61], v[142:145], v[166:169], v[58:61]
	v_mfma_f32_16x16x32_bf16 v[50:53], v[158:161], v[166:169], v[50:53]
	v_mfma_f32_16x16x32_bf16 v[42:45], v[142:145], v[174:177], v[42:45]
	v_mfma_f32_16x16x32_bf16 v[34:37], v[158:161], v[174:177], v[34:37]
	v_mfma_f32_16x16x32_bf16 v[26:29], v[142:145], v[182:185], v[26:29]
	v_mfma_f32_16x16x32_bf16 v[18:21], v[158:161], v[182:185], v[18:21]
	v_mfma_f32_16x16x32_bf16 v[10:13], v[142:145], v[190:193], v[10:13]
	v_mfma_f32_16x16x32_bf16 v[6:9], v[158:161], v[190:193], v[6:9]
	v_mfma_f32_16x16x32_bf16 v[58:61], v[146:149], v[170:173], v[58:61]
	v_mfma_f32_16x16x32_bf16 v[50:53], v[162:165], v[170:173], v[50:53]
	v_mfma_f32_16x16x32_bf16 v[42:45], v[146:149], v[178:181], v[42:45]
	v_mfma_f32_16x16x32_bf16 v[34:37], v[162:165], v[178:181], v[34:37]
	v_mfma_f32_16x16x32_bf16 v[26:29], v[146:149], v[186:189], v[26:29]
	v_mfma_f32_16x16x32_bf16 v[18:21], v[162:165], v[186:189], v[18:21]
	v_mfma_f32_16x16x32_bf16 v[10:13], v[146:149], v[194:197], v[10:13]
	v_mfma_f32_16x16x32_bf16 v[6:9], v[162:165], v[194:197], v[6:9]
	s_setprio 0
	s_barrier
	s_add_i32 s24, 0, 0x18000
	s_add_i32 s25, 0, 0x1c000
	v_add_u32_e32 v90, s24, v1
	v_add_u32_e32 v162, s25, v1
	ds_read_b128 v[78:81], v90
	ds_read_b128 v[82:85], v90 offset:1024
	ds_read_b128 v[86:89], v90 offset:2048
	ds_read_b128 v[90:93], v90 offset:3072
	ds_read_b128 v[142:145], v162
	ds_read_b128 v[146:149], v162 offset:1024
	ds_read_b128 v[158:161], v162 offset:2048
	ds_read_b128 v[162:165], v162 offset:3072
	s_add_u32 s22, s22, 0x100000
	s_addc_u32 s23, s23, 0
	s_mov_b32 m0, s37
	ds_read_b128 v[166:169], v5 offset:32768
	ds_read_b128 v[170:173], v5 offset:33792
	ds_read_b128 v[174:177], v5 offset:34816
	ds_read_b128 v[178:181], v5 offset:35840
	ds_read_b128 v[182:185], v5 offset:36864
	ds_read_b128 v[186:189], v5 offset:37888
	ds_read_b128 v[190:193], v5 offset:38912
	ds_read_b128 v[194:197], v5 offset:39936
	global_load_lds_dwordx4 v2, s[22:23]
	s_mov_b32 m0, s38
	s_nop 0
	global_load_lds_dwordx4 v218, s[22:23]
	s_waitcnt vmcnt(8)
	s_waitcnt lgkmcnt(0)
	s_barrier
	s_setprio 1
	v_mfma_f32_16x16x32_bf16 v[154:157], v[78:81], v[166:169], v[154:157]
	v_mfma_f32_16x16x32_bf16 v[150:153], v[86:89], v[166:169], v[150:153]
	v_mfma_f32_16x16x32_bf16 v[134:137], v[78:81], v[174:177], v[134:137]
	v_mfma_f32_16x16x32_bf16 v[126:129], v[86:89], v[174:177], v[126:129]
	v_mfma_f32_16x16x32_bf16 v[118:121], v[78:81], v[182:185], v[118:121]
	v_mfma_f32_16x16x32_bf16 v[110:113], v[86:89], v[182:185], v[110:113]
	v_mfma_f32_16x16x32_bf16 v[102:105], v[78:81], v[190:193], v[102:105]
	v_mfma_f32_16x16x32_bf16 v[94:97], v[86:89], v[190:193], v[94:97]
	v_mfma_f32_16x16x32_bf16 v[154:157], v[82:85], v[170:173], v[154:157]
	v_mfma_f32_16x16x32_bf16 v[150:153], v[90:93], v[170:173], v[150:153]
	v_mfma_f32_16x16x32_bf16 v[134:137], v[82:85], v[178:181], v[134:137]
	v_mfma_f32_16x16x32_bf16 v[126:129], v[90:93], v[178:181], v[126:129]
	v_mfma_f32_16x16x32_bf16 v[118:121], v[82:85], v[186:189], v[118:121]
	v_mfma_f32_16x16x32_bf16 v[110:113], v[90:93], v[186:189], v[110:113]
	v_mfma_f32_16x16x32_bf16 v[102:105], v[82:85], v[194:197], v[102:105]
	v_mfma_f32_16x16x32_bf16 v[94:97], v[90:93], v[194:197], v[94:97]
	s_setprio 0
	s_setprio 1
	v_mfma_f32_16x16x32_bf16 v[138:141], v[142:145], v[166:169], v[138:141]
	v_mfma_f32_16x16x32_bf16 v[130:133], v[158:161], v[166:169], v[130:133]
	v_mfma_f32_16x16x32_bf16 v[122:125], v[142:145], v[174:177], v[122:125]
	v_mfma_f32_16x16x32_bf16 v[114:117], v[158:161], v[174:177], v[114:117]
	v_mfma_f32_16x16x32_bf16 v[106:109], v[142:145], v[182:185], v[106:109]
	v_mfma_f32_16x16x32_bf16 v[98:101], v[158:161], v[182:185], v[98:101]
	v_mfma_f32_16x16x32_bf16 v[74:77], v[142:145], v[190:193], v[74:77]
	v_mfma_f32_16x16x32_bf16 v[70:73], v[158:161], v[190:193], v[70:73]
	v_mfma_f32_16x16x32_bf16 v[138:141], v[146:149], v[170:173], v[138:141]
	v_mfma_f32_16x16x32_bf16 v[130:133], v[162:165], v[170:173], v[130:133]
	v_mfma_f32_16x16x32_bf16 v[122:125], v[146:149], v[178:181], v[122:125]
	v_mfma_f32_16x16x32_bf16 v[114:117], v[162:165], v[178:181], v[114:117]
	v_mfma_f32_16x16x32_bf16 v[106:109], v[146:149], v[186:189], v[106:109]
	v_mfma_f32_16x16x32_bf16 v[98:101], v[162:165], v[186:189], v[98:101]
	v_mfma_f32_16x16x32_bf16 v[74:77], v[146:149], v[194:197], v[74:77]
	v_mfma_f32_16x16x32_bf16 v[70:73], v[162:165], v[194:197], v[70:73]
	s_setprio 0
	s_barrier
	s_add_i32 s22, s24, s29
	s_mov_b32 m0, s22
	ds_read_b128 v[166:169], v5 offset:49152
	ds_read_b128 v[170:173], v5 offset:50176
	ds_read_b128 v[174:177], v5 offset:51200
	ds_read_b128 v[178:181], v5 offset:52224
	ds_read_b128 v[182:185], v5 offset:53248
	ds_read_b128 v[186:189], v5 offset:54272
	ds_read_b128 v[190:193], v5 offset:55296
	ds_read_b128 v[194:197], v5 offset:56320
	global_load_lds_dwordx4 v216, s[20:21]
	s_add_i32 m0, s22, 0x2000
	s_add_i32 s22, s25, s29
	global_load_lds_dwordx4 v220, s[20:21]
	s_add_u32 s20, s20, 0x100000
	s_addc_u32 s21, s21, 0
	s_mov_b32 m0, s22
	s_nop 0
	global_load_lds_dwordx4 v216, s[20:21]
	s_add_i32 m0, s22, 0x2000
	s_nop 0
	global_load_lds_dwordx4 v220, s[20:21]
	s_mov_b32 m0, s41
	s_nop 0
	global_load_lds_dwordx4 v2, s[18:19]
	s_mov_b32 m0, s42
	s_nop 0
	global_load_lds_dwordx4 v218, s[18:19]
	s_waitcnt vmcnt(8)
	s_waitcnt lgkmcnt(0)
	s_barrier
	s_setprio 1
	v_mfma_f32_16x16x32_bf16 v[66:69], v[78:81], v[166:169], v[66:69]
	v_mfma_f32_16x16x32_bf16 v[62:65], v[86:89], v[166:169], v[62:65]
	v_mfma_f32_16x16x32_bf16 v[54:57], v[78:81], v[174:177], v[54:57]
	v_mfma_f32_16x16x32_bf16 v[46:49], v[86:89], v[174:177], v[46:49]
	v_mfma_f32_16x16x32_bf16 v[38:41], v[78:81], v[182:185], v[38:41]
	v_mfma_f32_16x16x32_bf16 v[30:33], v[86:89], v[182:185], v[30:33]
	v_mfma_f32_16x16x32_bf16 v[22:25], v[78:81], v[190:193], v[22:25]
	v_mfma_f32_16x16x32_bf16 v[14:17], v[86:89], v[190:193], v[14:17]
	v_mfma_f32_16x16x32_bf16 v[66:69], v[82:85], v[170:173], v[66:69]
	v_mfma_f32_16x16x32_bf16 v[62:65], v[90:93], v[170:173], v[62:65]
	v_mfma_f32_16x16x32_bf16 v[54:57], v[82:85], v[178:181], v[54:57]
	v_mfma_f32_16x16x32_bf16 v[46:49], v[90:93], v[178:181], v[46:49]
	v_mfma_f32_16x16x32_bf16 v[38:41], v[82:85], v[186:189], v[38:41]
	v_mfma_f32_16x16x32_bf16 v[30:33], v[90:93], v[186:189], v[30:33]
	v_mfma_f32_16x16x32_bf16 v[22:25], v[82:85], v[194:197], v[22:25]
	v_mfma_f32_16x16x32_bf16 v[14:17], v[90:93], v[194:197], v[14:17]
	s_setprio 0
	s_setprio 1
	v_mfma_f32_16x16x32_bf16 v[58:61], v[142:145], v[166:169], v[58:61]
	v_mfma_f32_16x16x32_bf16 v[50:53], v[158:161], v[166:169], v[50:53]
	v_mfma_f32_16x16x32_bf16 v[42:45], v[142:145], v[174:177], v[42:45]
	v_mfma_f32_16x16x32_bf16 v[34:37], v[158:161], v[174:177], v[34:37]
	v_mfma_f32_16x16x32_bf16 v[26:29], v[142:145], v[182:185], v[26:29]
	v_mfma_f32_16x16x32_bf16 v[18:21], v[158:161], v[182:185], v[18:21]
	v_mfma_f32_16x16x32_bf16 v[10:13], v[142:145], v[190:193], v[10:13]
	v_mfma_f32_16x16x32_bf16 v[6:9], v[158:161], v[190:193], v[6:9]
	v_mfma_f32_16x16x32_bf16 v[58:61], v[146:149], v[170:173], v[58:61]
	v_mfma_f32_16x16x32_bf16 v[50:53], v[162:165], v[170:173], v[50:53]
	v_mfma_f32_16x16x32_bf16 v[42:45], v[146:149], v[178:181], v[42:45]
	v_mfma_f32_16x16x32_bf16 v[34:37], v[162:165], v[178:181], v[34:37]
	v_mfma_f32_16x16x32_bf16 v[26:29], v[146:149], v[186:189], v[26:29]
	v_mfma_f32_16x16x32_bf16 v[18:21], v[162:165], v[186:189], v[18:21]
	v_mfma_f32_16x16x32_bf16 v[10:13], v[146:149], v[194:197], v[10:13]
	v_mfma_f32_16x16x32_bf16 v[6:9], v[162:165], v[194:197], v[6:9]
	s_setprio 0
	s_barrier
	s_add_i32 s47, s47, 2
	s_add_u32 s33, s33, 0x100
	s_addc_u32 s44, s44, 0
	s_add_u32 s45, s45, 0x100
	s_addc_u32 s46, s46, 0
	s_cmp_gt_u32 s47, 61
	s_cbranch_scc0 .LBB0_924
	v_mov_b32_e32 v142, v0
	s_mov_b64 s[20:21], s[84:85]
	s_add_u32 s7, s20, 0x4179c000
	v_readlane_b32 s18, v254, 26
	s_addc_u32 s9, s21, 0
	v_readlane_b32 s19, v254, 27
	v_readlane_b32 s44, v253, 35
	s_and_b64 s[18:19], s[18:19], exec
	v_readlane_b32 s45, v253, 36
	v_bfe_u32 v144, v142, 4, 2
	s_cselect_b32 s23, s9, s45
	s_cselect_b32 s22, s7, s44
	s_cselect_b32 s19, s83, s9
	s_cselect_b32 s18, s82, s7
	s_lshl_b32 s7, s8, 8
	s_lshl_b32 s6, s6, 8
	v_lshl_or_b32 v78, v144, 3, s7
	s_add_i32 s6, s6, s39
	v_or_b32_e32 v226, s40, v78
	v_ashrrev_i32_e32 v227, 31, v226
	v_readlane_b32 s8, v254, 9
	v_and_or_b32 v230, v142, 15, s6
	v_lshlrev_b64 v[244:245], 2, v[226:227]
	v_readlane_b32 s9, v254, 10
	v_lshl_add_u64 v[142:143], v[226:227], 1, s[20:21]
	s_mov_b64 s[6:7], 0x10f80000
	v_ashrrev_i32_e32 v231, 31, v230
	v_or_b32_e32 v240, 16, v230
	v_lshl_add_u64 v[82:83], s[8:9], 0, v[244:245]
	v_lshl_add_u64 v[228:229], s[22:23], 0, v[244:245]
	v_lshl_add_u64 v[224:225], v[142:143], 0, s[6:7]
	v_lshl_add_u64 v[142:143], v[230:231], 2, s[20:21]
	s_mov_b64 s[8:9], 0x18400
	v_lshlrev_b64 v[248:249], 14, v[230:231]
	v_ashrrev_i32_e32 v241, 31, v240
	v_or_b32_e32 v236, 32, v230
	v_or_b32_e32 v232, 48, v230
	v_lshl_add_u64 v[222:223], v[142:143], 0, s[8:9]
	v_lshl_add_u64 v[142:143], v[228:229], 0, v[248:249]
	v_lshlrev_b64 v[242:243], 14, v[240:241]
	v_ashrrev_i32_e32 v237, 31, v236
	v_ashrrev_i32_e32 v233, 31, v232
	global_load_dwordx4 v[86:89], v[82:83], off offset:16
	global_load_dwordx4 v[90:93], v[82:83], off
	global_load_dwordx4 v[78:81], v[82:83], off offset:528
	s_nop 0
	global_load_dwordx4 v[82:85], v[82:83], off offset:512
	s_nop 0
	global_load_dwordx4 v[206:209], v[142:143], off offset:16
	global_load_dwordx4 v[210:213], v[142:143], off
	global_load_dwordx4 v[198:201], v[142:143], off offset:528
	global_load_dwordx4 v[202:205], v[142:143], off offset:512
	v_lshl_add_u64 v[142:143], v[228:229], 0, v[242:243]
	v_lshlrev_b64 v[238:239], 14, v[236:237]
	v_lshlrev_b64 v[234:235], 14, v[232:233]
	global_load_dwordx4 v[190:193], v[142:143], off offset:16
	global_load_dwordx4 v[194:197], v[142:143], off
	global_load_dwordx4 v[182:185], v[142:143], off offset:528
	global_load_dwordx4 v[186:189], v[142:143], off offset:512
	v_lshl_add_u64 v[142:143], v[228:229], 0, v[238:239]
	v_lshl_add_u64 v[146:147], v[228:229], 0, v[234:235]
	v_cmp_eq_u32_e64 s[6:7], 0, v144
	global_load_dwordx4 v[174:177], v[142:143], off offset:16
	global_load_dwordx4 v[178:181], v[142:143], off
	global_load_dwordx4 v[166:169], v[142:143], off offset:528
	global_load_dwordx4 v[170:173], v[142:143], off offset:512
	global_load_dwordx4 v[158:161], v[146:147], off offset:16
	global_load_dwordx4 v[162:165], v[146:147], off
	s_nop 0
	global_load_dwordx4 v[142:145], v[146:147], off offset:528
	s_nop 0
	global_load_dwordx4 v[146:149], v[146:147], off offset:512
	v_lshl_add_u64 v[248:249], s[18:19], 0, v[248:249]
	v_lshl_add_u64 v[244:245], v[248:249], 0, v[244:245]
	s_mov_b64 s[20:21], -1
	s_andn2_b64 vcc, exec, s[60:61]
	v_readlane_b32 s46, v253, 37
	v_readlane_b32 s47, v253, 38
	v_readlane_b32 s48, v253, 39
	v_readlane_b32 s49, v253, 40
	v_readlane_b32 s50, v253, 41
	v_readlane_b32 s51, v253, 42
	v_readlane_b32 s52, v253, 43
	v_readlane_b32 s53, v253, 44
	v_readlane_b32 s54, v253, 45
	v_readlane_b32 s55, v253, 46
	v_readlane_b32 s56, v253, 47
	v_readlane_b32 s57, v253, 48
	v_readlane_b32 s58, v253, 49
	v_readlane_b32 s59, v253, 50
	s_waitcnt vmcnt(0)
	v_pk_add_f32 v[206:207], v[150:151], v[206:207]
	v_cndmask_b32_e64 v150, 0, 1, s[60:61]
	v_pk_add_f32 v[212:213], v[156:157], v[212:213]
	v_pk_add_f32 v[210:211], v[154:155], v[210:211]
	v_pk_add_f32 v[208:209], v[152:153], v[208:209]
	v_cmp_ne_u32_e64 s[8:9], 1, v150
	v_pk_add_f32 v[150:151], v[138:139], v[202:203]
	v_pk_add_f32 v[154:155], v[130:131], v[198:199]
	global_store_dwordx4 v[244:245], v[210:213], off
	global_store_dwordx4 v[244:245], v[206:209], off offset:16
	s_cbranch_vccnz .LBB0_929
	v_mul_f32_e32 v138, v211, v211
	v_mul_f32_e32 v139, v213, v213
	v_fmac_f32_e32 v138, v210, v210
	v_fmac_f32_e32 v139, v212, v212
	v_add_f32_e32 v138, v138, v139
	v_mul_f32_e32 v139, v207, v207
	v_fmac_f32_e32 v139, v206, v206
	v_add_f32_e32 v138, v138, v139
	v_mul_f32_e32 v139, v209, v209
	v_lshlrev_b64 v[130:131], 12, v[230:231]
	v_fmac_f32_e32 v139, v208, v208
	v_pk_mul_f32 v[152:153], v[90:91], v[210:211]
	v_pk_mul_f32 v[156:157], v[88:89], v[208:209]
	v_lshl_add_u64 v[130:131], v[130:131], 1, v[224:225]
	v_add_f32_e32 v231, v139, v138
	v_pk_mul_f32 v[138:139], v[92:93], v[212:213]
	v_pk_mul_f32 v[198:199], v[86:87], v[206:207]
	v_cvt_pk_bf16_f32 v206, v152, v153
	v_cvt_pk_bf16_f32 v207, v138, v139
	v_pk_add_f32 v[152:153], v[140:141], v[204:205]
	v_cvt_pk_bf16_f32 v208, v198, v199
	v_cvt_pk_bf16_f32 v209, v156, v157
	v_pk_add_f32 v[156:157], v[132:133], v[200:201]
	global_store_dwordx4 v[130:131], v[206:209], off
	global_store_dwordx4 v[244:245], v[150:153], off offset:512
	global_store_dwordx4 v[244:245], v[154:157], off offset:528
	v_pk_mul_f32 v[202:203], v[80:81], v[156:157]
	v_pk_mul_f32 v[138:139], v[84:85], v[152:153]
	v_mul_f32_e32 v157, v157, v157
	v_fmac_f32_e32 v157, v156, v156
	v_mul_f32_e32 v156, v151, v151
	v_mul_f32_e32 v153, v153, v153
	v_fmac_f32_e32 v156, v150, v150
	v_fmac_f32_e32 v153, v152, v152
	v_add_f32_e32 v152, v156, v153
	v_mul_f32_e32 v153, v155, v155
	v_fmac_f32_e32 v153, v154, v154
	v_add_f32_e32 v152, v152, v153
	v_add_f32_e32 v152, v157, v152
	v_add_f32_e32 v152, v231, v152
	ds_swizzle_b32 v153, v152 offset:swizzle(SWAP,16)
	v_pk_mul_f32 v[208:209], v[78:79], v[154:155]
	v_pk_mul_f32 v[198:199], v[82:83], v[150:151]
	s_nop 0
	v_cvt_pk_bf16_f32 v206, v198, v199
	v_cvt_pk_bf16_f32 v207, v138, v139
	v_cvt_pk_bf16_f32 v208, v208, v209
	v_cvt_pk_bf16_f32 v209, v202, v203
	global_store_dwordx4 v[130:131], v[206:209], off offset:256
	s_waitcnt lgkmcnt(0)
	v_add_f32_e32 v130, v152, v153
	v_mov_b32_e32 v131, v130
	s_nop 1
	v_permlane32_swap_b32_e32 v130, v131
	s_and_saveexec_b64 s[20:21], s[6:7]
	s_cbranch_execz .LBB0_928
	v_add_f32_e32 v130, v130, v131
	global_atomic_add_f32 v[222:223], v130, off
